# in-projection epilogue: dwordx4 stores (f32 cache outputs and bf16 q/k images) marked nt so they stream past the caches
# baseline (speedup 1.0000x reference)
;     __device__ __forceinline__ void operator()(const f32x4 (&acc)[2][2][4][2], const Unit& u, int wr, int wc, int fr, int fq) const {
;         const int pn = u.pn;
;         const bool do_rope = (pn < 4) || (pn == 7 && wc == 2);
; #pragma unroll
;         for (int ai = 0; ai < 2; ++ai)
; #pragma unroll
;             for (int m = 0; m < 4; ++m) {
;                 const int r = u.pm * 256 + ai * 128 + wr * 64 + m * 16 + fr;
;                 int pos, kr, kl, len; tok_row(r, pos, kr, kl, len);
;                 if (do_rope) {
;                     const float* cs = rope + pos * 64 + 8 * fq;
;                     const f32x4 c0 = *(const f32x4*)cs, c1 = *(const f32x4*)(cs + 4), s0 = *(const f32x4*)(cs + 32), s1 = *(const f32x4*)(cs + 36);
;                     const f32x4 x10 = acc[ai][0][m][0], x11 = acc[ai][0][m][1], x20 = acc[ai][1][m][0], x21 = acc[ai][1][m][1];
;                     f32x4 a0 = x10 * c0 - x20 * s0, a1 = x11 * c1 - x21 * s1, b0 = x20 * c0 + x10 * s0, b1 = x21 * c1 + x11 * s1;
;                     if (pn < 2) {
;                         const int g = 4 * pn + wc;
;                         bf16_t* d = qd + (size_t)r * 512 + 64 * g + 8 * fq;
;                         *(u32x4*)d = pack8(a0 * QS_D, a1 * QS_D); *(u32x4*)(d + 32) = pack8(b0 * QS_D, b1 * QS_D);
;                     } else if (pn < 4) {
;                         const int g = 4 * (pn - 2) + wc;
;                         float* o = out_row(out, r, O_DKP, O_DKS, 512) + 64 * g + 8 * fq;
;                         *(f32x4*)o = a0; *(f32x4*)(o + 4) = a1; *(f32x4*)(o + 32) = b0; *(f32x4*)(o + 36) = b1;
;                         bf16_t* d = kd + (size_t)kr * 512 + 64 * g + 8 * fq;
;                         *(u32x4*)d = pack8(a0, a1); *(u32x4*)(d + 32) = pack8(b0, b1);
;                     } else {
;                         float* o = out_row(out, r, O_KRP, O_KRS, 64) + 8 * fq;
;                         *(f32x4*)o = a0; *(f32x4*)(o + 4) = a1; *(f32x4*)(o + 32) = b0; *(f32x4*)(o + 36) = b1;
;                         const u32x4 wa = pack8(a0, a1), wb = pack8(b0, b1);
; #pragma unroll
;                         for (int hh = 0; hh < 4; ++hh) { bf16_t* d = km + (size_t)kr * 768 + hh * 192 + 128 + 8 * fq; *(u32x4*)d = wa; *(u32x4*)(d + 32) = wb; }
;                     }
;     ...
;                 } else if (wc < 2) {
;                     float* o = ckvraw + (size_t)r * 128 + 64 * wc + 8 * fq;
.LBB0_234:
	s_lshl_b32 s45, s8, 8
	s_add_i32 s45, s45, s77
	v_or_b32_e32 v166, s45, v172
	v_cmp_gt_i32_e64 s[8:9], s76, v166
	v_cmp_lt_i32_e32 vcc, s88, v166
	s_and_saveexec_b64 s[12:13], vcc
	s_xor_b64 s[12:13], exec, s[12:13]
	s_add_i32 s11, s45, 0xffff0000
	s_lshr_b32 s11, s11, 6
	s_mulk_i32 s11, 0x440
	v_add_u32_e32 v168, s11, v176
	s_or_saveexec_b64 s[12:13], s[12:13]
	v_mov_b64_e32 v[128:129], 0x440
	v_mov_b32_e32 v130, v175
	s_xor_b64 exec, exec, s[12:13]
	v_and_b32_e32 v130, 0xfcf, v166
	v_mov_b64_e32 v[128:129], 0x1000
	v_mov_b32_e32 v168, v166
	s_or_b64 exec, exec, s[12:13]
	s_cmp_gt_i32 s10, 3
	s_cselect_b64 s[52:53], -1, 0
	s_cmp_lg_u32 s10, 7
	s_cselect_b64 s[14:15], -1, 0
	s_or_b64 s[14:15], s[42:43], s[14:15]
	s_and_b64 s[62:63], s[52:53], s[14:15]
	s_cmp_gt_i32 s10, 5
	s_cselect_b64 s[64:65], -1, 0
	s_cmp_lg_u32 s10, 6
	s_cselect_b64 s[58:59], -1, 0
	s_lshl_b32 s14, s10, 8
	s_add_i32 s54, s14, s81
	s_ashr_i32 s55, s54, 31
	s_cmp_gt_i32 s10, 1
	s_mov_b64 s[12:13], -1
	v_or_b32_e32 v187, s54, v174
	s_cselect_b64 s[60:61], -1, 0
	s_and_b64 vcc, exec, s[62:63]
	s_cbranch_vccz .LBB0_252
	s_mov_b64 s[10:11], -1
	s_and_b64 vcc, exec, s[64:65]
	s_cbranch_vccz .LBB0_249
	s_and_b64 vcc, exec, s[58:59]
	s_cbranch_vccz .LBB0_244
	s_andn2_b64 vcc, exec, s[38:39]
	s_cbranch_vccnz .LBB0_243
	v_ashrrev_i32_e32 v167, 31, v166
	v_lshlrev_b64 v[132:133], 9, v[166:167]
	v_lshl_add_u64 v[132:133], v[148:149], 0, v[132:133]
	global_store_dwordx4 v[132:133], v[124:127], off nt
	global_store_dwordx4 v[132:133], v[120:123], off offset:16 nt
	global_store_dwordx4 v[132:133], v[116:119], off offset:128 nt
	global_store_dwordx4 v[132:133], v[112:115], off offset:144 nt

; __device__ __forceinline__ u32x4 pack8(f32x4 a, f32x4 b) { u32x4 w; w.x = pk2(a[0], a[1]); w.y = pk2(a[2], a[3]); w.z = pk2(b[0], b[1]); w.w = pk2(b[2], b[3]); return w; }
;     __device__ __forceinline__ void operator()(const f32x4 (&acc)[2][2][4][2], const Unit& u, int wr, int wc, int fr, int fq) const {
;     ...
;                 } else if (pn == 6) {
;                     const int c = 64 * wc + 8 * fq; float ss = 0.f;
; #pragma unroll
;                     for (int bj = 0; bj < 2; ++bj) {
;                         const f32x4 y0 = acc[ai][bj][m][0], y1 = acc[ai][bj][m][1];
;                         const f32x4 g0 = *(const f32x4*)(gq + c + 32 * bj), g1 = *(const f32x4*)(gq + c + 32 * bj + 4);
;                         *(u32x4*)(cq + (size_t)r * 256 + c + 32 * bj) = pack8(y0 * g0, y1 * g1);
;                         ss += (y0[0] * y0[0] + y0[1] * y0[1]) + (y0[2] * y0[2] + y0[3] * y0[3]) + (y1[0] * y1[0] + y1[1] * y1[1]) + (y1[2] * y1[2] + y1[3] * y1[3]);
;                     }
;                     ss += __shfl_xor(ss, 16); ss += __shfl_xor(ss, 32);
;                     if (fq == 0) atomicAdd(rsqq + r, ss);
.LBB0_244:
	s_andn2_b64 vcc, exec, s[10:11]
	s_cbranch_vccnz .LBB0_248
	global_load_dwordx4 v[132:135], v[154:155], off
	global_load_dwordx4 v[188:191], v[154:155], off offset:16
	v_ashrrev_i32_e32 v167, 31, v166
	v_lshlrev_b64 v[170:171], 9, v[166:167]
	v_lshl_add_u64 v[170:171], v[150:151], 0, v[170:171]
	v_mul_f32_e32 v129, v125, v125
	v_mul_f32_e32 v131, v127, v127
	v_mul_f32_e32 v192, v117, v117
	v_mul_f32_e32 v193, v119, v119
	v_mul_f32_e32 v144, v121, v121
	v_mul_f32_e32 v194, v113, v113
	v_and_b32_e32 v197, 64, v180
	v_fmac_f32_e32 v129, v124, v124
	v_fmac_f32_e32 v131, v126, v126
	v_fmac_f32_e32 v192, v116, v116
	v_fmac_f32_e32 v193, v118, v118
	v_mul_f32_e32 v169, v123, v123
	v_mul_f32_e32 v195, v115, v115
	v_xor_b32_e32 v196, 16, v180
	v_fmac_f32_e32 v144, v120, v120
	v_fmac_f32_e32 v194, v112, v112
	v_add_u32_e32 v197, 64, v197
	v_add_f32_e32 v129, v129, v131
	v_add_f32_e32 v131, v192, v193
	v_fmac_f32_e32 v169, v122, v122
	v_fmac_f32_e32 v195, v114, v114
	v_cmp_lt_i32_e32 vcc, v196, v197
	v_add_f32_e32 v129, v129, v144
	v_add_f32_e32 v131, v131, v194
	v_cndmask_b32_e32 v192, v180, v196, vcc
	v_add_f32_e32 v129, v169, v129
	v_add_f32_e32 v131, v195, v131
	v_lshlrev_b32_e32 v144, 2, v192
	v_add_f32_e32 v129, v129, v131
	ds_bpermute_b32 v131, v144, v129
	v_xor_b32_e32 v144, 32, v180
	v_cmp_lt_i32_e32 vcc, v144, v197
	s_waitcnt lgkmcnt(0)
	v_add_f32_e32 v129, v129, v131
	v_cndmask_b32_e32 v144, v180, v144, vcc
	v_lshlrev_b32_e32 v144, 2, v144
	ds_bpermute_b32 v131, v144, v129
	s_waitcnt vmcnt(0)
	v_pk_mul_f32 v[134:135], v[126:127], v[134:135]
	v_pk_mul_f32 v[132:133], v[124:125], v[132:133]
	v_pk_mul_f32 v[190:191], v[122:123], v[190:191]
	v_pk_mul_f32 v[188:189], v[120:121], v[188:189]
	v_cvt_pk_bf16_f32 v132, v132, v133
	v_cvt_pk_bf16_f32 v133, v134, v135
	v_cvt_pk_bf16_f32 v134, v188, v189
	v_cvt_pk_bf16_f32 v135, v190, v191
	global_store_dwordx4 v[170:171], v[132:135], off nt
	global_load_dwordx4 v[132:135], v[154:155], off offset:128
	s_nop 0
	global_load_dwordx4 v[188:191], v[154:155], off offset:144
	s_waitcnt vmcnt(1)
	v_pk_mul_f32 v[134:135], v[118:119], v[134:135]
	v_pk_mul_f32 v[132:133], v[116:117], v[132:133]
	s_waitcnt vmcnt(0)
	v_pk_mul_f32 v[190:191], v[114:115], v[190:191]
	v_pk_mul_f32 v[188:189], v[112:113], v[188:189]
	v_cvt_pk_bf16_f32 v132, v132, v133
	v_cvt_pk_bf16_f32 v133, v134, v135
	v_cvt_pk_bf16_f32 v134, v188, v189
	v_cvt_pk_bf16_f32 v135, v190, v191
	global_store_dwordx4 v[170:171], v[132:135], off offset:64 nt
	s_and_saveexec_b64 s[10:11], s[0:1]
	s_cbranch_execz .LBB0_247
	v_lshl_add_u64 v[132:133], v[166:167], 2, s[30:31]
	s_waitcnt lgkmcnt(0)
	v_add_f32_e32 v129, v129, v131
	global_atomic_add_f32 v[132:133], v129, off

;     __device__ __forceinline__ float* out() const { return (float*)(GAS float*)ld(25); }
; __device__ __forceinline__ unsigned pk2(float lo, float hi) { f32x2_t v = {lo, hi}; bf16x2_t b = __builtin_convertvector(v, bf16x2_t); return __builtin_bit_cast(unsigned, b); }
; __device__ __forceinline__ int permk(int k) { return (k & ~12) | ((k & 4) << 1) | ((k & 8) >> 1); }
;     __device__ __forceinline__ void operator()(const f32x4 (&acc)[2][2][4][2], const Unit& u, int wr, int wc, int fr, int fq) const {
;     ...
;                 } else if (pn < 6) {
;                     const int g = 4 * (pn - 4) + wc;
;                     float* o = out_row(out, r, O_DVP, O_DVS, 512) + 64 * g + 8 * fq;
;                     const bool odd = (fr & 1) != 0;
;                     bf16_t* vb = vtd + (size_t)(kr - kl) * 512 + permk(kl & ~1);
; #pragma unroll
;                     for (int bj = 0; bj < 2; ++bj) {
;                         *(f32x4*)(o + 32 * bj) = acc[ai][bj][m][0]; *(f32x4*)(o + 32 * bj + 4) = acc[ai][bj][m][1];
;                         const f32x4 mine = odd ? acc[ai][bj][m][1] : acc[ai][bj][m][0], send = odd ? acc[ai][bj][m][0] : acc[ai][bj][m][1];
; #pragma unroll
;                         for (int e = 0; e < 4; ++e) {
;                             const float recv = __shfl_xor(send[e], 1);
;                             const int col = 64 * g + 32 * bj + 8 * fq + (odd ? 4 : 0) + e;
;                             if (!novt) *(unsigned*)(vb + (size_t)col * len) = odd ? pk2(recv, mine[e]) : pk2(mine[e], recv);
;                         }
;                     }
.LBB0_249:
	s_andn2_b64 vcc, exec, s[10:11]
	s_cbranch_vccnz .LBB0_251
	v_add_u32_e32 v129, 0xffff0000, v166
	s_waitcnt lgkmcnt(0)
	v_ashrrev_i32_e32 v131, 31, v166
	v_cndmask_b32_e64 v133, 0, v131, s[8:9]
	v_cndmask_b32_e64 v132, v129, v166, s[8:9]
	v_cndmask_b32_e64 v144, v181, v182, s[8:9]
	v_lshl_add_u64 v[134:135], s[16:17], 0, v[144:145]
	v_lshlrev_b64 v[132:133], 11, v[132:133]
	v_lshl_add_u64 v[132:133], v[134:135], 0, v[132:133]
	v_lshl_add_u64 v[132:133], s[54:55], 2, v[132:133]
	v_lshlrev_b32_e32 v144, 2, v146
	v_lshl_add_u64 v[132:133], v[132:133], 0, v[144:145]
	v_lshlrev_b32_e32 v131, 1, v130
	v_lshrrev_b32_e32 v144, 1, v130
	v_and_b32_e32 v129, 0xfc2, v130
	v_and_b32_e32 v131, 8, v131
	v_and_b32_e32 v144, 4, v144
	v_or3_b32 v129, v131, v129, v144
	v_and_b32_e32 v131, 64, v180
	v_lshlrev_b32_e32 v144, 1, v129
	v_xor_b32_e32 v129, 1, v180
	v_add_u32_e32 v131, 64, v131
	v_cmp_lt_i32_e32 vcc, v129, v131
	v_cndmask_b32_e64 v169, v124, v120, s[4:5]
	v_cndmask_b32_e64 v170, v120, v124, s[4:5]
	v_cndmask_b32_e32 v129, v180, v129, vcc
	v_lshlrev_b32_e32 v129, 2, v129
	ds_bpermute_b32 v169, v129, v169
	v_sub_u32_e32 v134, v168, v130
	v_cndmask_b32_e64 v171, v125, v121, s[4:5]
	v_ashrrev_i32_e32 v135, 31, v134
	v_cndmask_b32_e64 v189, v126, v122, s[4:5]
	s_waitcnt lgkmcnt(0)
	v_cndmask_b32_e64 v190, v170, v169, s[4:5]
	v_cndmask_b32_e64 v169, v169, v170, s[4:5]
	v_cvt_pk_bf16_f32 v169, v169, v190
	ds_bpermute_b32 v190, v129, v171
	v_lshlrev_b64 v[134:135], 10, v[134:135]
	ds_bpermute_b32 v189, v129, v189
	v_lshl_add_u64 v[134:135], s[28:29], 0, v[134:135]
	v_lshl_add_u64 v[134:135], v[134:135], 0, v[144:145]
	v_mad_i64_i32 v[170:171], s[10:11], v128, v187, 0
	v_cndmask_b32_e64 v167, v121, v125, s[4:5]
	v_lshl_add_u64 v[170:171], v[170:171], 1, v[134:135]
	global_store_dwordx4 v[132:133], v[124:127], off nt
	global_store_dwordx4 v[132:133], v[120:123], off offset:16 nt
	v_cndmask_b32_e64 v144, v122, v126, s[4:5]
	global_store_dword v[170:171], v169, off
	v_or_b32_e32 v169, 1, v187
	s_waitcnt lgkmcnt(0)
	v_cndmask_b32_e64 v170, v167, v190, s[4:5]
	v_cndmask_b32_e64 v167, v190, v167, s[4:5]
	v_cndmask_b32_e64 v188, v127, v123, s[4:5]
	v_cvt_pk_bf16_f32 v167, v167, v170
	v_mad_i64_i32 v[170:171], s[10:11], v128, v169, 0
	v_cndmask_b32_e64 v169, v144, v189, s[4:5]
	v_cndmask_b32_e64 v144, v189, v144, s[4:5]
	v_lshl_add_u64 v[170:171], v[170:171], 1, v[134:135]
	v_cvt_pk_bf16_f32 v144, v144, v169
	ds_bpermute_b32 v169, v129, v188
	global_store_dword v[170:171], v167, off
	v_or_b32_e32 v167, 2, v187
	v_mad_i64_i32 v[170:171], s[10:11], v128, v167, 0
	v_lshl_add_u64 v[170:171], v[170:171], 1, v[134:135]
	v_cndmask_b32_e64 v131, v123, v127, s[4:5]
	global_store_dword v[170:171], v144, off
	v_or_b32_e32 v144, 3, v187
	s_waitcnt lgkmcnt(0)
	v_cndmask_b32_e64 v167, v131, v169, s[4:5]
	v_cndmask_b32_e64 v131, v169, v131, s[4:5]
	v_mad_i64_i32 v[170:171], s[10:11], v128, v144, 0
	v_cvt_pk_bf16_f32 v131, v131, v167
	v_lshl_add_u64 v[170:171], v[170:171], 1, v[134:135]
	global_store_dword v[170:171], v131, off
	global_store_dwordx4 v[132:133], v[116:119], off offset:128 nt
	global_store_dwordx4 v[132:133], v[112:115], off offset:144 nt
	v_cndmask_b32_e64 v133, v116, v112, s[4:5]
	ds_bpermute_b32 v133, v129, v133
	v_cndmask_b32_e64 v171, v117, v113, s[4:5]
	ds_bpermute_b32 v171, v129, v171
	v_cndmask_b32_e64 v132, v112, v116, s[4:5]
	v_cndmask_b32_e64 v170, v118, v114, s[4:5]
	v_or_b32_e32 v188, 32, v187
	s_waitcnt lgkmcnt(0)
	v_cndmask_b32_e64 v189, v132, v133, s[4:5]
	v_cndmask_b32_e64 v132, v133, v132, s[4:5]
	v_cvt_pk_bf16_f32 v189, v132, v189
	v_mad_i64_i32 v[132:133], s[10:11], v128, v188, 0
	ds_bpermute_b32 v170, v129, v170
	v_cndmask_b32_e64 v167, v113, v117, s[4:5]
	v_lshl_add_u64 v[132:133], v[132:133], 1, v[134:135]
	v_cndmask_b32_e64 v169, v119, v115, s[4:5]
	global_store_dword v[132:133], v189, off
	v_or_b32_e32 v132, 33, v187
	v_cndmask_b32_e64 v133, v167, v171, s[4:5]
	v_cndmask_b32_e64 v167, v171, v167, s[4:5]
	v_cvt_pk_bf16_f32 v167, v167, v133
	v_mad_i64_i32 v[132:133], s[10:11], v128, v132, 0
	ds_bpermute_b32 v129, v129, v169
	v_cndmask_b32_e64 v144, v114, v118, s[4:5]
	v_lshl_add_u64 v[132:133], v[132:133], 1, v[134:135]
	global_store_dword v[132:133], v167, off
	v_or_b32_e32 v132, 34, v187
	s_waitcnt lgkmcnt(0)
	v_cndmask_b32_e64 v133, v144, v170, s[4:5]
	v_cndmask_b32_e64 v144, v170, v144, s[4:5]
	v_cvt_pk_bf16_f32 v144, v144, v133
	v_mad_i64_i32 v[132:133], s[10:11], v128, v132, 0
	v_cndmask_b32_e64 v131, v115, v119, s[4:5]
	v_lshl_add_u64 v[132:133], v[132:133], 1, v[134:135]
	global_store_dword v[132:133], v144, off
	v_or_b32_e32 v132, 35, v187
	v_cndmask_b32_e64 v133, v131, v129, s[4:5]
	v_cndmask_b32_e64 v129, v129, v131, s[4:5]
	v_cvt_pk_bf16_f32 v131, v129, v133
	v_mad_i64_i32 v[128:129], s[10:11], v128, v132, 0
	v_lshl_add_u64 v[128:129], v[128:129], 1, v[134:135]
	global_store_dword v[128:129], v131, off

;     __device__ __forceinline__ float* out() const { return (float*)(GAS float*)ld(25); }
; __device__ __forceinline__ u32x4 pack8(f32x4 a, f32x4 b) { u32x4 w; w.x = pk2(a[0], a[1]); w.y = pk2(a[2], a[3]); w.z = pk2(b[0], b[1]); w.w = pk2(b[2], b[3]); return w; }
;     __device__ __forceinline__ void operator()(const f32x4 (&acc)[2][2][4][2], const Unit& u, int wr, int wc, int fr, int fq) const {
;     ...
;                 if (do_rope) {
;                     const float* cs = rope + pos * 64 + 8 * fq;
;                     const f32x4 c0 = *(const f32x4*)cs, c1 = *(const f32x4*)(cs + 4), s0 = *(const f32x4*)(cs + 32), s1 = *(const f32x4*)(cs + 36);
;                     const f32x4 x10 = acc[ai][0][m][0], x11 = acc[ai][0][m][1], x20 = acc[ai][1][m][0], x21 = acc[ai][1][m][1];
;                     f32x4 a0 = x10 * c0 - x20 * s0, a1 = x11 * c1 - x21 * s1, b0 = x20 * c0 + x10 * s0, b1 = x21 * c1 + x11 * s1;
;                     if (pn < 2) {
;                         const int g = 4 * pn + wc;
;                         bf16_t* d = qd + (size_t)r * 512 + 64 * g + 8 * fq;
;                         *(u32x4*)d = pack8(a0 * QS_D, a1 * QS_D); *(u32x4*)(d + 32) = pack8(b0 * QS_D, b1 * QS_D);
;                     } else if (pn < 4) {
;                         const int g = 4 * (pn - 2) + wc;
;                         float* o = out_row(out, r, O_DKP, O_DKS, 512) + 64 * g + 8 * fq;
;                         *(f32x4*)o = a0; *(f32x4*)(o + 4) = a1; *(f32x4*)(o + 32) = b0; *(f32x4*)(o + 36) = b1;
;                         bf16_t* d = kd + (size_t)kr * 512 + 64 * g + 8 * fq;
;                         *(u32x4*)d = pack8(a0, a1); *(u32x4*)(d + 32) = pack8(b0, b1);
;                     } else {
;                         float* o = out_row(out, r, O_KRP, O_KRS, 64) + 8 * fq;
;                         *(f32x4*)o = a0; *(f32x4*)(o + 4) = a1; *(f32x4*)(o + 32) = b0; *(f32x4*)(o + 36) = b1;
;                         const u32x4 wa = pack8(a0, a1), wb = pack8(b0, b1);
; #pragma unroll
;                         for (int hh = 0; hh < 4; ++hh) { bf16_t* d = km + (size_t)kr * 768 + hh * 192 + 128 + 8 * fq; *(u32x4*)d = wa; *(u32x4*)(d + 32) = wb; }
;                     }
.LBB0_252:
	s_or_b32 s56, s14, s80
	s_add_i32 s20, s82, s14
	s_andn2_b64 vcc, exec, s[12:13]
	s_ashr_i32 s57, s56, 31
	s_cbranch_vccnz .LBB0_261
	v_lshlrev_b32_e32 v144, 8, v130
	v_lshl_add_u64 v[170:171], v[152:153], 0, v[144:145]
	s_waitcnt lgkmcnt(0)
	global_load_dwordx4 v[128:131], v[170:171], off offset:128
	global_load_dwordx4 v[132:135], v[170:171], off offset:144
	global_load_dwordx4 v[188:191], v[170:171], off
	global_load_dwordx4 v[192:195], v[170:171], off offset:16
	s_mov_b64 s[10:11], -1
	s_and_b64 vcc, exec, s[60:61]
	v_ashrrev_i32_e32 v167, 31, v166
	s_waitcnt vmcnt(0)
	v_pk_mul_f32 v[170:171], v[118:119], v[130:131]
	v_pk_mul_f32 v[196:197], v[116:117], v[128:129]
	v_pk_mul_f32 v[198:199], v[114:115], v[134:135]
	v_pk_mul_f32 v[200:201], v[112:113], v[132:133]
	v_pk_mul_f32 v[130:131], v[126:127], v[130:131]
	v_pk_mul_f32 v[128:129], v[124:125], v[128:129]
	v_pk_mul_f32 v[134:135], v[122:123], v[134:135]
	v_pk_mul_f32 v[132:133], v[120:121], v[132:133]
	v_pk_fma_f32 v[126:127], v[126:127], v[190:191], v[170:171] neg_lo:[0,0,1] neg_hi:[0,0,1]
	v_pk_fma_f32 v[124:125], v[124:125], v[188:189], v[196:197] neg_lo:[0,0,1] neg_hi:[0,0,1]
	v_pk_fma_f32 v[122:123], v[122:123], v[194:195], v[198:199] neg_lo:[0,0,1] neg_hi:[0,0,1]
	v_pk_fma_f32 v[120:121], v[120:121], v[192:193], v[200:201] neg_lo:[0,0,1] neg_hi:[0,0,1]
	v_pk_fma_f32 v[118:119], v[118:119], v[190:191], v[130:131]
	v_pk_fma_f32 v[116:117], v[116:117], v[188:189], v[128:129]
	v_pk_fma_f32 v[114:115], v[114:115], v[194:195], v[134:135]
	v_pk_fma_f32 v[112:113], v[112:113], v[192:193], v[132:133]
	s_cbranch_vccz .LBB0_259
	v_add_u32_e32 v128, 0xffff0000, v166
	v_cndmask_b32_e64 v171, 0, v167, s[8:9]
	v_cndmask_b32_e64 v170, v128, v166, s[8:9]
	s_and_b64 vcc, exec, s[52:53]
	v_cvt_pk_bf16_f32 v132, v124, v125
	v_cvt_pk_bf16_f32 v133, v126, v127
	v_cvt_pk_bf16_f32 v134, v120, v121
	v_cvt_pk_bf16_f32 v135, v122, v123
	v_cvt_pk_bf16_f32 v128, v116, v117
	v_cvt_pk_bf16_f32 v129, v118, v119
	v_cvt_pk_bf16_f32 v130, v112, v113
	v_cvt_pk_bf16_f32 v131, v114, v115
	s_cbranch_vccz .LBB0_256
	v_cndmask_b32_e64 v144, v183, v184, s[8:9]
	v_lshl_add_u64 v[188:189], s[16:17], 0, v[144:145]
	v_lshlrev_b64 v[190:191], 8, v[170:171]
	v_lshl_add_u64 v[188:189], v[188:189], 0, v[190:191]
	v_lshlrev_b32_e32 v144, 2, v146
	v_lshl_add_u64 v[188:189], v[188:189], 0, v[144:145]
	global_store_dwordx4 v[188:189], v[124:127], off nt
	global_store_dwordx4 v[188:189], v[120:123], off offset:16 nt
	global_store_dwordx4 v[188:189], v[116:119], off offset:128 nt
	global_store_dwordx4 v[188:189], v[112:115], off offset:144 nt
	v_mad_i64_i32 v[188:189], s[10:11], v168, s89, v[156:157]
	global_store_dwordx4 v[188:189], v[132:135], off offset:256 nt
	global_store_dwordx4 v[188:189], v[128:131], off offset:320 nt
	global_store_dwordx4 v[188:189], v[132:135], off offset:640 nt
	global_store_dwordx4 v[188:189], v[128:131], off offset:704 nt
	global_store_dwordx4 v[188:189], v[132:135], off offset:1024 nt
	global_store_dwordx4 v[188:189], v[128:131], off offset:1088 nt
	global_store_dwordx4 v[188:189], v[132:135], off offset:1408 nt
	global_store_dwordx4 v[188:189], v[128:131], off offset:1472 nt
	s_mov_b64 s[10:11], 0
.LBB0_256:
	s_andn2_b64 vcc, exec, s[10:11]
	s_cbranch_vccnz .LBB0_258
	v_cndmask_b32_e64 v144, v185, v186, s[8:9]
	v_lshl_add_u64 v[188:189], s[16:17], 0, v[144:145]
	v_lshlrev_b64 v[170:171], 11, v[170:171]
	v_ashrrev_i32_e32 v169, 31, v168
	v_lshl_add_u64 v[170:171], v[188:189], 0, v[170:171]
	v_lshlrev_b64 v[168:169], 10, v[168:169]
	v_lshl_add_u64 v[170:171], s[20:21], 2, v[170:171]
	v_lshlrev_b32_e32 v144, 2, v146
	v_lshl_add_u64 v[168:169], s[26:27], 0, v[168:169]
	v_lshl_add_u64 v[170:171], v[170:171], 0, v[144:145]
	v_lshl_add_u64 v[168:169], s[20:21], 1, v[168:169]
	v_lshlrev_b32_e32 v144, 1, v146
	v_lshl_add_u64 v[168:169], v[168:169], 0, v[144:145]
	global_store_dwordx4 v[170:171], v[124:127], off nt
	global_store_dwordx4 v[170:171], v[120:123], off offset:16 nt
	global_store_dwordx4 v[170:171], v[116:119], off offset:128 nt
	global_store_dwordx4 v[170:171], v[112:115], off offset:144 nt
	global_store_dwordx4 v[168:169], v[132:135], off nt
	global_store_dwordx4 v[168:169], v[128:131], off offset:64 nt

; __device__ __forceinline__ u32x4 pack8(f32x4 a, f32x4 b) { u32x4 w; w.x = pk2(a[0], a[1]); w.y = pk2(a[2], a[3]); w.z = pk2(b[0], b[1]); w.w = pk2(b[2], b[3]); return w; }
;     __device__ __forceinline__ void operator()(const f32x4 (&acc)[2][2][4][2], const Unit& u, int wr, int wc, int fr, int fq) const {
;     ...
;                     if (pn < 2) {
;                         const int g = 4 * pn + wc;
;                         bf16_t* d = qd + (size_t)r * 512 + 64 * g + 8 * fq;
;                         *(u32x4*)d = pack8(a0 * QS_D, a1 * QS_D); *(u32x4*)(d + 32) = pack8(b0 * QS_D, b1 * QS_D);
;     ...
;                 } else if (wc < 2) {
;                     float* o = ckvraw + (size_t)r * 128 + 64 * wc + 8 * fq;
; #pragma unroll
;                     for (int bj = 0; bj < 2; ++bj) { *(f32x4*)(o + 32 * bj) = acc[ai][bj][m][0]; *(f32x4*)(o + 32 * bj + 4) = acc[ai][bj][m][1]; }
.LBB0_259:
	s_andn2_b64 vcc, exec, s[10:11]
	s_cbranch_vccnz .LBB0_261
	v_lshlrev_b64 v[128:129], 10, v[166:167]
	v_lshl_add_u64 v[128:129], s[24:25], 0, v[128:129]
	v_lshl_add_u64 v[128:129], s[56:57], 1, v[128:129]
	v_lshlrev_b32_e32 v144, 1, v146
	v_pk_mul_f32 v[126:127], v[126:127], s[40:41] op_sel_hi:[1,0]
	v_pk_mul_f32 v[124:125], v[124:125], s[40:41] op_sel_hi:[1,0]
	v_pk_mul_f32 v[130:131], v[122:123], s[40:41] op_sel_hi:[1,0]
	v_pk_mul_f32 v[122:123], v[120:121], s[40:41] op_sel_hi:[1,0]
	v_lshl_add_u64 v[128:129], v[128:129], 0, v[144:145]
	v_cvt_pk_bf16_f32 v120, v124, v125
	v_cvt_pk_bf16_f32 v121, v126, v127
	v_cvt_pk_bf16_f32 v122, v122, v123
	v_cvt_pk_bf16_f32 v123, v130, v131
	global_store_dwordx4 v[128:129], v[120:123], off nt
	v_pk_mul_f32 v[118:119], v[118:119], s[40:41] op_sel_hi:[1,0]
	v_pk_mul_f32 v[116:117], v[116:117], s[40:41] op_sel_hi:[1,0]
	v_pk_mul_f32 v[120:121], v[114:115], s[40:41] op_sel_hi:[1,0]
	v_pk_mul_f32 v[114:115], v[112:113], s[40:41] op_sel_hi:[1,0]
	v_cvt_pk_bf16_f32 v112, v116, v117
	v_cvt_pk_bf16_f32 v113, v118, v119
	v_cvt_pk_bf16_f32 v114, v114, v115
	v_cvt_pk_bf16_f32 v115, v120, v121
	global_store_dwordx4 v[128:129], v[112:115], off offset:64 nt
.LBB0_261:
	v_or_b32_e32 v120, 16, v166
	v_cmp_gt_i32_e64 s[14:15], s76, v120
	v_cmp_lt_i32_e32 vcc, s88, v120
	s_and_saveexec_b64 s[8:9], vcc
	s_xor_b64 s[8:9], exec, s[8:9]
	s_add_i32 s10, s45, 0xffff0000
	s_lshr_b32 s10, s10, 6
	v_and_b32_e32 v112, 31, v120
	s_mulk_i32 s10, 0x440
	v_or_b32_e32 v114, 0x400, v112
	v_or_b32_e32 v112, s10, v112
	v_add_u32_e32 v122, 0x10400, v112
	s_or_saveexec_b64 s[8:9], s[8:9]
	v_mov_b64_e32 v[112:113], 0x440
	s_xor_b64 exec, exec, s[8:9]
	v_and_b32_e32 v114, 0xfdf, v120
	v_mov_b64_e32 v[112:113], 0x1000
	v_mov_b32_e32 v122, v120
	s_or_b64 exec, exec, s[8:9]
	v_cndmask_b32_e64 v113, 0, 1, s[62:63]
	v_cmp_ne_u32_e64 s[12:13], 1, v113
	v_cndmask_b32_e64 v113, 0, 1, s[64:65]
	s_mov_b64 s[8:9], -1
	s_andn2_b64 vcc, exec, s[62:63]
	v_cmp_ne_u32_e64 s[10:11], 1, v113
	s_cbranch_vccnz .LBB0_279
	s_and_b64 vcc, exec, s[10:11]
	s_cbranch_vccnz .LBB0_276
	s_andn2_b64 vcc, exec, s[58:59]
	s_cbranch_vccnz .LBB0_271
	s_andn2_b64 vcc, exec, s[38:39]
	s_cbranch_vccnz .LBB0_270
	v_ashrrev_i32_e32 v121, 31, v120
	v_lshlrev_b64 v[116:117], 9, v[120:121]
	v_lshl_add_u64 v[116:117], v[148:149], 0, v[116:117]
	global_store_dwordx4 v[116:117], v[108:111], off nt
	global_store_dwordx4 v[116:117], v[104:107], off offset:16 nt
	global_store_dwordx4 v[116:117], v[100:103], off offset:128 nt
	global_store_dwordx4 v[116:117], v[96:99], off offset:144 nt

; __device__ __forceinline__ u32x4 pack8(f32x4 a, f32x4 b) { u32x4 w; w.x = pk2(a[0], a[1]); w.y = pk2(a[2], a[3]); w.z = pk2(b[0], b[1]); w.w = pk2(b[2], b[3]); return w; }
;     __device__ __forceinline__ void operator()(const f32x4 (&acc)[2][2][4][2], const Unit& u, int wr, int wc, int fr, int fq) const {
;     ...
;                 } else if (pn == 6) {
;                     const int c = 64 * wc + 8 * fq; float ss = 0.f;
; #pragma unroll
;                     for (int bj = 0; bj < 2; ++bj) {
;                         const f32x4 y0 = acc[ai][bj][m][0], y1 = acc[ai][bj][m][1];
;                         const f32x4 g0 = *(const f32x4*)(gq + c + 32 * bj), g1 = *(const f32x4*)(gq + c + 32 * bj + 4);
;                         *(u32x4*)(cq + (size_t)r * 256 + c + 32 * bj) = pack8(y0 * g0, y1 * g1);
;                         ss += (y0[0] * y0[0] + y0[1] * y0[1]) + (y0[2] * y0[2] + y0[3] * y0[3]) + (y1[0] * y1[0] + y1[1] * y1[1]) + (y1[2] * y1[2] + y1[3] * y1[3]);
;                     }
;                     ss += __shfl_xor(ss, 16); ss += __shfl_xor(ss, 32);
;                     if (fq == 0) atomicAdd(rsqq + r, ss);
.LBB0_271:
	s_andn2_b64 vcc, exec, s[8:9]
	s_cbranch_vccnz .LBB0_275
	global_load_dwordx4 v[116:119], v[154:155], off
	global_load_dwordx4 v[124:127], v[154:155], off offset:16
	v_ashrrev_i32_e32 v121, 31, v120
	v_lshlrev_b64 v[128:129], 9, v[120:121]
	v_lshl_add_u64 v[128:129], v[150:151], 0, v[128:129]
	v_mul_f32_e32 v113, v109, v109
	v_mul_f32_e32 v115, v111, v111
	s_waitcnt lgkmcnt(0)
	v_mul_f32_e32 v131, v101, v101
	v_mul_f32_e32 v132, v103, v103
	v_mul_f32_e32 v123, v105, v105
	v_mul_f32_e32 v133, v97, v97
	v_and_b32_e32 v144, 64, v180
	v_fmac_f32_e32 v113, v108, v108
	v_fmac_f32_e32 v115, v110, v110
	v_fmac_f32_e32 v131, v100, v100
	v_fmac_f32_e32 v132, v102, v102
	v_mul_f32_e32 v130, v107, v107
	v_mul_f32_e32 v134, v99, v99
	v_xor_b32_e32 v135, 16, v180
	v_fmac_f32_e32 v123, v104, v104
	v_fmac_f32_e32 v133, v96, v96
	v_add_u32_e32 v144, 64, v144
	v_add_f32_e32 v113, v113, v115
	v_add_f32_e32 v115, v131, v132
	v_fmac_f32_e32 v130, v106, v106
	v_fmac_f32_e32 v134, v98, v98
	v_cmp_lt_i32_e32 vcc, v135, v144
	v_add_f32_e32 v113, v113, v123
	v_add_f32_e32 v115, v115, v133
	v_cndmask_b32_e32 v131, v180, v135, vcc
	v_add_f32_e32 v113, v130, v113
	v_add_f32_e32 v115, v134, v115
	v_lshlrev_b32_e32 v123, 2, v131
	v_add_f32_e32 v113, v113, v115
	ds_bpermute_b32 v115, v123, v113
	v_xor_b32_e32 v123, 32, v180
	v_cmp_lt_i32_e32 vcc, v123, v144
	s_waitcnt lgkmcnt(0)
	v_add_f32_e32 v113, v113, v115
	v_cndmask_b32_e32 v123, v180, v123, vcc
	v_lshlrev_b32_e32 v123, 2, v123
	ds_bpermute_b32 v115, v123, v113
	s_waitcnt vmcnt(0)
	v_pk_mul_f32 v[118:119], v[110:111], v[118:119]
	v_pk_mul_f32 v[116:117], v[108:109], v[116:117]
	v_pk_mul_f32 v[126:127], v[106:107], v[126:127]
	v_pk_mul_f32 v[124:125], v[104:105], v[124:125]
	v_cvt_pk_bf16_f32 v116, v116, v117
	v_cvt_pk_bf16_f32 v117, v118, v119
	v_cvt_pk_bf16_f32 v118, v124, v125
	v_cvt_pk_bf16_f32 v119, v126, v127
	global_store_dwordx4 v[128:129], v[116:119], off nt
	global_load_dwordx4 v[116:119], v[154:155], off offset:128
	s_nop 0
	global_load_dwordx4 v[124:127], v[154:155], off offset:144
	s_waitcnt vmcnt(1)
	v_pk_mul_f32 v[118:119], v[102:103], v[118:119]
	v_pk_mul_f32 v[116:117], v[100:101], v[116:117]
	s_waitcnt vmcnt(0)
	v_pk_mul_f32 v[126:127], v[98:99], v[126:127]
	v_pk_mul_f32 v[124:125], v[96:97], v[124:125]
	v_cvt_pk_bf16_f32 v116, v116, v117
	v_cvt_pk_bf16_f32 v117, v118, v119
	v_cvt_pk_bf16_f32 v118, v124, v125
	v_cvt_pk_bf16_f32 v119, v126, v127
	global_store_dwordx4 v[128:129], v[116:119], off offset:64 nt
	s_and_saveexec_b64 s[8:9], s[0:1]
	s_cbranch_execz .LBB0_274
	v_lshl_add_u64 v[116:117], v[120:121], 2, s[30:31]
	s_waitcnt lgkmcnt(0)
	v_add_f32_e32 v113, v113, v115
	global_atomic_add_f32 v[116:117], v113, off

;     __device__ __forceinline__ float* out() const { return (float*)(GAS float*)ld(25); }
; __device__ __forceinline__ unsigned pk2(float lo, float hi) { f32x2_t v = {lo, hi}; bf16x2_t b = __builtin_convertvector(v, bf16x2_t); return __builtin_bit_cast(unsigned, b); }
; __device__ __forceinline__ int permk(int k) { return (k & ~12) | ((k & 4) << 1) | ((k & 8) >> 1); }
;     __device__ __forceinline__ void operator()(const f32x4 (&acc)[2][2][4][2], const Unit& u, int wr, int wc, int fr, int fq) const {
;     ...
;                 } else if (pn < 6) {
;                     const int g = 4 * (pn - 4) + wc;
;                     float* o = out_row(out, r, O_DVP, O_DVS, 512) + 64 * g + 8 * fq;
;                     const bool odd = (fr & 1) != 0;
;                     bf16_t* vb = vtd + (size_t)(kr - kl) * 512 + permk(kl & ~1);
; #pragma unroll
;                     for (int bj = 0; bj < 2; ++bj) {
;                         *(f32x4*)(o + 32 * bj) = acc[ai][bj][m][0]; *(f32x4*)(o + 32 * bj + 4) = acc[ai][bj][m][1];
;                         const f32x4 mine = odd ? acc[ai][bj][m][1] : acc[ai][bj][m][0], send = odd ? acc[ai][bj][m][0] : acc[ai][bj][m][1];
; #pragma unroll
;                         for (int e = 0; e < 4; ++e) {
;                             const float recv = __shfl_xor(send[e], 1);
;                             const int col = 64 * g + 32 * bj + 8 * fq + (odd ? 4 : 0) + e;
;                             if (!novt) *(unsigned*)(vb + (size_t)col * len) = odd ? pk2(recv, mine[e]) : pk2(mine[e], recv);
;                         }
;                     }
.LBB0_276:
	s_andn2_b64 vcc, exec, s[8:9]
	s_cbranch_vccnz .LBB0_278
	v_add_u32_e32 v113, 0xffff0010, v166
	s_waitcnt lgkmcnt(0)
	v_ashrrev_i32_e32 v115, 31, v120
	v_cndmask_b32_e64 v117, 0, v115, s[14:15]
	v_cndmask_b32_e64 v116, v113, v120, s[14:15]
	v_cndmask_b32_e64 v144, v181, v182, s[14:15]
	v_lshl_add_u64 v[118:119], s[16:17], 0, v[144:145]
	v_lshlrev_b64 v[116:117], 11, v[116:117]
	v_lshl_add_u64 v[116:117], v[118:119], 0, v[116:117]
	v_lshlrev_b32_e32 v115, 1, v114
	v_lshrrev_b32_e32 v121, 1, v114
	v_lshl_add_u64 v[116:117], s[54:55], 2, v[116:117]
	v_lshlrev_b32_e32 v144, 2, v146
	v_and_b32_e32 v113, -14, v114
	v_and_b32_e32 v115, 8, v115
	v_and_b32_e32 v121, 4, v121
	v_lshl_add_u64 v[116:117], v[116:117], 0, v[144:145]
	v_or3_b32 v144, v115, v113, v121
	v_and_b32_e32 v115, 64, v180
	v_xor_b32_e32 v113, 1, v180
	v_add_u32_e32 v115, 64, v115
	v_cmp_lt_i32_e32 vcc, v113, v115
	v_cndmask_b32_e64 v124, v108, v104, s[4:5]
	v_sub_u32_e32 v118, v122, v114
	v_cndmask_b32_e32 v113, v180, v113, vcc
	v_lshlrev_b32_e32 v113, 2, v113
	ds_bpermute_b32 v124, v113, v124
	v_cndmask_b32_e64 v128, v109, v105, s[4:5]
	v_ashrrev_i32_e32 v119, 31, v118
	ds_bpermute_b32 v128, v113, v128
	v_lshlrev_b64 v[118:119], 10, v[118:119]
	v_cndmask_b32_e64 v125, v104, v108, s[4:5]
	v_lshl_add_u64 v[118:119], s[28:29], 0, v[118:119]
	v_cndmask_b32_e64 v127, v110, v106, s[4:5]
	s_waitcnt lgkmcnt(0)
	v_cndmask_b32_e64 v129, v125, v124, s[4:5]
	v_cndmask_b32_e64 v124, v124, v125, s[4:5]
	v_lshl_add_u64 v[118:119], v[144:145], 1, v[118:119]
	v_cvt_pk_bf16_f32 v129, v124, v129
	v_mad_i64_i32 v[124:125], s[8:9], v112, v187, 0
	ds_bpermute_b32 v127, v113, v127
	v_cndmask_b32_e64 v123, v105, v109, s[4:5]
	v_lshl_add_u64 v[124:125], v[124:125], 1, v[118:119]
	global_store_dwordx4 v[116:117], v[108:111], off nt
	global_store_dwordx4 v[116:117], v[104:107], off offset:16 nt
	global_store_dword v[124:125], v129, off
	v_or_b32_e32 v124, 1, v187
	v_cndmask_b32_e64 v125, v123, v128, s[4:5]
	v_cndmask_b32_e64 v123, v128, v123, s[4:5]
	v_cndmask_b32_e64 v126, v111, v107, s[4:5]
	v_cvt_pk_bf16_f32 v123, v123, v125
	v_mad_i64_i32 v[124:125], s[8:9], v112, v124, 0
	v_cndmask_b32_e64 v121, v106, v110, s[4:5]
	v_lshl_add_u64 v[124:125], v[124:125], 1, v[118:119]
	ds_bpermute_b32 v126, v113, v126
	global_store_dword v[124:125], v123, off
	v_or_b32_e32 v123, 2, v187
	s_waitcnt lgkmcnt(0)
	v_cndmask_b32_e64 v124, v121, v127, s[4:5]
	v_cndmask_b32_e64 v121, v127, v121, s[4:5]
	v_cvt_pk_bf16_f32 v121, v121, v124
	v_mad_i64_i32 v[124:125], s[8:9], v112, v123, 0
	v_lshl_add_u64 v[124:125], v[124:125], 1, v[118:119]
	v_cndmask_b32_e64 v115, v107, v111, s[4:5]
	global_store_dword v[124:125], v121, off
	v_or_b32_e32 v121, 3, v187
	v_cndmask_b32_e64 v123, v115, v126, s[4:5]
	v_cndmask_b32_e64 v115, v126, v115, s[4:5]
	v_mad_i64_i32 v[124:125], s[8:9], v112, v121, 0
	v_cvt_pk_bf16_f32 v115, v115, v123
	v_lshl_add_u64 v[124:125], v[124:125], 1, v[118:119]
	global_store_dword v[124:125], v115, off
	global_store_dwordx4 v[116:117], v[100:103], off offset:128 nt
	global_store_dwordx4 v[116:117], v[96:99], off offset:144 nt
	v_cndmask_b32_e64 v117, v100, v96, s[4:5]
	ds_bpermute_b32 v117, v113, v117
	v_cndmask_b32_e64 v126, v101, v97, s[4:5]
	ds_bpermute_b32 v126, v113, v126
	v_cndmask_b32_e64 v116, v96, v100, s[4:5]
	v_cndmask_b32_e64 v125, v102, v98, s[4:5]
	v_or_b32_e32 v127, 32, v187
	s_waitcnt lgkmcnt(0)
	v_cndmask_b32_e64 v128, v116, v117, s[4:5]
	v_cndmask_b32_e64 v116, v117, v116, s[4:5]
	v_cvt_pk_bf16_f32 v128, v116, v128
	v_mad_i64_i32 v[116:117], s[8:9], v112, v127, 0
	ds_bpermute_b32 v125, v113, v125
	v_cndmask_b32_e64 v123, v97, v101, s[4:5]
	v_lshl_add_u64 v[116:117], v[116:117], 1, v[118:119]
	v_cndmask_b32_e64 v124, v103, v99, s[4:5]
	global_store_dword v[116:117], v128, off
	v_or_b32_e32 v116, 33, v187
	v_cndmask_b32_e64 v117, v123, v126, s[4:5]
	v_cndmask_b32_e64 v123, v126, v123, s[4:5]
	v_cvt_pk_bf16_f32 v123, v123, v117
	v_mad_i64_i32 v[116:117], s[8:9], v112, v116, 0
	ds_bpermute_b32 v113, v113, v124
	v_cndmask_b32_e64 v121, v98, v102, s[4:5]
	v_lshl_add_u64 v[116:117], v[116:117], 1, v[118:119]
	global_store_dword v[116:117], v123, off
	v_or_b32_e32 v116, 34, v187
	s_waitcnt lgkmcnt(0)
	v_cndmask_b32_e64 v117, v121, v125, s[4:5]
	v_cndmask_b32_e64 v121, v125, v121, s[4:5]
	v_cvt_pk_bf16_f32 v121, v121, v117
	v_mad_i64_i32 v[116:117], s[8:9], v112, v116, 0
	v_cndmask_b32_e64 v115, v99, v103, s[4:5]
	v_lshl_add_u64 v[116:117], v[116:117], 1, v[118:119]
	global_store_dword v[116:117], v121, off
	v_or_b32_e32 v116, 35, v187
	v_cndmask_b32_e64 v117, v115, v113, s[4:5]
	v_cndmask_b32_e64 v113, v113, v115, s[4:5]
	v_cvt_pk_bf16_f32 v115, v113, v117
	v_mad_i64_i32 v[112:113], s[8:9], v112, v116, 0
	v_lshl_add_u64 v[112:113], v[112:113], 1, v[118:119]
	global_store_dword v[112:113], v115, off

;     __device__ __forceinline__ float* out() const { return (float*)(GAS float*)ld(25); }
; __device__ __forceinline__ u32x4 pack8(f32x4 a, f32x4 b) { u32x4 w; w.x = pk2(a[0], a[1]); w.y = pk2(a[2], a[3]); w.z = pk2(b[0], b[1]); w.w = pk2(b[2], b[3]); return w; }
;     __device__ __forceinline__ void operator()(const f32x4 (&acc)[2][2][4][2], const Unit& u, int wr, int wc, int fr, int fq) const {
;     ...
;                 if (do_rope) {
;                     const float* cs = rope + pos * 64 + 8 * fq;
;                     const f32x4 c0 = *(const f32x4*)cs, c1 = *(const f32x4*)(cs + 4), s0 = *(const f32x4*)(cs + 32), s1 = *(const f32x4*)(cs + 36);
;                     const f32x4 x10 = acc[ai][0][m][0], x11 = acc[ai][0][m][1], x20 = acc[ai][1][m][0], x21 = acc[ai][1][m][1];
;                     f32x4 a0 = x10 * c0 - x20 * s0, a1 = x11 * c1 - x21 * s1, b0 = x20 * c0 + x10 * s0, b1 = x21 * c1 + x11 * s1;
;                     if (pn < 2) {
;                         const int g = 4 * pn + wc;
;                         bf16_t* d = qd + (size_t)r * 512 + 64 * g + 8 * fq;
;                         *(u32x4*)d = pack8(a0 * QS_D, a1 * QS_D); *(u32x4*)(d + 32) = pack8(b0 * QS_D, b1 * QS_D);
;                     } else if (pn < 4) {
;                         const int g = 4 * (pn - 2) + wc;
;                         float* o = out_row(out, r, O_DKP, O_DKS, 512) + 64 * g + 8 * fq;
;                         *(f32x4*)o = a0; *(f32x4*)(o + 4) = a1; *(f32x4*)(o + 32) = b0; *(f32x4*)(o + 36) = b1;
;                         bf16_t* d = kd + (size_t)kr * 512 + 64 * g + 8 * fq;
;                         *(u32x4*)d = pack8(a0, a1); *(u32x4*)(d + 32) = pack8(b0, b1);
;                     } else {
;                         float* o = out_row(out, r, O_KRP, O_KRS, 64) + 8 * fq;
;                         *(f32x4*)o = a0; *(f32x4*)(o + 4) = a1; *(f32x4*)(o + 32) = b0; *(f32x4*)(o + 36) = b1;
;                         const u32x4 wa = pack8(a0, a1), wb = pack8(b0, b1);
; #pragma unroll
;                         for (int hh = 0; hh < 4; ++hh) { bf16_t* d = km + (size_t)kr * 768 + hh * 192 + 128 + 8 * fq; *(u32x4*)d = wa; *(u32x4*)(d + 32) = wb; }
;                     }
.LBB0_279:
	v_cndmask_b32_e64 v112, 0, 1, s[60:61]
	s_andn2_b64 vcc, exec, s[8:9]
	v_cmp_ne_u32_e64 s[8:9], 1, v112
	s_cbranch_vccnz .LBB0_288
	v_lshlrev_b32_e32 v144, 6, v114
	v_lshl_add_u64 v[128:129], v[144:145], 2, v[152:153]
	s_waitcnt lgkmcnt(0)
	global_load_dwordx4 v[112:115], v[128:129], off offset:128
	global_load_dwordx4 v[116:119], v[128:129], off offset:144
	global_load_dwordx4 v[124:127], v[128:129], off
	s_nop 0
	global_load_dwordx4 v[128:131], v[128:129], off offset:16
	s_mov_b64 s[60:61], -1
	s_and_b64 vcc, exec, s[8:9]
	v_ashrrev_i32_e32 v121, 31, v120
	s_waitcnt vmcnt(0)
	v_pk_mul_f32 v[132:133], v[102:103], v[114:115]
	v_pk_mul_f32 v[134:135], v[100:101], v[112:113]
	v_pk_mul_f32 v[168:169], v[98:99], v[118:119]
	v_pk_mul_f32 v[170:171], v[96:97], v[116:117]
	v_pk_mul_f32 v[114:115], v[110:111], v[114:115]
	v_pk_mul_f32 v[112:113], v[108:109], v[112:113]
	v_pk_mul_f32 v[118:119], v[106:107], v[118:119]
	v_pk_mul_f32 v[116:117], v[104:105], v[116:117]
	v_pk_fma_f32 v[110:111], v[110:111], v[126:127], v[132:133] neg_lo:[0,0,1] neg_hi:[0,0,1]
	v_pk_fma_f32 v[108:109], v[108:109], v[124:125], v[134:135] neg_lo:[0,0,1] neg_hi:[0,0,1]
	v_pk_fma_f32 v[106:107], v[106:107], v[130:131], v[168:169] neg_lo:[0,0,1] neg_hi:[0,0,1]
	v_pk_fma_f32 v[104:105], v[104:105], v[128:129], v[170:171] neg_lo:[0,0,1] neg_hi:[0,0,1]
	v_pk_fma_f32 v[102:103], v[102:103], v[126:127], v[114:115]
	v_pk_fma_f32 v[100:101], v[100:101], v[124:125], v[112:113]
	v_pk_fma_f32 v[98:99], v[98:99], v[130:131], v[118:119]
	v_pk_fma_f32 v[96:97], v[96:97], v[128:129], v[116:117]
	s_cbranch_vccnz .LBB0_286
	v_add_u32_e32 v112, 0xffff0010, v166
	v_cndmask_b32_e64 v125, 0, v121, s[14:15]
	v_cndmask_b32_e64 v124, v112, v120, s[14:15]
	s_andn2_b64 vcc, exec, s[52:53]
	v_cvt_pk_bf16_f32 v116, v108, v109
	v_cvt_pk_bf16_f32 v117, v110, v111
	v_cvt_pk_bf16_f32 v118, v104, v105
	v_cvt_pk_bf16_f32 v119, v106, v107
	v_cvt_pk_bf16_f32 v112, v100, v101
	v_cvt_pk_bf16_f32 v113, v102, v103
	v_cvt_pk_bf16_f32 v114, v96, v97
	v_cvt_pk_bf16_f32 v115, v98, v99
	s_cbranch_vccnz .LBB0_283
	v_cndmask_b32_e64 v144, v183, v184, s[14:15]
	v_lshl_add_u64 v[126:127], s[16:17], 0, v[144:145]
	v_lshlrev_b64 v[128:129], 8, v[124:125]
	v_lshl_add_u64 v[126:127], v[126:127], 0, v[128:129]
	v_lshlrev_b32_e32 v144, 2, v146
	v_lshl_add_u64 v[126:127], v[126:127], 0, v[144:145]
	global_store_dwordx4 v[126:127], v[108:111], off nt
	global_store_dwordx4 v[126:127], v[104:107], off offset:16 nt
	global_store_dwordx4 v[126:127], v[100:103], off offset:128 nt
	global_store_dwordx4 v[126:127], v[96:99], off offset:144 nt
	v_mad_i64_i32 v[126:127], s[60:61], v122, s89, v[156:157]
	s_mov_b64 s[60:61], 0
	global_store_dwordx4 v[126:127], v[116:119], off offset:256 nt
	global_store_dwordx4 v[126:127], v[112:115], off offset:320 nt
	global_store_dwordx4 v[126:127], v[116:119], off offset:640 nt
	global_store_dwordx4 v[126:127], v[112:115], off offset:704 nt
	global_store_dwordx4 v[126:127], v[116:119], off offset:1024 nt
	global_store_dwordx4 v[126:127], v[112:115], off offset:1088 nt
	global_store_dwordx4 v[126:127], v[116:119], off offset:1408 nt
	global_store_dwordx4 v[126:127], v[112:115], off offset:1472 nt
.LBB0_283:
	s_andn2_b64 vcc, exec, s[60:61]
	s_cbranch_vccnz .LBB0_285
	v_cndmask_b32_e64 v144, v185, v186, s[14:15]
	v_lshl_add_u64 v[126:127], s[16:17], 0, v[144:145]
	v_lshlrev_b64 v[124:125], 11, v[124:125]
	v_ashrrev_i32_e32 v123, 31, v122
	v_lshl_add_u64 v[124:125], v[126:127], 0, v[124:125]
	v_lshlrev_b64 v[122:123], 10, v[122:123]
	v_lshl_add_u64 v[124:125], s[20:21], 2, v[124:125]
	v_lshlrev_b32_e32 v144, 2, v146
	v_lshl_add_u64 v[122:123], s[26:27], 0, v[122:123]
	v_lshl_add_u64 v[124:125], v[124:125], 0, v[144:145]
	v_lshl_add_u64 v[122:123], s[20:21], 1, v[122:123]
	v_lshlrev_b32_e32 v144, 1, v146
	v_lshl_add_u64 v[122:123], v[122:123], 0, v[144:145]
	global_store_dwordx4 v[124:125], v[108:111], off nt
	global_store_dwordx4 v[124:125], v[104:107], off offset:16 nt
	global_store_dwordx4 v[124:125], v[100:103], off offset:128 nt
	global_store_dwordx4 v[124:125], v[96:99], off offset:144 nt
	global_store_dwordx4 v[122:123], v[116:119], off nt
	global_store_dwordx4 v[122:123], v[112:115], off offset:64 nt

; __device__ __forceinline__ u32x4 pack8(f32x4 a, f32x4 b) { u32x4 w; w.x = pk2(a[0], a[1]); w.y = pk2(a[2], a[3]); w.z = pk2(b[0], b[1]); w.w = pk2(b[2], b[3]); return w; }
;     __device__ __forceinline__ void operator()(const f32x4 (&acc)[2][2][4][2], const Unit& u, int wr, int wc, int fr, int fq) const {
;     ...
;                     if (pn < 2) {
;                         const int g = 4 * pn + wc;
;                         bf16_t* d = qd + (size_t)r * 512 + 64 * g + 8 * fq;
;                         *(u32x4*)d = pack8(a0 * QS_D, a1 * QS_D); *(u32x4*)(d + 32) = pack8(b0 * QS_D, b1 * QS_D);
.LBB0_286:
	s_andn2_b64 vcc, exec, s[60:61]
	s_cbranch_vccnz .LBB0_288
	v_lshlrev_b64 v[112:113], 10, v[120:121]
	v_lshl_add_u64 v[112:113], s[24:25], 0, v[112:113]
	v_lshl_add_u64 v[112:113], s[56:57], 1, v[112:113]
	v_lshlrev_b32_e32 v144, 1, v146
	v_pk_mul_f32 v[110:111], v[110:111], s[40:41] op_sel_hi:[1,0]
	v_pk_mul_f32 v[108:109], v[108:109], s[40:41] op_sel_hi:[1,0]
	v_pk_mul_f32 v[114:115], v[106:107], s[40:41] op_sel_hi:[1,0]
	v_pk_mul_f32 v[106:107], v[104:105], s[40:41] op_sel_hi:[1,0]
	v_lshl_add_u64 v[112:113], v[112:113], 0, v[144:145]
	v_cvt_pk_bf16_f32 v104, v108, v109
	v_cvt_pk_bf16_f32 v105, v110, v111
	v_cvt_pk_bf16_f32 v106, v106, v107
	v_cvt_pk_bf16_f32 v107, v114, v115
	global_store_dwordx4 v[112:113], v[104:107], off nt
	v_pk_mul_f32 v[102:103], v[102:103], s[40:41] op_sel_hi:[1,0]
	v_pk_mul_f32 v[100:101], v[100:101], s[40:41] op_sel_hi:[1,0]
	v_pk_mul_f32 v[104:105], v[98:99], s[40:41] op_sel_hi:[1,0]
	v_pk_mul_f32 v[98:99], v[96:97], s[40:41] op_sel_hi:[1,0]
	v_cvt_pk_bf16_f32 v96, v100, v101
	v_cvt_pk_bf16_f32 v97, v102, v103
	v_cvt_pk_bf16_f32 v98, v98, v99
	v_cvt_pk_bf16_f32 v99, v104, v105
	global_store_dwordx4 v[112:113], v[96:99], off offset:64 nt

;     __device__ __forceinline__ void operator()(const f32x4 (&acc)[2][2][4][2], const Unit& u, int wr, int wc, int fr, int fq) const {
;     ...
;                 } else if (wc < 2) {
;                     float* o = ckvraw + (size_t)r * 128 + 64 * wc + 8 * fq;
; #pragma unroll
;                     for (int bj = 0; bj < 2; ++bj) { *(f32x4*)(o + 32 * bj) = acc[ai][bj][m][0]; *(f32x4*)(o + 32 * bj + 4) = acc[ai][bj][m][1]; }
.LBB0_294:
	s_and_b64 vcc, exec, s[10:11]
	s_cbranch_vccnz .LBB0_304
	s_andn2_b64 vcc, exec, s[58:59]
	s_cbranch_vccnz .LBB0_299
	s_andn2_b64 vcc, exec, s[38:39]
	s_cbranch_vccnz .LBB0_298
	v_ashrrev_i32_e32 v105, 31, v104
	v_lshlrev_b64 v[100:101], 9, v[104:105]
	v_lshl_add_u64 v[100:101], v[148:149], 0, v[100:101]
	global_store_dwordx4 v[100:101], v[92:95], off nt
	global_store_dwordx4 v[100:101], v[88:91], off offset:16 nt
	global_store_dwordx4 v[100:101], v[84:87], off offset:128 nt
	global_store_dwordx4 v[100:101], v[80:83], off offset:144 nt

; __device__ __forceinline__ u32x4 pack8(f32x4 a, f32x4 b) { u32x4 w; w.x = pk2(a[0], a[1]); w.y = pk2(a[2], a[3]); w.z = pk2(b[0], b[1]); w.w = pk2(b[2], b[3]); return w; }
;     __device__ __forceinline__ void operator()(const f32x4 (&acc)[2][2][4][2], const Unit& u, int wr, int wc, int fr, int fq) const {
;     ...
;                 } else if (pn == 6) {
;                     const int c = 64 * wc + 8 * fq; float ss = 0.f;
; #pragma unroll
;                     for (int bj = 0; bj < 2; ++bj) {
;                         const f32x4 y0 = acc[ai][bj][m][0], y1 = acc[ai][bj][m][1];
;                         const f32x4 g0 = *(const f32x4*)(gq + c + 32 * bj), g1 = *(const f32x4*)(gq + c + 32 * bj + 4);
;                         *(u32x4*)(cq + (size_t)r * 256 + c + 32 * bj) = pack8(y0 * g0, y1 * g1);
;                         ss += (y0[0] * y0[0] + y0[1] * y0[1]) + (y0[2] * y0[2] + y0[3] * y0[3]) + (y1[0] * y1[0] + y1[1] * y1[1]) + (y1[2] * y1[2] + y1[3] * y1[3]);
;                     }
;                     ss += __shfl_xor(ss, 16); ss += __shfl_xor(ss, 32);
;                     if (fq == 0) atomicAdd(rsqq + r, ss);
.LBB0_299:
	s_andn2_b64 vcc, exec, s[60:61]
	s_cbranch_vccnz .LBB0_303
	global_load_dwordx4 v[100:103], v[154:155], off
	global_load_dwordx4 v[108:111], v[154:155], off offset:16
	v_ashrrev_i32_e32 v105, 31, v104
	v_lshlrev_b64 v[112:113], 9, v[104:105]
	v_lshl_add_u64 v[112:113], v[150:151], 0, v[112:113]
	v_mul_f32_e32 v97, v93, v93
	v_mul_f32_e32 v99, v95, v95
	s_waitcnt lgkmcnt(0)
	v_mul_f32_e32 v115, v85, v85
	v_mul_f32_e32 v116, v87, v87
	v_mul_f32_e32 v107, v89, v89
	v_mul_f32_e32 v117, v81, v81
	v_and_b32_e32 v120, 64, v180
	v_fmac_f32_e32 v97, v92, v92
	v_fmac_f32_e32 v99, v94, v94
	v_fmac_f32_e32 v115, v84, v84
	v_fmac_f32_e32 v116, v86, v86
	v_mul_f32_e32 v114, v91, v91
	v_mul_f32_e32 v118, v83, v83
	v_xor_b32_e32 v119, 16, v180
	v_fmac_f32_e32 v107, v88, v88
	v_fmac_f32_e32 v117, v80, v80
	v_add_u32_e32 v120, 64, v120
	v_add_f32_e32 v97, v97, v99
	v_add_f32_e32 v99, v115, v116
	v_fmac_f32_e32 v114, v90, v90
	v_fmac_f32_e32 v118, v82, v82
	v_cmp_lt_i32_e32 vcc, v119, v120
	v_add_f32_e32 v97, v97, v107
	v_add_f32_e32 v99, v99, v117
	v_cndmask_b32_e32 v115, v180, v119, vcc
	v_add_f32_e32 v97, v114, v97
	v_add_f32_e32 v99, v118, v99
	v_lshlrev_b32_e32 v107, 2, v115
	v_add_f32_e32 v97, v97, v99
	ds_bpermute_b32 v99, v107, v97
	v_xor_b32_e32 v107, 32, v180
	v_cmp_lt_i32_e32 vcc, v107, v120
	s_waitcnt lgkmcnt(0)
	v_add_f32_e32 v97, v97, v99
	v_cndmask_b32_e32 v107, v180, v107, vcc
	v_lshlrev_b32_e32 v107, 2, v107
	ds_bpermute_b32 v99, v107, v97
	s_waitcnt vmcnt(0)
	v_pk_mul_f32 v[102:103], v[94:95], v[102:103]
	v_pk_mul_f32 v[100:101], v[92:93], v[100:101]
	v_pk_mul_f32 v[110:111], v[90:91], v[110:111]
	v_pk_mul_f32 v[108:109], v[88:89], v[108:109]
	v_cvt_pk_bf16_f32 v100, v100, v101
	v_cvt_pk_bf16_f32 v101, v102, v103
	v_cvt_pk_bf16_f32 v102, v108, v109
	v_cvt_pk_bf16_f32 v103, v110, v111
	global_store_dwordx4 v[112:113], v[100:103], off nt
	global_load_dwordx4 v[100:103], v[154:155], off offset:128
	s_nop 0
	global_load_dwordx4 v[108:111], v[154:155], off offset:144
	s_waitcnt vmcnt(1)
	v_pk_mul_f32 v[102:103], v[86:87], v[102:103]
	v_pk_mul_f32 v[100:101], v[84:85], v[100:101]
	s_waitcnt vmcnt(0)
	v_pk_mul_f32 v[110:111], v[82:83], v[110:111]
	v_pk_mul_f32 v[108:109], v[80:81], v[108:109]
	v_cvt_pk_bf16_f32 v100, v100, v101
	v_cvt_pk_bf16_f32 v101, v102, v103
	v_cvt_pk_bf16_f32 v102, v108, v109
	v_cvt_pk_bf16_f32 v103, v110, v111
	global_store_dwordx4 v[112:113], v[100:103], off offset:64 nt
	s_and_saveexec_b64 s[60:61], s[0:1]
	s_cbranch_execz .LBB0_302
	v_lshl_add_u64 v[100:101], v[104:105], 2, s[30:31]
	s_waitcnt lgkmcnt(0)
	v_add_f32_e32 v97, v97, v99
	global_atomic_add_f32 v[100:101], v97, off

;     __device__ __forceinline__ float* out() const { return (float*)(GAS float*)ld(25); }
; __device__ __forceinline__ unsigned pk2(float lo, float hi) { f32x2_t v = {lo, hi}; bf16x2_t b = __builtin_convertvector(v, bf16x2_t); return __builtin_bit_cast(unsigned, b); }
; __device__ __forceinline__ int permk(int k) { return (k & ~12) | ((k & 4) << 1) | ((k & 8) >> 1); }
;     __device__ __forceinline__ void operator()(const f32x4 (&acc)[2][2][4][2], const Unit& u, int wr, int wc, int fr, int fq) const {
;     ...
;                 } else if (pn < 6) {
;                     const int g = 4 * (pn - 4) + wc;
;                     float* o = out_row(out, r, O_DVP, O_DVS, 512) + 64 * g + 8 * fq;
;                     const bool odd = (fr & 1) != 0;
;                     bf16_t* vb = vtd + (size_t)(kr - kl) * 512 + permk(kl & ~1);
; #pragma unroll
;                     for (int bj = 0; bj < 2; ++bj) {
;                         *(f32x4*)(o + 32 * bj) = acc[ai][bj][m][0]; *(f32x4*)(o + 32 * bj + 4) = acc[ai][bj][m][1];
;                         const f32x4 mine = odd ? acc[ai][bj][m][1] : acc[ai][bj][m][0], send = odd ? acc[ai][bj][m][0] : acc[ai][bj][m][1];
; #pragma unroll
;                         for (int e = 0; e < 4; ++e) {
;                             const float recv = __shfl_xor(send[e], 1);
;                             const int col = 64 * g + 32 * bj + 8 * fq + (odd ? 4 : 0) + e;
;                             if (!novt) *(unsigned*)(vb + (size_t)col * len) = odd ? pk2(recv, mine[e]) : pk2(mine[e], recv);
;                         }
;                     }
.LBB0_304:
	s_andn2_b64 vcc, exec, s[60:61]
	s_cbranch_vccnz .LBB0_306
	v_add_u32_e32 v97, 0xffff0020, v166
	s_waitcnt lgkmcnt(0)
	v_ashrrev_i32_e32 v99, 31, v104
	v_cndmask_b32_e64 v101, 0, v99, s[14:15]
	v_cndmask_b32_e64 v100, v97, v104, s[14:15]
	v_cndmask_b32_e64 v144, v181, v182, s[14:15]
	v_lshl_add_u64 v[102:103], s[16:17], 0, v[144:145]
	v_lshlrev_b64 v[100:101], 11, v[100:101]
	v_lshl_add_u64 v[100:101], v[102:103], 0, v[100:101]
	v_lshlrev_b32_e32 v99, 1, v98
	v_lshrrev_b32_e32 v105, 1, v98
	v_lshl_add_u64 v[100:101], s[54:55], 2, v[100:101]
	v_lshlrev_b32_e32 v144, 2, v146
	v_and_b32_e32 v97, -14, v98
	v_and_b32_e32 v99, 8, v99
	v_and_b32_e32 v105, 4, v105
	v_lshl_add_u64 v[100:101], v[100:101], 0, v[144:145]
	v_or3_b32 v144, v99, v97, v105
	v_and_b32_e32 v99, 64, v180
	v_xor_b32_e32 v97, 1, v180
	v_add_u32_e32 v99, 64, v99
	v_cmp_lt_i32_e32 vcc, v97, v99
	v_cndmask_b32_e64 v108, v92, v88, s[4:5]
	v_sub_u32_e32 v102, v106, v98
	v_cndmask_b32_e32 v97, v180, v97, vcc
	v_lshlrev_b32_e32 v97, 2, v97
	ds_bpermute_b32 v108, v97, v108
	v_cndmask_b32_e64 v112, v93, v89, s[4:5]
	v_ashrrev_i32_e32 v103, 31, v102
	ds_bpermute_b32 v112, v97, v112
	v_lshlrev_b64 v[102:103], 10, v[102:103]
	v_cndmask_b32_e64 v109, v88, v92, s[4:5]
	v_lshl_add_u64 v[102:103], s[28:29], 0, v[102:103]
	v_cndmask_b32_e64 v111, v94, v90, s[4:5]
	s_waitcnt lgkmcnt(0)
	v_cndmask_b32_e64 v113, v109, v108, s[4:5]
	v_cndmask_b32_e64 v108, v108, v109, s[4:5]
	v_lshl_add_u64 v[102:103], v[144:145], 1, v[102:103]
	v_cvt_pk_bf16_f32 v113, v108, v113
	v_mad_i64_i32 v[108:109], s[60:61], v96, v187, 0
	ds_bpermute_b32 v111, v97, v111
	v_cndmask_b32_e64 v107, v89, v93, s[4:5]
	v_lshl_add_u64 v[108:109], v[108:109], 1, v[102:103]
	global_store_dwordx4 v[100:101], v[92:95], off nt
	global_store_dwordx4 v[100:101], v[88:91], off offset:16 nt
	global_store_dword v[108:109], v113, off
	v_or_b32_e32 v108, 1, v187
	v_cndmask_b32_e64 v109, v107, v112, s[4:5]
	v_cndmask_b32_e64 v107, v112, v107, s[4:5]
	v_cndmask_b32_e64 v110, v95, v91, s[4:5]
	v_cvt_pk_bf16_f32 v107, v107, v109
	v_mad_i64_i32 v[108:109], s[60:61], v96, v108, 0
	v_cndmask_b32_e64 v105, v90, v94, s[4:5]
	v_lshl_add_u64 v[108:109], v[108:109], 1, v[102:103]
	ds_bpermute_b32 v110, v97, v110
	global_store_dword v[108:109], v107, off
	v_or_b32_e32 v107, 2, v187
	s_waitcnt lgkmcnt(0)
	v_cndmask_b32_e64 v108, v105, v111, s[4:5]
	v_cndmask_b32_e64 v105, v111, v105, s[4:5]
	v_cvt_pk_bf16_f32 v105, v105, v108
	v_mad_i64_i32 v[108:109], s[60:61], v96, v107, 0
	v_lshl_add_u64 v[108:109], v[108:109], 1, v[102:103]
	v_cndmask_b32_e64 v99, v91, v95, s[4:5]
	global_store_dword v[108:109], v105, off
	v_or_b32_e32 v105, 3, v187
	v_cndmask_b32_e64 v107, v99, v110, s[4:5]
	v_cndmask_b32_e64 v99, v110, v99, s[4:5]
	v_mad_i64_i32 v[108:109], s[60:61], v96, v105, 0
	v_cvt_pk_bf16_f32 v99, v99, v107
	v_lshl_add_u64 v[108:109], v[108:109], 1, v[102:103]
	global_store_dword v[108:109], v99, off
	global_store_dwordx4 v[100:101], v[84:87], off offset:128 nt
	global_store_dwordx4 v[100:101], v[80:83], off offset:144 nt
	v_cndmask_b32_e64 v101, v84, v80, s[4:5]
	ds_bpermute_b32 v101, v97, v101
	v_cndmask_b32_e64 v110, v85, v81, s[4:5]
	ds_bpermute_b32 v110, v97, v110
	v_cndmask_b32_e64 v100, v80, v84, s[4:5]
	v_cndmask_b32_e64 v109, v86, v82, s[4:5]
	v_or_b32_e32 v111, 32, v187
	s_waitcnt lgkmcnt(0)
	v_cndmask_b32_e64 v112, v100, v101, s[4:5]
	v_cndmask_b32_e64 v100, v101, v100, s[4:5]
	v_cvt_pk_bf16_f32 v112, v100, v112
	v_mad_i64_i32 v[100:101], s[60:61], v96, v111, 0
	ds_bpermute_b32 v109, v97, v109
	v_cndmask_b32_e64 v107, v81, v85, s[4:5]
	v_lshl_add_u64 v[100:101], v[100:101], 1, v[102:103]
	v_cndmask_b32_e64 v108, v87, v83, s[4:5]
	global_store_dword v[100:101], v112, off
	v_or_b32_e32 v100, 33, v187
	v_cndmask_b32_e64 v101, v107, v110, s[4:5]
	v_cndmask_b32_e64 v107, v110, v107, s[4:5]
	v_cvt_pk_bf16_f32 v107, v107, v101
	v_mad_i64_i32 v[100:101], s[60:61], v96, v100, 0
	ds_bpermute_b32 v97, v97, v108
	v_cndmask_b32_e64 v105, v82, v86, s[4:5]
	v_lshl_add_u64 v[100:101], v[100:101], 1, v[102:103]
	global_store_dword v[100:101], v107, off
	v_or_b32_e32 v100, 34, v187
	s_waitcnt lgkmcnt(0)
	v_cndmask_b32_e64 v101, v105, v109, s[4:5]
	v_cndmask_b32_e64 v105, v109, v105, s[4:5]
	v_cvt_pk_bf16_f32 v105, v105, v101
	v_mad_i64_i32 v[100:101], s[60:61], v96, v100, 0
	v_cndmask_b32_e64 v99, v83, v87, s[4:5]
	v_lshl_add_u64 v[100:101], v[100:101], 1, v[102:103]
	global_store_dword v[100:101], v105, off
	v_or_b32_e32 v100, 35, v187
	v_cndmask_b32_e64 v101, v99, v97, s[4:5]
	v_cndmask_b32_e64 v97, v97, v99, s[4:5]
	v_cvt_pk_bf16_f32 v99, v97, v101
	v_mad_i64_i32 v[96:97], s[60:61], v96, v100, 0
	v_lshl_add_u64 v[96:97], v[96:97], 1, v[102:103]
	global_store_dword v[96:97], v99, off

;     __device__ __forceinline__ float* out() const { return (float*)(GAS float*)ld(25); }
; __device__ __forceinline__ u32x4 pack8(f32x4 a, f32x4 b) { u32x4 w; w.x = pk2(a[0], a[1]); w.y = pk2(a[2], a[3]); w.z = pk2(b[0], b[1]); w.w = pk2(b[2], b[3]); return w; }
;     __device__ __forceinline__ void operator()(const f32x4 (&acc)[2][2][4][2], const Unit& u, int wr, int wc, int fr, int fq) const {
;     ...
;                 if (do_rope) {
;                     const float* cs = rope + pos * 64 + 8 * fq;
;                     const f32x4 c0 = *(const f32x4*)cs, c1 = *(const f32x4*)(cs + 4), s0 = *(const f32x4*)(cs + 32), s1 = *(const f32x4*)(cs + 36);
;                     const f32x4 x10 = acc[ai][0][m][0], x11 = acc[ai][0][m][1], x20 = acc[ai][1][m][0], x21 = acc[ai][1][m][1];
;                     f32x4 a0 = x10 * c0 - x20 * s0, a1 = x11 * c1 - x21 * s1, b0 = x20 * c0 + x10 * s0, b1 = x21 * c1 + x11 * s1;
;                     if (pn < 2) {
;                         const int g = 4 * pn + wc;
;                         bf16_t* d = qd + (size_t)r * 512 + 64 * g + 8 * fq;
;                         *(u32x4*)d = pack8(a0 * QS_D, a1 * QS_D); *(u32x4*)(d + 32) = pack8(b0 * QS_D, b1 * QS_D);
;                     } else if (pn < 4) {
;                         const int g = 4 * (pn - 2) + wc;
;                         float* o = out_row(out, r, O_DKP, O_DKS, 512) + 64 * g + 8 * fq;
;                         *(f32x4*)o = a0; *(f32x4*)(o + 4) = a1; *(f32x4*)(o + 32) = b0; *(f32x4*)(o + 36) = b1;
;                         bf16_t* d = kd + (size_t)kr * 512 + 64 * g + 8 * fq;
;                         *(u32x4*)d = pack8(a0, a1); *(u32x4*)(d + 32) = pack8(b0, b1);
;                     } else {
;                         float* o = out_row(out, r, O_KRP, O_KRS, 64) + 8 * fq;
;                         *(f32x4*)o = a0; *(f32x4*)(o + 4) = a1; *(f32x4*)(o + 32) = b0; *(f32x4*)(o + 36) = b1;
;                         const u32x4 wa = pack8(a0, a1), wb = pack8(b0, b1);
; #pragma unroll
;                         for (int hh = 0; hh < 4; ++hh) { bf16_t* d = km + (size_t)kr * 768 + hh * 192 + 128 + 8 * fq; *(u32x4*)d = wa; *(u32x4*)(d + 32) = wb; }
;                     }
.LBB0_307:
	v_lshlrev_b32_e32 v144, 6, v98
	v_lshl_add_u64 v[112:113], v[144:145], 2, v[152:153]
	s_waitcnt lgkmcnt(0)
	global_load_dwordx4 v[96:99], v[112:113], off offset:128
	global_load_dwordx4 v[100:103], v[112:113], off offset:144
	global_load_dwordx4 v[108:111], v[112:113], off
	s_nop 0
	global_load_dwordx4 v[112:115], v[112:113], off offset:16
	s_mov_b64 s[60:61], -1
	s_and_b64 vcc, exec, s[8:9]
	v_ashrrev_i32_e32 v105, 31, v104
	s_waitcnt vmcnt(0)
	v_pk_mul_f32 v[116:117], v[86:87], v[98:99]
	v_pk_mul_f32 v[118:119], v[84:85], v[96:97]
	v_pk_mul_f32 v[120:121], v[82:83], v[102:103]
	v_pk_mul_f32 v[122:123], v[80:81], v[100:101]
	v_pk_mul_f32 v[98:99], v[94:95], v[98:99]
	v_pk_mul_f32 v[96:97], v[92:93], v[96:97]
	v_pk_mul_f32 v[102:103], v[90:91], v[102:103]
	v_pk_mul_f32 v[100:101], v[88:89], v[100:101]
	v_pk_fma_f32 v[94:95], v[94:95], v[110:111], v[116:117] neg_lo:[0,0,1] neg_hi:[0,0,1]
	v_pk_fma_f32 v[92:93], v[92:93], v[108:109], v[118:119] neg_lo:[0,0,1] neg_hi:[0,0,1]
	v_pk_fma_f32 v[90:91], v[90:91], v[114:115], v[120:121] neg_lo:[0,0,1] neg_hi:[0,0,1]
	v_pk_fma_f32 v[88:89], v[88:89], v[112:113], v[122:123] neg_lo:[0,0,1] neg_hi:[0,0,1]
	v_pk_fma_f32 v[86:87], v[86:87], v[110:111], v[98:99]
	v_pk_fma_f32 v[84:85], v[84:85], v[108:109], v[96:97]
	v_pk_fma_f32 v[82:83], v[82:83], v[114:115], v[102:103]
	v_pk_fma_f32 v[80:81], v[80:81], v[112:113], v[100:101]
	s_cbranch_vccnz .LBB0_313
	v_add_u32_e32 v96, 0xffff0020, v166
	v_cndmask_b32_e64 v109, 0, v105, s[14:15]
	v_cndmask_b32_e64 v108, v96, v104, s[14:15]
	s_andn2_b64 vcc, exec, s[52:53]
	v_cvt_pk_bf16_f32 v100, v92, v93
	v_cvt_pk_bf16_f32 v101, v94, v95
	v_cvt_pk_bf16_f32 v102, v88, v89
	v_cvt_pk_bf16_f32 v103, v90, v91
	v_cvt_pk_bf16_f32 v96, v84, v85
	v_cvt_pk_bf16_f32 v97, v86, v87
	v_cvt_pk_bf16_f32 v98, v80, v81
	v_cvt_pk_bf16_f32 v99, v82, v83
	s_cbranch_vccnz .LBB0_310
	v_cndmask_b32_e64 v144, v183, v184, s[14:15]
	v_lshl_add_u64 v[110:111], s[16:17], 0, v[144:145]
	v_lshlrev_b64 v[112:113], 8, v[108:109]
	v_lshl_add_u64 v[110:111], v[110:111], 0, v[112:113]
	v_lshlrev_b32_e32 v144, 2, v146
	v_lshl_add_u64 v[110:111], v[110:111], 0, v[144:145]
	global_store_dwordx4 v[110:111], v[92:95], off nt
	global_store_dwordx4 v[110:111], v[88:91], off offset:16 nt
	global_store_dwordx4 v[110:111], v[84:87], off offset:128 nt
	global_store_dwordx4 v[110:111], v[80:83], off offset:144 nt
	v_mad_i64_i32 v[110:111], s[60:61], v106, s89, v[156:157]
	s_mov_b64 s[60:61], 0
	global_store_dwordx4 v[110:111], v[100:103], off offset:256 nt
	global_store_dwordx4 v[110:111], v[96:99], off offset:320 nt
	global_store_dwordx4 v[110:111], v[100:103], off offset:640 nt
	global_store_dwordx4 v[110:111], v[96:99], off offset:704 nt
	global_store_dwordx4 v[110:111], v[100:103], off offset:1024 nt
	global_store_dwordx4 v[110:111], v[96:99], off offset:1088 nt
	global_store_dwordx4 v[110:111], v[100:103], off offset:1408 nt
	global_store_dwordx4 v[110:111], v[96:99], off offset:1472 nt
.LBB0_310:
	s_andn2_b64 vcc, exec, s[60:61]
	s_cbranch_vccnz .LBB0_312
	v_cndmask_b32_e64 v144, v185, v186, s[14:15]
	v_lshl_add_u64 v[110:111], s[16:17], 0, v[144:145]
	v_lshlrev_b64 v[108:109], 11, v[108:109]
	v_ashrrev_i32_e32 v107, 31, v106
	v_lshl_add_u64 v[108:109], v[110:111], 0, v[108:109]
	v_lshlrev_b64 v[106:107], 10, v[106:107]
	v_lshl_add_u64 v[108:109], s[20:21], 2, v[108:109]
	v_lshlrev_b32_e32 v144, 2, v146
	v_lshl_add_u64 v[106:107], s[26:27], 0, v[106:107]
	v_lshl_add_u64 v[108:109], v[108:109], 0, v[144:145]
	v_lshl_add_u64 v[106:107], s[20:21], 1, v[106:107]
	v_lshlrev_b32_e32 v144, 1, v146
	v_lshl_add_u64 v[106:107], v[106:107], 0, v[144:145]
	global_store_dwordx4 v[108:109], v[92:95], off nt
	global_store_dwordx4 v[108:109], v[88:91], off offset:16 nt
	global_store_dwordx4 v[108:109], v[84:87], off offset:128 nt
	global_store_dwordx4 v[108:109], v[80:83], off offset:144 nt
	global_store_dwordx4 v[106:107], v[100:103], off nt
	global_store_dwordx4 v[106:107], v[96:99], off offset:64 nt

; __device__ __forceinline__ u32x4 pack8(f32x4 a, f32x4 b) { u32x4 w; w.x = pk2(a[0], a[1]); w.y = pk2(a[2], a[3]); w.z = pk2(b[0], b[1]); w.w = pk2(b[2], b[3]); return w; }
;     __device__ __forceinline__ void operator()(const f32x4 (&acc)[2][2][4][2], const Unit& u, int wr, int wc, int fr, int fq) const {
;     ...
;                     if (pn < 2) {
;                         const int g = 4 * pn + wc;
;                         bf16_t* d = qd + (size_t)r * 512 + 64 * g + 8 * fq;
;                         *(u32x4*)d = pack8(a0 * QS_D, a1 * QS_D); *(u32x4*)(d + 32) = pack8(b0 * QS_D, b1 * QS_D);
.LBB0_313:
	s_andn2_b64 vcc, exec, s[60:61]
	s_cbranch_vccnz .LBB0_315
	v_lshlrev_b64 v[96:97], 10, v[104:105]
	v_lshl_add_u64 v[96:97], s[24:25], 0, v[96:97]
	v_lshl_add_u64 v[96:97], s[56:57], 1, v[96:97]
	v_lshlrev_b32_e32 v144, 1, v146
	v_pk_mul_f32 v[94:95], v[94:95], s[40:41] op_sel_hi:[1,0]
	v_pk_mul_f32 v[92:93], v[92:93], s[40:41] op_sel_hi:[1,0]
	v_pk_mul_f32 v[98:99], v[90:91], s[40:41] op_sel_hi:[1,0]
	v_pk_mul_f32 v[90:91], v[88:89], s[40:41] op_sel_hi:[1,0]
	v_lshl_add_u64 v[96:97], v[96:97], 0, v[144:145]
	v_cvt_pk_bf16_f32 v88, v92, v93
	v_cvt_pk_bf16_f32 v89, v94, v95
	v_cvt_pk_bf16_f32 v90, v90, v91
	v_cvt_pk_bf16_f32 v91, v98, v99
	global_store_dwordx4 v[96:97], v[88:91], off nt
	v_pk_mul_f32 v[86:87], v[86:87], s[40:41] op_sel_hi:[1,0]
	v_pk_mul_f32 v[84:85], v[84:85], s[40:41] op_sel_hi:[1,0]
	v_pk_mul_f32 v[88:89], v[82:83], s[40:41] op_sel_hi:[1,0]
	v_pk_mul_f32 v[82:83], v[80:81], s[40:41] op_sel_hi:[1,0]
	v_cvt_pk_bf16_f32 v80, v84, v85
	v_cvt_pk_bf16_f32 v81, v86, v87
	v_cvt_pk_bf16_f32 v82, v82, v83
	v_cvt_pk_bf16_f32 v83, v88, v89
	global_store_dwordx4 v[96:97], v[80:83], off offset:64 nt

;     __device__ __forceinline__ void operator()(const f32x4 (&acc)[2][2][4][2], const Unit& u, int wr, int wc, int fr, int fq) const {
;     ...
;                 } else if (wc < 2) {
;                     float* o = ckvraw + (size_t)r * 128 + 64 * wc + 8 * fq;
; #pragma unroll
;                     for (int bj = 0; bj < 2; ++bj) { *(f32x4*)(o + 32 * bj) = acc[ai][bj][m][0]; *(f32x4*)(o + 32 * bj + 4) = acc[ai][bj][m][1]; }
.LBB0_321:
	s_and_b64 vcc, exec, s[10:11]
	s_cbranch_vccnz .LBB0_331
	s_andn2_b64 vcc, exec, s[58:59]
	s_cbranch_vccnz .LBB0_326
	s_andn2_b64 vcc, exec, s[38:39]
	s_cbranch_vccnz .LBB0_325
	v_ashrrev_i32_e32 v89, 31, v88
	v_lshlrev_b64 v[84:85], 9, v[88:89]
	v_lshl_add_u64 v[84:85], v[148:149], 0, v[84:85]
	global_store_dwordx4 v[84:85], v[76:79], off nt
	global_store_dwordx4 v[84:85], v[72:75], off offset:16 nt
	global_store_dwordx4 v[84:85], v[68:71], off offset:128 nt
	global_store_dwordx4 v[84:85], v[64:67], off offset:144 nt

; __device__ __forceinline__ u32x4 pack8(f32x4 a, f32x4 b) { u32x4 w; w.x = pk2(a[0], a[1]); w.y = pk2(a[2], a[3]); w.z = pk2(b[0], b[1]); w.w = pk2(b[2], b[3]); return w; }
;     __device__ __forceinline__ void operator()(const f32x4 (&acc)[2][2][4][2], const Unit& u, int wr, int wc, int fr, int fq) const {
;     ...
;                 } else if (pn == 6) {
;                     const int c = 64 * wc + 8 * fq; float ss = 0.f;
; #pragma unroll
;                     for (int bj = 0; bj < 2; ++bj) {
;                         const f32x4 y0 = acc[ai][bj][m][0], y1 = acc[ai][bj][m][1];
;                         const f32x4 g0 = *(const f32x4*)(gq + c + 32 * bj), g1 = *(const f32x4*)(gq + c + 32 * bj + 4);
;                         *(u32x4*)(cq + (size_t)r * 256 + c + 32 * bj) = pack8(y0 * g0, y1 * g1);
;                         ss += (y0[0] * y0[0] + y0[1] * y0[1]) + (y0[2] * y0[2] + y0[3] * y0[3]) + (y1[0] * y1[0] + y1[1] * y1[1]) + (y1[2] * y1[2] + y1[3] * y1[3]);
;                     }
;                     ss += __shfl_xor(ss, 16); ss += __shfl_xor(ss, 32);
;                     if (fq == 0) atomicAdd(rsqq + r, ss);
.LBB0_326:
	s_andn2_b64 vcc, exec, s[60:61]
	s_cbranch_vccnz .LBB0_330
	global_load_dwordx4 v[84:87], v[154:155], off
	global_load_dwordx4 v[92:95], v[154:155], off offset:16
	v_ashrrev_i32_e32 v89, 31, v88
	v_lshlrev_b64 v[96:97], 9, v[88:89]
	v_lshl_add_u64 v[96:97], v[150:151], 0, v[96:97]
	v_mul_f32_e32 v81, v77, v77
	v_mul_f32_e32 v83, v79, v79
	s_waitcnt lgkmcnt(0)
	v_mul_f32_e32 v99, v69, v69
	v_mul_f32_e32 v100, v71, v71
	v_mul_f32_e32 v91, v73, v73
	v_mul_f32_e32 v101, v65, v65
	v_and_b32_e32 v104, 64, v180
	v_fmac_f32_e32 v81, v76, v76
	v_fmac_f32_e32 v83, v78, v78
	v_fmac_f32_e32 v99, v68, v68
	v_fmac_f32_e32 v100, v70, v70
	v_mul_f32_e32 v98, v75, v75
	v_mul_f32_e32 v102, v67, v67
	v_xor_b32_e32 v103, 16, v180
	v_fmac_f32_e32 v91, v72, v72
	v_fmac_f32_e32 v101, v64, v64
	v_add_u32_e32 v104, 64, v104
	v_add_f32_e32 v81, v81, v83
	v_add_f32_e32 v83, v99, v100
	v_fmac_f32_e32 v98, v74, v74
	v_fmac_f32_e32 v102, v66, v66
	v_cmp_lt_i32_e32 vcc, v103, v104
	v_add_f32_e32 v81, v81, v91
	v_add_f32_e32 v83, v83, v101
	v_cndmask_b32_e32 v99, v180, v103, vcc
	v_add_f32_e32 v81, v98, v81
	v_add_f32_e32 v83, v102, v83
	v_lshlrev_b32_e32 v91, 2, v99
	v_add_f32_e32 v81, v81, v83
	ds_bpermute_b32 v83, v91, v81
	v_xor_b32_e32 v91, 32, v180
	v_cmp_lt_i32_e32 vcc, v91, v104
	s_waitcnt lgkmcnt(0)
	v_add_f32_e32 v81, v81, v83
	v_cndmask_b32_e32 v91, v180, v91, vcc
	v_lshlrev_b32_e32 v91, 2, v91
	ds_bpermute_b32 v83, v91, v81
	s_waitcnt vmcnt(0)
	v_pk_mul_f32 v[86:87], v[78:79], v[86:87]
	v_pk_mul_f32 v[84:85], v[76:77], v[84:85]
	v_pk_mul_f32 v[94:95], v[74:75], v[94:95]
	v_pk_mul_f32 v[92:93], v[72:73], v[92:93]
	v_cvt_pk_bf16_f32 v84, v84, v85
	v_cvt_pk_bf16_f32 v85, v86, v87
	v_cvt_pk_bf16_f32 v86, v92, v93
	v_cvt_pk_bf16_f32 v87, v94, v95
	global_store_dwordx4 v[96:97], v[84:87], off nt
	global_load_dwordx4 v[84:87], v[154:155], off offset:128
	s_nop 0
	global_load_dwordx4 v[92:95], v[154:155], off offset:144
	s_waitcnt vmcnt(1)
	v_pk_mul_f32 v[86:87], v[70:71], v[86:87]
	v_pk_mul_f32 v[84:85], v[68:69], v[84:85]
	s_waitcnt vmcnt(0)
	v_pk_mul_f32 v[94:95], v[66:67], v[94:95]
	v_pk_mul_f32 v[92:93], v[64:65], v[92:93]
	v_cvt_pk_bf16_f32 v84, v84, v85
	v_cvt_pk_bf16_f32 v85, v86, v87
	v_cvt_pk_bf16_f32 v86, v92, v93
	v_cvt_pk_bf16_f32 v87, v94, v95
	global_store_dwordx4 v[96:97], v[84:87], off offset:64 nt
	s_and_saveexec_b64 s[60:61], s[0:1]
	s_cbranch_execz .LBB0_329
	v_lshl_add_u64 v[84:85], v[88:89], 2, s[30:31]
	s_waitcnt lgkmcnt(0)
	v_add_f32_e32 v81, v81, v83
	global_atomic_add_f32 v[84:85], v81, off

;     __device__ __forceinline__ float* out() const { return (float*)(GAS float*)ld(25); }
; __device__ __forceinline__ unsigned pk2(float lo, float hi) { f32x2_t v = {lo, hi}; bf16x2_t b = __builtin_convertvector(v, bf16x2_t); return __builtin_bit_cast(unsigned, b); }
; __device__ __forceinline__ int permk(int k) { return (k & ~12) | ((k & 4) << 1) | ((k & 8) >> 1); }
;     __device__ __forceinline__ void operator()(const f32x4 (&acc)[2][2][4][2], const Unit& u, int wr, int wc, int fr, int fq) const {
;     ...
;                 } else if (pn < 6) {
;                     const int g = 4 * (pn - 4) + wc;
;                     float* o = out_row(out, r, O_DVP, O_DVS, 512) + 64 * g + 8 * fq;
;                     const bool odd = (fr & 1) != 0;
;                     bf16_t* vb = vtd + (size_t)(kr - kl) * 512 + permk(kl & ~1);
; #pragma unroll
;                     for (int bj = 0; bj < 2; ++bj) {
;                         *(f32x4*)(o + 32 * bj) = acc[ai][bj][m][0]; *(f32x4*)(o + 32 * bj + 4) = acc[ai][bj][m][1];
;                         const f32x4 mine = odd ? acc[ai][bj][m][1] : acc[ai][bj][m][0], send = odd ? acc[ai][bj][m][0] : acc[ai][bj][m][1];
; #pragma unroll
;                         for (int e = 0; e < 4; ++e) {
;                             const float recv = __shfl_xor(send[e], 1);
;                             const int col = 64 * g + 32 * bj + 8 * fq + (odd ? 4 : 0) + e;
;                             if (!novt) *(unsigned*)(vb + (size_t)col * len) = odd ? pk2(recv, mine[e]) : pk2(mine[e], recv);
;                         }
;                     }
.LBB0_331:
	s_andn2_b64 vcc, exec, s[60:61]
	s_cbranch_vccnz .LBB0_333
	v_add_u32_e32 v81, 0xffff0030, v166
	s_waitcnt lgkmcnt(0)
	v_ashrrev_i32_e32 v83, 31, v88
	v_cndmask_b32_e64 v85, 0, v83, s[14:15]
	v_cndmask_b32_e64 v84, v81, v88, s[14:15]
	v_cndmask_b32_e64 v144, v181, v182, s[14:15]
	v_lshl_add_u64 v[86:87], s[16:17], 0, v[144:145]
	v_lshlrev_b64 v[84:85], 11, v[84:85]
	v_lshl_add_u64 v[84:85], v[86:87], 0, v[84:85]
	v_lshlrev_b32_e32 v83, 1, v82
	v_lshrrev_b32_e32 v89, 1, v82
	v_lshl_add_u64 v[84:85], s[54:55], 2, v[84:85]
	v_lshlrev_b32_e32 v144, 2, v146
	v_and_b32_e32 v81, -14, v82
	v_and_b32_e32 v83, 8, v83
	v_and_b32_e32 v89, 4, v89
	v_lshl_add_u64 v[84:85], v[84:85], 0, v[144:145]
	v_or3_b32 v144, v83, v81, v89
	v_and_b32_e32 v83, 64, v180
	v_xor_b32_e32 v81, 1, v180
	v_add_u32_e32 v83, 64, v83
	v_cmp_lt_i32_e32 vcc, v81, v83
	v_cndmask_b32_e64 v92, v76, v72, s[4:5]
	v_sub_u32_e32 v86, v90, v82
	v_cndmask_b32_e32 v81, v180, v81, vcc
	v_lshlrev_b32_e32 v81, 2, v81
	ds_bpermute_b32 v92, v81, v92
	v_cndmask_b32_e64 v96, v77, v73, s[4:5]
	v_ashrrev_i32_e32 v87, 31, v86
	ds_bpermute_b32 v96, v81, v96
	v_lshlrev_b64 v[86:87], 10, v[86:87]
	v_cndmask_b32_e64 v93, v72, v76, s[4:5]
	v_lshl_add_u64 v[86:87], s[28:29], 0, v[86:87]
	v_cndmask_b32_e64 v95, v78, v74, s[4:5]
	s_waitcnt lgkmcnt(0)
	v_cndmask_b32_e64 v97, v93, v92, s[4:5]
	v_cndmask_b32_e64 v92, v92, v93, s[4:5]
	v_lshl_add_u64 v[86:87], v[144:145], 1, v[86:87]
	v_cvt_pk_bf16_f32 v97, v92, v97
	v_mad_i64_i32 v[92:93], s[60:61], v80, v187, 0
	ds_bpermute_b32 v95, v81, v95
	v_cndmask_b32_e64 v91, v73, v77, s[4:5]
	v_lshl_add_u64 v[92:93], v[92:93], 1, v[86:87]
	global_store_dwordx4 v[84:85], v[76:79], off nt
	global_store_dwordx4 v[84:85], v[72:75], off offset:16 nt
	global_store_dword v[92:93], v97, off
	v_or_b32_e32 v92, 1, v187
	v_cndmask_b32_e64 v93, v91, v96, s[4:5]
	v_cndmask_b32_e64 v91, v96, v91, s[4:5]
	v_cndmask_b32_e64 v94, v79, v75, s[4:5]
	v_cvt_pk_bf16_f32 v91, v91, v93
	v_mad_i64_i32 v[92:93], s[60:61], v80, v92, 0
	v_cndmask_b32_e64 v89, v74, v78, s[4:5]
	v_lshl_add_u64 v[92:93], v[92:93], 1, v[86:87]
	ds_bpermute_b32 v94, v81, v94
	global_store_dword v[92:93], v91, off
	v_or_b32_e32 v91, 2, v187
	s_waitcnt lgkmcnt(0)
	v_cndmask_b32_e64 v92, v89, v95, s[4:5]
	v_cndmask_b32_e64 v89, v95, v89, s[4:5]
	v_cvt_pk_bf16_f32 v89, v89, v92
	v_mad_i64_i32 v[92:93], s[60:61], v80, v91, 0
	v_lshl_add_u64 v[92:93], v[92:93], 1, v[86:87]
	v_cndmask_b32_e64 v83, v75, v79, s[4:5]
	global_store_dword v[92:93], v89, off
	v_or_b32_e32 v89, 3, v187
	v_cndmask_b32_e64 v91, v83, v94, s[4:5]
	v_cndmask_b32_e64 v83, v94, v83, s[4:5]
	v_mad_i64_i32 v[92:93], s[60:61], v80, v89, 0
	v_cvt_pk_bf16_f32 v83, v83, v91
	v_lshl_add_u64 v[92:93], v[92:93], 1, v[86:87]
	global_store_dword v[92:93], v83, off
	global_store_dwordx4 v[84:85], v[68:71], off offset:128 nt
	global_store_dwordx4 v[84:85], v[64:67], off offset:144 nt
	v_cndmask_b32_e64 v85, v68, v64, s[4:5]
	ds_bpermute_b32 v85, v81, v85
	v_cndmask_b32_e64 v94, v69, v65, s[4:5]
	ds_bpermute_b32 v94, v81, v94
	v_cndmask_b32_e64 v84, v64, v68, s[4:5]
	v_cndmask_b32_e64 v93, v70, v66, s[4:5]
	v_or_b32_e32 v95, 32, v187
	s_waitcnt lgkmcnt(0)
	v_cndmask_b32_e64 v96, v84, v85, s[4:5]
	v_cndmask_b32_e64 v84, v85, v84, s[4:5]
	v_cvt_pk_bf16_f32 v96, v84, v96
	v_mad_i64_i32 v[84:85], s[60:61], v80, v95, 0
	ds_bpermute_b32 v93, v81, v93
	v_cndmask_b32_e64 v91, v65, v69, s[4:5]
	v_lshl_add_u64 v[84:85], v[84:85], 1, v[86:87]
	v_cndmask_b32_e64 v92, v71, v67, s[4:5]
	global_store_dword v[84:85], v96, off
	v_or_b32_e32 v84, 33, v187
	v_cndmask_b32_e64 v85, v91, v94, s[4:5]
	v_cndmask_b32_e64 v91, v94, v91, s[4:5]
	v_cvt_pk_bf16_f32 v91, v91, v85
	v_mad_i64_i32 v[84:85], s[60:61], v80, v84, 0
	ds_bpermute_b32 v81, v81, v92
	v_cndmask_b32_e64 v89, v66, v70, s[4:5]
	v_lshl_add_u64 v[84:85], v[84:85], 1, v[86:87]
	global_store_dword v[84:85], v91, off
	v_or_b32_e32 v84, 34, v187
	s_waitcnt lgkmcnt(0)
	v_cndmask_b32_e64 v85, v89, v93, s[4:5]
	v_cndmask_b32_e64 v89, v93, v89, s[4:5]
	v_cvt_pk_bf16_f32 v89, v89, v85
	v_mad_i64_i32 v[84:85], s[60:61], v80, v84, 0
	v_cndmask_b32_e64 v83, v67, v71, s[4:5]
	v_lshl_add_u64 v[84:85], v[84:85], 1, v[86:87]
	global_store_dword v[84:85], v89, off
	v_or_b32_e32 v84, 35, v187
	v_cndmask_b32_e64 v85, v83, v81, s[4:5]
	v_cndmask_b32_e64 v81, v81, v83, s[4:5]
	v_cvt_pk_bf16_f32 v83, v81, v85
	v_mad_i64_i32 v[80:81], s[60:61], v80, v84, 0
	v_lshl_add_u64 v[80:81], v[80:81], 1, v[86:87]
	global_store_dword v[80:81], v83, off

;     __device__ __forceinline__ float* out() const { return (float*)(GAS float*)ld(25); }
; __device__ __forceinline__ u32x4 pack8(f32x4 a, f32x4 b) { u32x4 w; w.x = pk2(a[0], a[1]); w.y = pk2(a[2], a[3]); w.z = pk2(b[0], b[1]); w.w = pk2(b[2], b[3]); return w; }
;     __device__ __forceinline__ void operator()(const f32x4 (&acc)[2][2][4][2], const Unit& u, int wr, int wc, int fr, int fq) const {
;     ...
;                 if (do_rope) {
;                     const float* cs = rope + pos * 64 + 8 * fq;
;                     const f32x4 c0 = *(const f32x4*)cs, c1 = *(const f32x4*)(cs + 4), s0 = *(const f32x4*)(cs + 32), s1 = *(const f32x4*)(cs + 36);
;                     const f32x4 x10 = acc[ai][0][m][0], x11 = acc[ai][0][m][1], x20 = acc[ai][1][m][0], x21 = acc[ai][1][m][1];
;                     f32x4 a0 = x10 * c0 - x20 * s0, a1 = x11 * c1 - x21 * s1, b0 = x20 * c0 + x10 * s0, b1 = x21 * c1 + x11 * s1;
;                     if (pn < 2) {
;                         const int g = 4 * pn + wc;
;                         bf16_t* d = qd + (size_t)r * 512 + 64 * g + 8 * fq;
;                         *(u32x4*)d = pack8(a0 * QS_D, a1 * QS_D); *(u32x4*)(d + 32) = pack8(b0 * QS_D, b1 * QS_D);
;                     } else if (pn < 4) {
;                         const int g = 4 * (pn - 2) + wc;
;                         float* o = out_row(out, r, O_DKP, O_DKS, 512) + 64 * g + 8 * fq;
;                         *(f32x4*)o = a0; *(f32x4*)(o + 4) = a1; *(f32x4*)(o + 32) = b0; *(f32x4*)(o + 36) = b1;
;                         bf16_t* d = kd + (size_t)kr * 512 + 64 * g + 8 * fq;
;                         *(u32x4*)d = pack8(a0, a1); *(u32x4*)(d + 32) = pack8(b0, b1);
;                     } else {
;                         float* o = out_row(out, r, O_KRP, O_KRS, 64) + 8 * fq;
;                         *(f32x4*)o = a0; *(f32x4*)(o + 4) = a1; *(f32x4*)(o + 32) = b0; *(f32x4*)(o + 36) = b1;
;                         const u32x4 wa = pack8(a0, a1), wb = pack8(b0, b1);
; #pragma unroll
;                         for (int hh = 0; hh < 4; ++hh) { bf16_t* d = km + (size_t)kr * 768 + hh * 192 + 128 + 8 * fq; *(u32x4*)d = wa; *(u32x4*)(d + 32) = wb; }
;                     }
.LBB0_334:
	v_lshlrev_b32_e32 v144, 6, v82
	v_lshl_add_u64 v[96:97], v[144:145], 2, v[152:153]
	s_waitcnt lgkmcnt(0)
	global_load_dwordx4 v[80:83], v[96:97], off offset:128
	global_load_dwordx4 v[84:87], v[96:97], off offset:144
	global_load_dwordx4 v[92:95], v[96:97], off
	s_nop 0
	global_load_dwordx4 v[96:99], v[96:97], off offset:16
	s_mov_b64 s[60:61], -1
	s_and_b64 vcc, exec, s[8:9]
	v_ashrrev_i32_e32 v89, 31, v88
	s_waitcnt vmcnt(0)
	v_pk_mul_f32 v[100:101], v[70:71], v[82:83]
	v_pk_mul_f32 v[102:103], v[68:69], v[80:81]
	v_pk_mul_f32 v[104:105], v[66:67], v[86:87]
	v_pk_mul_f32 v[106:107], v[64:65], v[84:85]
	v_pk_mul_f32 v[82:83], v[78:79], v[82:83]
	v_pk_mul_f32 v[80:81], v[76:77], v[80:81]
	v_pk_mul_f32 v[86:87], v[74:75], v[86:87]
	v_pk_mul_f32 v[84:85], v[72:73], v[84:85]
	v_pk_fma_f32 v[78:79], v[78:79], v[94:95], v[100:101] neg_lo:[0,0,1] neg_hi:[0,0,1]
	v_pk_fma_f32 v[76:77], v[76:77], v[92:93], v[102:103] neg_lo:[0,0,1] neg_hi:[0,0,1]
	v_pk_fma_f32 v[74:75], v[74:75], v[98:99], v[104:105] neg_lo:[0,0,1] neg_hi:[0,0,1]
	v_pk_fma_f32 v[72:73], v[72:73], v[96:97], v[106:107] neg_lo:[0,0,1] neg_hi:[0,0,1]
	v_pk_fma_f32 v[70:71], v[70:71], v[94:95], v[82:83]
	v_pk_fma_f32 v[68:69], v[68:69], v[92:93], v[80:81]
	v_pk_fma_f32 v[66:67], v[66:67], v[98:99], v[86:87]
	v_pk_fma_f32 v[64:65], v[64:65], v[96:97], v[84:85]
	s_cbranch_vccnz .LBB0_340
	v_add_u32_e32 v80, 0xffff0030, v166
	v_cndmask_b32_e64 v93, 0, v89, s[14:15]
	v_cndmask_b32_e64 v92, v80, v88, s[14:15]
	s_andn2_b64 vcc, exec, s[52:53]
	v_cvt_pk_bf16_f32 v84, v76, v77
	v_cvt_pk_bf16_f32 v85, v78, v79
	v_cvt_pk_bf16_f32 v86, v72, v73
	v_cvt_pk_bf16_f32 v87, v74, v75
	v_cvt_pk_bf16_f32 v80, v68, v69
	v_cvt_pk_bf16_f32 v81, v70, v71
	v_cvt_pk_bf16_f32 v82, v64, v65
	v_cvt_pk_bf16_f32 v83, v66, v67
	s_cbranch_vccnz .LBB0_337
	v_cndmask_b32_e64 v144, v183, v184, s[14:15]
	v_lshl_add_u64 v[94:95], s[16:17], 0, v[144:145]
	v_lshlrev_b64 v[96:97], 8, v[92:93]
	v_lshl_add_u64 v[94:95], v[94:95], 0, v[96:97]
	v_lshlrev_b32_e32 v144, 2, v146
	v_lshl_add_u64 v[94:95], v[94:95], 0, v[144:145]
	global_store_dwordx4 v[94:95], v[76:79], off nt
	global_store_dwordx4 v[94:95], v[72:75], off offset:16 nt
	global_store_dwordx4 v[94:95], v[68:71], off offset:128 nt
	global_store_dwordx4 v[94:95], v[64:67], off offset:144 nt
	v_mad_i64_i32 v[94:95], s[60:61], v90, s89, v[156:157]
	s_mov_b64 s[60:61], 0
	global_store_dwordx4 v[94:95], v[84:87], off offset:256 nt
	global_store_dwordx4 v[94:95], v[80:83], off offset:320 nt
	global_store_dwordx4 v[94:95], v[84:87], off offset:640 nt
	global_store_dwordx4 v[94:95], v[80:83], off offset:704 nt
	global_store_dwordx4 v[94:95], v[84:87], off offset:1024 nt
	global_store_dwordx4 v[94:95], v[80:83], off offset:1088 nt
	global_store_dwordx4 v[94:95], v[84:87], off offset:1408 nt
	global_store_dwordx4 v[94:95], v[80:83], off offset:1472 nt
.LBB0_337:
	s_andn2_b64 vcc, exec, s[60:61]
	s_cbranch_vccnz .LBB0_339
	v_cndmask_b32_e64 v144, v185, v186, s[14:15]
	v_lshl_add_u64 v[94:95], s[16:17], 0, v[144:145]
	v_lshlrev_b64 v[92:93], 11, v[92:93]
	v_ashrrev_i32_e32 v91, 31, v90
	v_lshl_add_u64 v[92:93], v[94:95], 0, v[92:93]
	v_lshlrev_b64 v[90:91], 10, v[90:91]
	v_lshl_add_u64 v[92:93], s[20:21], 2, v[92:93]
	v_lshlrev_b32_e32 v144, 2, v146
	v_lshl_add_u64 v[90:91], s[26:27], 0, v[90:91]
	v_lshl_add_u64 v[92:93], v[92:93], 0, v[144:145]
	v_lshl_add_u64 v[90:91], s[20:21], 1, v[90:91]
	v_lshlrev_b32_e32 v144, 1, v146
	v_lshl_add_u64 v[90:91], v[90:91], 0, v[144:145]
	global_store_dwordx4 v[92:93], v[76:79], off nt
	global_store_dwordx4 v[92:93], v[72:75], off offset:16 nt
	global_store_dwordx4 v[92:93], v[68:71], off offset:128 nt
	global_store_dwordx4 v[92:93], v[64:67], off offset:144 nt
	global_store_dwordx4 v[90:91], v[84:87], off nt
	global_store_dwordx4 v[90:91], v[80:83], off offset:64 nt

; __device__ __forceinline__ u32x4 pack8(f32x4 a, f32x4 b) { u32x4 w; w.x = pk2(a[0], a[1]); w.y = pk2(a[2], a[3]); w.z = pk2(b[0], b[1]); w.w = pk2(b[2], b[3]); return w; }
;     __device__ __forceinline__ void operator()(const f32x4 (&acc)[2][2][4][2], const Unit& u, int wr, int wc, int fr, int fq) const {
;     ...
;                     if (pn < 2) {
;                         const int g = 4 * pn + wc;
;                         bf16_t* d = qd + (size_t)r * 512 + 64 * g + 8 * fq;
;                         *(u32x4*)d = pack8(a0 * QS_D, a1 * QS_D); *(u32x4*)(d + 32) = pack8(b0 * QS_D, b1 * QS_D);
.LBB0_340:
	s_andn2_b64 vcc, exec, s[60:61]
	s_cbranch_vccnz .LBB0_342
	v_lshlrev_b64 v[80:81], 10, v[88:89]
	v_lshl_add_u64 v[80:81], s[24:25], 0, v[80:81]
	v_lshl_add_u64 v[80:81], s[56:57], 1, v[80:81]
	v_lshlrev_b32_e32 v144, 1, v146
	v_pk_mul_f32 v[78:79], v[78:79], s[40:41] op_sel_hi:[1,0]
	v_pk_mul_f32 v[76:77], v[76:77], s[40:41] op_sel_hi:[1,0]
	v_pk_mul_f32 v[82:83], v[74:75], s[40:41] op_sel_hi:[1,0]
	v_pk_mul_f32 v[74:75], v[72:73], s[40:41] op_sel_hi:[1,0]
	v_lshl_add_u64 v[80:81], v[80:81], 0, v[144:145]
	v_cvt_pk_bf16_f32 v72, v76, v77
	v_cvt_pk_bf16_f32 v73, v78, v79
	v_cvt_pk_bf16_f32 v74, v74, v75
	v_cvt_pk_bf16_f32 v75, v82, v83
	global_store_dwordx4 v[80:81], v[72:75], off nt
	v_pk_mul_f32 v[70:71], v[70:71], s[40:41] op_sel_hi:[1,0]
	v_pk_mul_f32 v[68:69], v[68:69], s[40:41] op_sel_hi:[1,0]
	v_pk_mul_f32 v[72:73], v[66:67], s[40:41] op_sel_hi:[1,0]
	v_pk_mul_f32 v[66:67], v[64:65], s[40:41] op_sel_hi:[1,0]
	v_cvt_pk_bf16_f32 v64, v68, v69
	v_cvt_pk_bf16_f32 v65, v70, v71
	v_cvt_pk_bf16_f32 v66, v66, v67
	v_cvt_pk_bf16_f32 v67, v72, v73
	global_store_dwordx4 v[80:81], v[64:67], off offset:64 nt

;     __device__ __forceinline__ void operator()(const f32x4 (&acc)[2][2][4][2], const Unit& u, int wr, int wc, int fr, int fq) const {
;     ...
;                 } else if (wc < 2) {
;                     float* o = ckvraw + (size_t)r * 128 + 64 * wc + 8 * fq;
; #pragma unroll
;                     for (int bj = 0; bj < 2; ++bj) { *(f32x4*)(o + 32 * bj) = acc[ai][bj][m][0]; *(f32x4*)(o + 32 * bj + 4) = acc[ai][bj][m][1]; }
.LBB0_348:
	s_and_b64 vcc, exec, s[10:11]
	s_cbranch_vccnz .LBB0_358
	s_andn2_b64 vcc, exec, s[58:59]
	s_cbranch_vccnz .LBB0_353
	s_andn2_b64 vcc, exec, s[38:39]
	s_cbranch_vccnz .LBB0_352
	v_ashrrev_i32_e32 v73, 31, v72
	v_lshlrev_b64 v[68:69], 9, v[72:73]
	v_lshl_add_u64 v[68:69], v[148:149], 0, v[68:69]
	global_store_dwordx4 v[68:69], v[60:63], off nt
	global_store_dwordx4 v[68:69], v[56:59], off offset:16 nt
	global_store_dwordx4 v[68:69], v[52:55], off offset:128 nt
	global_store_dwordx4 v[68:69], v[48:51], off offset:144 nt

; __device__ __forceinline__ u32x4 pack8(f32x4 a, f32x4 b) { u32x4 w; w.x = pk2(a[0], a[1]); w.y = pk2(a[2], a[3]); w.z = pk2(b[0], b[1]); w.w = pk2(b[2], b[3]); return w; }
;     __device__ __forceinline__ void operator()(const f32x4 (&acc)[2][2][4][2], const Unit& u, int wr, int wc, int fr, int fq) const {
;     ...
;                 } else if (pn == 6) {
;                     const int c = 64 * wc + 8 * fq; float ss = 0.f;
; #pragma unroll
;                     for (int bj = 0; bj < 2; ++bj) {
;                         const f32x4 y0 = acc[ai][bj][m][0], y1 = acc[ai][bj][m][1];
;                         const f32x4 g0 = *(const f32x4*)(gq + c + 32 * bj), g1 = *(const f32x4*)(gq + c + 32 * bj + 4);
;                         *(u32x4*)(cq + (size_t)r * 256 + c + 32 * bj) = pack8(y0 * g0, y1 * g1);
;                         ss += (y0[0] * y0[0] + y0[1] * y0[1]) + (y0[2] * y0[2] + y0[3] * y0[3]) + (y1[0] * y1[0] + y1[1] * y1[1]) + (y1[2] * y1[2] + y1[3] * y1[3]);
;                     }
;                     ss += __shfl_xor(ss, 16); ss += __shfl_xor(ss, 32);
;                     if (fq == 0) atomicAdd(rsqq + r, ss);
.LBB0_353:
	s_andn2_b64 vcc, exec, s[60:61]
	s_cbranch_vccnz .LBB0_357
	global_load_dwordx4 v[68:71], v[154:155], off
	global_load_dwordx4 v[76:79], v[154:155], off offset:16
	v_ashrrev_i32_e32 v73, 31, v72
	v_lshlrev_b64 v[80:81], 9, v[72:73]
	v_lshl_add_u64 v[80:81], v[150:151], 0, v[80:81]
	v_mul_f32_e32 v65, v61, v61
	v_mul_f32_e32 v67, v63, v63
	s_waitcnt lgkmcnt(0)
	v_mul_f32_e32 v83, v53, v53
	v_mul_f32_e32 v84, v55, v55
	v_mul_f32_e32 v75, v57, v57
	v_mul_f32_e32 v85, v49, v49
	v_and_b32_e32 v88, 64, v180
	v_fmac_f32_e32 v65, v60, v60
	v_fmac_f32_e32 v67, v62, v62
	v_fmac_f32_e32 v83, v52, v52
	v_fmac_f32_e32 v84, v54, v54
	v_mul_f32_e32 v82, v59, v59
	v_mul_f32_e32 v86, v51, v51
	v_xor_b32_e32 v87, 16, v180
	v_fmac_f32_e32 v75, v56, v56
	v_fmac_f32_e32 v85, v48, v48
	v_add_u32_e32 v88, 64, v88
	v_add_f32_e32 v65, v65, v67
	v_add_f32_e32 v67, v83, v84
	v_fmac_f32_e32 v82, v58, v58
	v_fmac_f32_e32 v86, v50, v50
	v_cmp_lt_i32_e32 vcc, v87, v88
	v_add_f32_e32 v65, v65, v75
	v_add_f32_e32 v67, v67, v85
	v_cndmask_b32_e32 v83, v180, v87, vcc
	v_add_f32_e32 v65, v82, v65
	v_add_f32_e32 v67, v86, v67
	v_lshlrev_b32_e32 v75, 2, v83
	v_add_f32_e32 v65, v65, v67
	ds_bpermute_b32 v67, v75, v65
	v_xor_b32_e32 v75, 32, v180
	v_cmp_lt_i32_e32 vcc, v75, v88
	s_waitcnt lgkmcnt(0)
	v_add_f32_e32 v65, v65, v67
	v_cndmask_b32_e32 v75, v180, v75, vcc
	v_lshlrev_b32_e32 v75, 2, v75
	ds_bpermute_b32 v67, v75, v65
	s_waitcnt vmcnt(0)
	v_pk_mul_f32 v[70:71], v[62:63], v[70:71]
	v_pk_mul_f32 v[68:69], v[60:61], v[68:69]
	v_pk_mul_f32 v[78:79], v[58:59], v[78:79]
	v_pk_mul_f32 v[76:77], v[56:57], v[76:77]
	v_cvt_pk_bf16_f32 v68, v68, v69
	v_cvt_pk_bf16_f32 v69, v70, v71
	v_cvt_pk_bf16_f32 v70, v76, v77
	v_cvt_pk_bf16_f32 v71, v78, v79
	global_store_dwordx4 v[80:81], v[68:71], off nt
	global_load_dwordx4 v[68:71], v[154:155], off offset:128
	s_nop 0
	global_load_dwordx4 v[76:79], v[154:155], off offset:144
	s_waitcnt vmcnt(1)
	v_pk_mul_f32 v[70:71], v[54:55], v[70:71]
	v_pk_mul_f32 v[68:69], v[52:53], v[68:69]
	s_waitcnt vmcnt(0)
	v_pk_mul_f32 v[78:79], v[50:51], v[78:79]
	v_pk_mul_f32 v[76:77], v[48:49], v[76:77]
	v_cvt_pk_bf16_f32 v68, v68, v69
	v_cvt_pk_bf16_f32 v69, v70, v71
	v_cvt_pk_bf16_f32 v70, v76, v77
	v_cvt_pk_bf16_f32 v71, v78, v79
	global_store_dwordx4 v[80:81], v[68:71], off offset:64 nt
	s_and_saveexec_b64 s[60:61], s[0:1]
	s_cbranch_execz .LBB0_356
	v_lshl_add_u64 v[68:69], v[72:73], 2, s[30:31]
	s_waitcnt lgkmcnt(0)
	v_add_f32_e32 v65, v65, v67
	global_atomic_add_f32 v[68:69], v65, off

;     __device__ __forceinline__ float* out() const { return (float*)(GAS float*)ld(25); }
; __device__ __forceinline__ unsigned pk2(float lo, float hi) { f32x2_t v = {lo, hi}; bf16x2_t b = __builtin_convertvector(v, bf16x2_t); return __builtin_bit_cast(unsigned, b); }
; __device__ __forceinline__ int permk(int k) { return (k & ~12) | ((k & 4) << 1) | ((k & 8) >> 1); }
;     __device__ __forceinline__ void operator()(const f32x4 (&acc)[2][2][4][2], const Unit& u, int wr, int wc, int fr, int fq) const {
;     ...
;                 } else if (pn < 6) {
;                     const int g = 4 * (pn - 4) + wc;
;                     float* o = out_row(out, r, O_DVP, O_DVS, 512) + 64 * g + 8 * fq;
;                     const bool odd = (fr & 1) != 0;
;                     bf16_t* vb = vtd + (size_t)(kr - kl) * 512 + permk(kl & ~1);
; #pragma unroll
;                     for (int bj = 0; bj < 2; ++bj) {
;                         *(f32x4*)(o + 32 * bj) = acc[ai][bj][m][0]; *(f32x4*)(o + 32 * bj + 4) = acc[ai][bj][m][1];
;                         const f32x4 mine = odd ? acc[ai][bj][m][1] : acc[ai][bj][m][0], send = odd ? acc[ai][bj][m][0] : acc[ai][bj][m][1];
; #pragma unroll
;                         for (int e = 0; e < 4; ++e) {
;                             const float recv = __shfl_xor(send[e], 1);
;                             const int col = 64 * g + 32 * bj + 8 * fq + (odd ? 4 : 0) + e;
;                             if (!novt) *(unsigned*)(vb + (size_t)col * len) = odd ? pk2(recv, mine[e]) : pk2(mine[e], recv);
;                         }
;                     }
.LBB0_358:
	s_andn2_b64 vcc, exec, s[60:61]
	s_cbranch_vccnz .LBB0_360
	v_add_u32_e32 v65, 0xffff0000, v72
	s_waitcnt lgkmcnt(0)
	v_ashrrev_i32_e32 v67, 31, v72
	v_cndmask_b32_e64 v69, 0, v67, s[14:15]
	v_cndmask_b32_e64 v68, v65, v72, s[14:15]
	v_cndmask_b32_e64 v144, v181, v182, s[14:15]
	v_lshl_add_u64 v[70:71], s[16:17], 0, v[144:145]
	v_lshlrev_b64 v[68:69], 11, v[68:69]
	v_lshlrev_b32_e32 v67, 1, v66
	v_lshrrev_b32_e32 v73, 1, v66
	v_lshl_add_u64 v[68:69], v[70:71], 0, v[68:69]
	v_and_b32_e32 v65, 0xfc2, v66
	v_and_b32_e32 v67, 8, v67
	v_and_b32_e32 v73, 4, v73
	v_lshl_add_u64 v[68:69], s[54:55], 2, v[68:69]
	v_lshlrev_b32_e32 v144, 2, v146
	v_or3_b32 v65, v67, v65, v73
	v_and_b32_e32 v67, 64, v180
	v_lshl_add_u64 v[68:69], v[68:69], 0, v[144:145]
	v_lshlrev_b32_e32 v144, 1, v65
	v_xor_b32_e32 v65, 1, v180
	v_add_u32_e32 v67, 64, v67
	v_cmp_lt_i32_e32 vcc, v65, v67
	v_cndmask_b32_e64 v76, v60, v56, s[4:5]
	v_sub_u32_e32 v70, v74, v66
	v_cndmask_b32_e32 v65, v180, v65, vcc
	v_lshlrev_b32_e32 v65, 2, v65
	ds_bpermute_b32 v76, v65, v76
	v_cndmask_b32_e64 v80, v61, v57, s[4:5]
	v_ashrrev_i32_e32 v71, 31, v70
	ds_bpermute_b32 v80, v65, v80
	v_lshlrev_b64 v[70:71], 10, v[70:71]
	v_cndmask_b32_e64 v77, v56, v60, s[4:5]
	v_lshl_add_u64 v[70:71], s[28:29], 0, v[70:71]
	v_cndmask_b32_e64 v79, v62, v58, s[4:5]
	s_waitcnt lgkmcnt(0)
	v_cndmask_b32_e64 v81, v77, v76, s[4:5]
	v_cndmask_b32_e64 v76, v76, v77, s[4:5]
	v_lshl_add_u64 v[70:71], v[70:71], 0, v[144:145]
	v_cvt_pk_bf16_f32 v81, v76, v81
	v_mad_i64_i32 v[76:77], s[60:61], v64, v187, 0
	ds_bpermute_b32 v79, v65, v79
	v_cndmask_b32_e64 v75, v57, v61, s[4:5]
	v_lshl_add_u64 v[76:77], v[76:77], 1, v[70:71]
	global_store_dwordx4 v[68:69], v[60:63], off nt
	global_store_dwordx4 v[68:69], v[56:59], off offset:16 nt
	global_store_dword v[76:77], v81, off
	v_or_b32_e32 v76, 1, v187
	v_cndmask_b32_e64 v77, v75, v80, s[4:5]
	v_cndmask_b32_e64 v75, v80, v75, s[4:5]
	v_cndmask_b32_e64 v78, v63, v59, s[4:5]
	v_cvt_pk_bf16_f32 v75, v75, v77
	v_mad_i64_i32 v[76:77], s[60:61], v64, v76, 0
	v_cndmask_b32_e64 v73, v58, v62, s[4:5]
	v_lshl_add_u64 v[76:77], v[76:77], 1, v[70:71]
	ds_bpermute_b32 v78, v65, v78
	global_store_dword v[76:77], v75, off
	v_or_b32_e32 v75, 2, v187
	s_waitcnt lgkmcnt(0)
	v_cndmask_b32_e64 v76, v73, v79, s[4:5]
	v_cndmask_b32_e64 v73, v79, v73, s[4:5]
	v_cvt_pk_bf16_f32 v73, v73, v76
	v_mad_i64_i32 v[76:77], s[60:61], v64, v75, 0
	v_lshl_add_u64 v[76:77], v[76:77], 1, v[70:71]
	v_cndmask_b32_e64 v67, v59, v63, s[4:5]
	global_store_dword v[76:77], v73, off
	v_or_b32_e32 v73, 3, v187
	v_cndmask_b32_e64 v75, v67, v78, s[4:5]
	v_cndmask_b32_e64 v67, v78, v67, s[4:5]
	v_mad_i64_i32 v[76:77], s[60:61], v64, v73, 0
	v_cvt_pk_bf16_f32 v67, v67, v75
	v_lshl_add_u64 v[76:77], v[76:77], 1, v[70:71]
	global_store_dword v[76:77], v67, off
	global_store_dwordx4 v[68:69], v[52:55], off offset:128 nt
	global_store_dwordx4 v[68:69], v[48:51], off offset:144 nt
	v_cndmask_b32_e64 v69, v52, v48, s[4:5]
	ds_bpermute_b32 v69, v65, v69
	v_cndmask_b32_e64 v78, v53, v49, s[4:5]
	ds_bpermute_b32 v78, v65, v78
	v_cndmask_b32_e64 v68, v48, v52, s[4:5]
	v_cndmask_b32_e64 v77, v54, v50, s[4:5]
	v_or_b32_e32 v79, 32, v187
	s_waitcnt lgkmcnt(0)
	v_cndmask_b32_e64 v80, v68, v69, s[4:5]
	v_cndmask_b32_e64 v68, v69, v68, s[4:5]
	v_cvt_pk_bf16_f32 v80, v68, v80
	v_mad_i64_i32 v[68:69], s[60:61], v64, v79, 0
	ds_bpermute_b32 v77, v65, v77
	v_cndmask_b32_e64 v75, v49, v53, s[4:5]
	v_lshl_add_u64 v[68:69], v[68:69], 1, v[70:71]
	v_cndmask_b32_e64 v76, v55, v51, s[4:5]
	global_store_dword v[68:69], v80, off
	v_or_b32_e32 v68, 33, v187
	v_cndmask_b32_e64 v69, v75, v78, s[4:5]
	v_cndmask_b32_e64 v75, v78, v75, s[4:5]
	v_cvt_pk_bf16_f32 v75, v75, v69
	v_mad_i64_i32 v[68:69], s[60:61], v64, v68, 0
	ds_bpermute_b32 v65, v65, v76
	v_cndmask_b32_e64 v73, v50, v54, s[4:5]
	v_lshl_add_u64 v[68:69], v[68:69], 1, v[70:71]
	global_store_dword v[68:69], v75, off
	v_or_b32_e32 v68, 34, v187
	s_waitcnt lgkmcnt(0)
	v_cndmask_b32_e64 v69, v73, v77, s[4:5]
	v_cndmask_b32_e64 v73, v77, v73, s[4:5]
	v_cvt_pk_bf16_f32 v73, v73, v69
	v_mad_i64_i32 v[68:69], s[60:61], v64, v68, 0
	v_cndmask_b32_e64 v67, v51, v55, s[4:5]
	v_lshl_add_u64 v[68:69], v[68:69], 1, v[70:71]
	global_store_dword v[68:69], v73, off
	v_or_b32_e32 v68, 35, v187
	v_cndmask_b32_e64 v69, v67, v65, s[4:5]
	v_cndmask_b32_e64 v65, v65, v67, s[4:5]
	v_cvt_pk_bf16_f32 v67, v65, v69
	v_mad_i64_i32 v[64:65], s[60:61], v64, v68, 0
	v_lshl_add_u64 v[64:65], v[64:65], 1, v[70:71]
	global_store_dword v[64:65], v67, off

;     __device__ __forceinline__ float* out() const { return (float*)(GAS float*)ld(25); }
; __device__ __forceinline__ u32x4 pack8(f32x4 a, f32x4 b) { u32x4 w; w.x = pk2(a[0], a[1]); w.y = pk2(a[2], a[3]); w.z = pk2(b[0], b[1]); w.w = pk2(b[2], b[3]); return w; }
;     __device__ __forceinline__ void operator()(const f32x4 (&acc)[2][2][4][2], const Unit& u, int wr, int wc, int fr, int fq) const {
;     ...
;                 if (do_rope) {
;                     const float* cs = rope + pos * 64 + 8 * fq;
;                     const f32x4 c0 = *(const f32x4*)cs, c1 = *(const f32x4*)(cs + 4), s0 = *(const f32x4*)(cs + 32), s1 = *(const f32x4*)(cs + 36);
;                     const f32x4 x10 = acc[ai][0][m][0], x11 = acc[ai][0][m][1], x20 = acc[ai][1][m][0], x21 = acc[ai][1][m][1];
;                     f32x4 a0 = x10 * c0 - x20 * s0, a1 = x11 * c1 - x21 * s1, b0 = x20 * c0 + x10 * s0, b1 = x21 * c1 + x11 * s1;
;                     if (pn < 2) {
;                         const int g = 4 * pn + wc;
;                         bf16_t* d = qd + (size_t)r * 512 + 64 * g + 8 * fq;
;                         *(u32x4*)d = pack8(a0 * QS_D, a1 * QS_D); *(u32x4*)(d + 32) = pack8(b0 * QS_D, b1 * QS_D);
;                     } else if (pn < 4) {
;                         const int g = 4 * (pn - 2) + wc;
;                         float* o = out_row(out, r, O_DKP, O_DKS, 512) + 64 * g + 8 * fq;
;                         *(f32x4*)o = a0; *(f32x4*)(o + 4) = a1; *(f32x4*)(o + 32) = b0; *(f32x4*)(o + 36) = b1;
;                         bf16_t* d = kd + (size_t)kr * 512 + 64 * g + 8 * fq;
;                         *(u32x4*)d = pack8(a0, a1); *(u32x4*)(d + 32) = pack8(b0, b1);
;                     } else {
;                         float* o = out_row(out, r, O_KRP, O_KRS, 64) + 8 * fq;
;                         *(f32x4*)o = a0; *(f32x4*)(o + 4) = a1; *(f32x4*)(o + 32) = b0; *(f32x4*)(o + 36) = b1;
;                         const u32x4 wa = pack8(a0, a1), wb = pack8(b0, b1);
; #pragma unroll
;                         for (int hh = 0; hh < 4; ++hh) { bf16_t* d = km + (size_t)kr * 768 + hh * 192 + 128 + 8 * fq; *(u32x4*)d = wa; *(u32x4*)(d + 32) = wb; }
;                     }
.LBB0_361:
	v_lshlrev_b32_e32 v144, 8, v66
	v_lshl_add_u64 v[80:81], v[152:153], 0, v[144:145]
	s_waitcnt lgkmcnt(0)
	global_load_dwordx4 v[64:67], v[80:81], off offset:128
	global_load_dwordx4 v[68:71], v[80:81], off offset:144
	global_load_dwordx4 v[76:79], v[80:81], off
	s_nop 0
	global_load_dwordx4 v[80:83], v[80:81], off offset:16
	s_mov_b64 s[60:61], -1
	s_and_b64 vcc, exec, s[8:9]
	v_ashrrev_i32_e32 v73, 31, v72
	s_waitcnt vmcnt(0)
	v_pk_mul_f32 v[84:85], v[54:55], v[66:67]
	v_pk_mul_f32 v[86:87], v[52:53], v[64:65]
	v_pk_mul_f32 v[88:89], v[50:51], v[70:71]
	v_pk_mul_f32 v[90:91], v[48:49], v[68:69]
	v_pk_mul_f32 v[66:67], v[62:63], v[66:67]
	v_pk_mul_f32 v[64:65], v[60:61], v[64:65]
	v_pk_mul_f32 v[70:71], v[58:59], v[70:71]
	v_pk_mul_f32 v[68:69], v[56:57], v[68:69]
	v_pk_fma_f32 v[62:63], v[62:63], v[78:79], v[84:85] neg_lo:[0,0,1] neg_hi:[0,0,1]
	v_pk_fma_f32 v[60:61], v[60:61], v[76:77], v[86:87] neg_lo:[0,0,1] neg_hi:[0,0,1]
	v_pk_fma_f32 v[58:59], v[58:59], v[82:83], v[88:89] neg_lo:[0,0,1] neg_hi:[0,0,1]
	v_pk_fma_f32 v[56:57], v[56:57], v[80:81], v[90:91] neg_lo:[0,0,1] neg_hi:[0,0,1]
	v_pk_fma_f32 v[54:55], v[54:55], v[78:79], v[66:67]
	v_pk_fma_f32 v[52:53], v[52:53], v[76:77], v[64:65]
	v_pk_fma_f32 v[50:51], v[50:51], v[82:83], v[70:71]
	v_pk_fma_f32 v[48:49], v[48:49], v[80:81], v[68:69]
	s_cbranch_vccnz .LBB0_367
	v_add_u32_e32 v64, 0xffff0000, v72
	v_cndmask_b32_e64 v77, 0, v73, s[14:15]
	v_cndmask_b32_e64 v76, v64, v72, s[14:15]
	s_andn2_b64 vcc, exec, s[52:53]
	v_cvt_pk_bf16_f32 v68, v60, v61
	v_cvt_pk_bf16_f32 v69, v62, v63
	v_cvt_pk_bf16_f32 v70, v56, v57
	v_cvt_pk_bf16_f32 v71, v58, v59
	v_cvt_pk_bf16_f32 v64, v52, v53
	v_cvt_pk_bf16_f32 v65, v54, v55
	v_cvt_pk_bf16_f32 v66, v48, v49
	v_cvt_pk_bf16_f32 v67, v50, v51
	s_cbranch_vccnz .LBB0_364
	v_cndmask_b32_e64 v144, v183, v184, s[14:15]
	v_lshl_add_u64 v[78:79], s[16:17], 0, v[144:145]
	v_lshlrev_b64 v[80:81], 8, v[76:77]
	v_lshl_add_u64 v[78:79], v[78:79], 0, v[80:81]
	v_lshlrev_b32_e32 v144, 2, v146
	v_lshl_add_u64 v[78:79], v[78:79], 0, v[144:145]
	global_store_dwordx4 v[78:79], v[60:63], off nt
	global_store_dwordx4 v[78:79], v[56:59], off offset:16 nt
	global_store_dwordx4 v[78:79], v[52:55], off offset:128 nt
	global_store_dwordx4 v[78:79], v[48:51], off offset:144 nt
	v_mad_i64_i32 v[78:79], s[60:61], v74, s89, v[156:157]
	s_mov_b64 s[60:61], 0
	global_store_dwordx4 v[78:79], v[68:71], off offset:256 nt
	global_store_dwordx4 v[78:79], v[64:67], off offset:320 nt
	global_store_dwordx4 v[78:79], v[68:71], off offset:640 nt
	global_store_dwordx4 v[78:79], v[64:67], off offset:704 nt
	global_store_dwordx4 v[78:79], v[68:71], off offset:1024 nt
	global_store_dwordx4 v[78:79], v[64:67], off offset:1088 nt
	global_store_dwordx4 v[78:79], v[68:71], off offset:1408 nt
	global_store_dwordx4 v[78:79], v[64:67], off offset:1472 nt
.LBB0_364:
	s_andn2_b64 vcc, exec, s[60:61]
	s_cbranch_vccnz .LBB0_366
	v_cndmask_b32_e64 v144, v185, v186, s[14:15]
	v_lshl_add_u64 v[78:79], s[16:17], 0, v[144:145]
	v_lshlrev_b64 v[76:77], 11, v[76:77]
	v_ashrrev_i32_e32 v75, 31, v74
	v_lshl_add_u64 v[76:77], v[78:79], 0, v[76:77]
	v_lshlrev_b64 v[74:75], 10, v[74:75]
	v_lshl_add_u64 v[76:77], s[20:21], 2, v[76:77]
	v_lshlrev_b32_e32 v144, 2, v146
	v_lshl_add_u64 v[74:75], s[26:27], 0, v[74:75]
	v_lshl_add_u64 v[76:77], v[76:77], 0, v[144:145]
	v_lshl_add_u64 v[74:75], s[20:21], 1, v[74:75]
	v_lshlrev_b32_e32 v144, 1, v146
	v_lshl_add_u64 v[74:75], v[74:75], 0, v[144:145]
	global_store_dwordx4 v[76:77], v[60:63], off nt
	global_store_dwordx4 v[76:77], v[56:59], off offset:16 nt
	global_store_dwordx4 v[76:77], v[52:55], off offset:128 nt
	global_store_dwordx4 v[76:77], v[48:51], off offset:144 nt
	global_store_dwordx4 v[74:75], v[68:71], off nt
	global_store_dwordx4 v[74:75], v[64:67], off offset:64 nt

; __device__ __forceinline__ u32x4 pack8(f32x4 a, f32x4 b) { u32x4 w; w.x = pk2(a[0], a[1]); w.y = pk2(a[2], a[3]); w.z = pk2(b[0], b[1]); w.w = pk2(b[2], b[3]); return w; }
;     __device__ __forceinline__ void operator()(const f32x4 (&acc)[2][2][4][2], const Unit& u, int wr, int wc, int fr, int fq) const {
;     ...
;                     if (pn < 2) {
;                         const int g = 4 * pn + wc;
;                         bf16_t* d = qd + (size_t)r * 512 + 64 * g + 8 * fq;
;                         *(u32x4*)d = pack8(a0 * QS_D, a1 * QS_D); *(u32x4*)(d + 32) = pack8(b0 * QS_D, b1 * QS_D);
.LBB0_367:
	s_andn2_b64 vcc, exec, s[60:61]
	s_cbranch_vccnz .LBB0_369
	v_lshlrev_b64 v[64:65], 10, v[72:73]
	v_lshl_add_u64 v[64:65], s[24:25], 0, v[64:65]
	v_lshl_add_u64 v[64:65], s[56:57], 1, v[64:65]
	v_lshlrev_b32_e32 v144, 1, v146
	v_pk_mul_f32 v[62:63], v[62:63], s[40:41] op_sel_hi:[1,0]
	v_pk_mul_f32 v[60:61], v[60:61], s[40:41] op_sel_hi:[1,0]
	v_pk_mul_f32 v[66:67], v[58:59], s[40:41] op_sel_hi:[1,0]
	v_pk_mul_f32 v[58:59], v[56:57], s[40:41] op_sel_hi:[1,0]
	v_lshl_add_u64 v[64:65], v[64:65], 0, v[144:145]
	v_cvt_pk_bf16_f32 v56, v60, v61
	v_cvt_pk_bf16_f32 v57, v62, v63
	v_cvt_pk_bf16_f32 v58, v58, v59
	v_cvt_pk_bf16_f32 v59, v66, v67
	global_store_dwordx4 v[64:65], v[56:59], off nt
	v_pk_mul_f32 v[54:55], v[54:55], s[40:41] op_sel_hi:[1,0]
	v_pk_mul_f32 v[52:53], v[52:53], s[40:41] op_sel_hi:[1,0]
	v_pk_mul_f32 v[56:57], v[50:51], s[40:41] op_sel_hi:[1,0]
	v_pk_mul_f32 v[50:51], v[48:49], s[40:41] op_sel_hi:[1,0]
	v_cvt_pk_bf16_f32 v48, v52, v53
	v_cvt_pk_bf16_f32 v49, v54, v55
	v_cvt_pk_bf16_f32 v50, v50, v51
	v_cvt_pk_bf16_f32 v51, v56, v57
	global_store_dwordx4 v[64:65], v[48:51], off offset:64 nt

;     __device__ __forceinline__ void operator()(const f32x4 (&acc)[2][2][4][2], const Unit& u, int wr, int wc, int fr, int fq) const {
;     ...
;                 } else if (wc < 2) {
;                     float* o = ckvraw + (size_t)r * 128 + 64 * wc + 8 * fq;
; #pragma unroll
;                     for (int bj = 0; bj < 2; ++bj) { *(f32x4*)(o + 32 * bj) = acc[ai][bj][m][0]; *(f32x4*)(o + 32 * bj + 4) = acc[ai][bj][m][1]; }
.LBB0_375:
	s_and_b64 vcc, exec, s[10:11]
	s_cbranch_vccnz .LBB0_385
	s_andn2_b64 vcc, exec, s[58:59]
	s_cbranch_vccnz .LBB0_380
	s_andn2_b64 vcc, exec, s[38:39]
	s_cbranch_vccnz .LBB0_379
	v_ashrrev_i32_e32 v57, 31, v56
	v_lshlrev_b64 v[52:53], 9, v[56:57]
	v_lshl_add_u64 v[52:53], v[148:149], 0, v[52:53]
	global_store_dwordx4 v[52:53], v[44:47], off nt
	global_store_dwordx4 v[52:53], v[40:43], off offset:16 nt
	global_store_dwordx4 v[52:53], v[36:39], off offset:128 nt
	global_store_dwordx4 v[52:53], v[32:35], off offset:144 nt

; __device__ __forceinline__ u32x4 pack8(f32x4 a, f32x4 b) { u32x4 w; w.x = pk2(a[0], a[1]); w.y = pk2(a[2], a[3]); w.z = pk2(b[0], b[1]); w.w = pk2(b[2], b[3]); return w; }
;     __device__ __forceinline__ void operator()(const f32x4 (&acc)[2][2][4][2], const Unit& u, int wr, int wc, int fr, int fq) const {
;     ...
;                 } else if (pn == 6) {
;                     const int c = 64 * wc + 8 * fq; float ss = 0.f;
; #pragma unroll
;                     for (int bj = 0; bj < 2; ++bj) {
;                         const f32x4 y0 = acc[ai][bj][m][0], y1 = acc[ai][bj][m][1];
;                         const f32x4 g0 = *(const f32x4*)(gq + c + 32 * bj), g1 = *(const f32x4*)(gq + c + 32 * bj + 4);
;                         *(u32x4*)(cq + (size_t)r * 256 + c + 32 * bj) = pack8(y0 * g0, y1 * g1);
;                         ss += (y0[0] * y0[0] + y0[1] * y0[1]) + (y0[2] * y0[2] + y0[3] * y0[3]) + (y1[0] * y1[0] + y1[1] * y1[1]) + (y1[2] * y1[2] + y1[3] * y1[3]);
;                     }
;                     ss += __shfl_xor(ss, 16); ss += __shfl_xor(ss, 32);
;                     if (fq == 0) atomicAdd(rsqq + r, ss);
.LBB0_380:
	s_andn2_b64 vcc, exec, s[60:61]
	s_cbranch_vccnz .LBB0_384
	global_load_dwordx4 v[52:55], v[154:155], off
	global_load_dwordx4 v[60:63], v[154:155], off offset:16
	v_ashrrev_i32_e32 v57, 31, v56
	v_lshlrev_b64 v[64:65], 9, v[56:57]
	v_lshl_add_u64 v[64:65], v[150:151], 0, v[64:65]
	v_mul_f32_e32 v49, v45, v45
	v_mul_f32_e32 v51, v47, v47
	s_waitcnt lgkmcnt(0)
	v_mul_f32_e32 v67, v37, v37
	v_mul_f32_e32 v68, v39, v39
	v_mul_f32_e32 v59, v41, v41
	v_mul_f32_e32 v69, v33, v33
	v_and_b32_e32 v73, 64, v180
	v_fmac_f32_e32 v49, v44, v44
	v_fmac_f32_e32 v51, v46, v46
	v_fmac_f32_e32 v67, v36, v36
	v_fmac_f32_e32 v68, v38, v38
	v_mul_f32_e32 v66, v43, v43
	v_mul_f32_e32 v70, v35, v35
	v_xor_b32_e32 v71, 16, v180
	v_fmac_f32_e32 v59, v40, v40
	v_fmac_f32_e32 v69, v32, v32
	v_add_u32_e32 v73, 64, v73
	v_add_f32_e32 v49, v49, v51
	v_add_f32_e32 v51, v67, v68
	v_fmac_f32_e32 v66, v42, v42
	v_fmac_f32_e32 v70, v34, v34
	v_cmp_lt_i32_e32 vcc, v71, v73
	v_add_f32_e32 v49, v49, v59
	v_add_f32_e32 v51, v51, v69
	v_cndmask_b32_e32 v67, v180, v71, vcc
	v_add_f32_e32 v49, v66, v49
	v_add_f32_e32 v51, v70, v51
	v_lshlrev_b32_e32 v59, 2, v67
	v_add_f32_e32 v49, v49, v51
	ds_bpermute_b32 v51, v59, v49
	v_xor_b32_e32 v59, 32, v180
	v_cmp_lt_i32_e32 vcc, v59, v73
	s_waitcnt lgkmcnt(0)
	v_add_f32_e32 v49, v49, v51
	v_cndmask_b32_e32 v59, v180, v59, vcc
	v_lshlrev_b32_e32 v59, 2, v59
	ds_bpermute_b32 v51, v59, v49
	s_waitcnt vmcnt(0)
	v_pk_mul_f32 v[54:55], v[46:47], v[54:55]
	v_pk_mul_f32 v[52:53], v[44:45], v[52:53]
	v_pk_mul_f32 v[62:63], v[42:43], v[62:63]
	v_pk_mul_f32 v[60:61], v[40:41], v[60:61]
	v_cvt_pk_bf16_f32 v52, v52, v53
	v_cvt_pk_bf16_f32 v53, v54, v55
	v_cvt_pk_bf16_f32 v54, v60, v61
	v_cvt_pk_bf16_f32 v55, v62, v63
	global_store_dwordx4 v[64:65], v[52:55], off nt
	global_load_dwordx4 v[52:55], v[154:155], off offset:128
	s_nop 0
	global_load_dwordx4 v[60:63], v[154:155], off offset:144
	s_waitcnt vmcnt(1)
	v_pk_mul_f32 v[54:55], v[38:39], v[54:55]
	v_pk_mul_f32 v[52:53], v[36:37], v[52:53]
	s_waitcnt vmcnt(0)
	v_pk_mul_f32 v[62:63], v[34:35], v[62:63]
	v_pk_mul_f32 v[60:61], v[32:33], v[60:61]
	v_cvt_pk_bf16_f32 v52, v52, v53
	v_cvt_pk_bf16_f32 v53, v54, v55
	v_cvt_pk_bf16_f32 v54, v60, v61
	v_cvt_pk_bf16_f32 v55, v62, v63
	global_store_dwordx4 v[64:65], v[52:55], off offset:64 nt
	s_and_saveexec_b64 s[60:61], s[0:1]
	s_cbranch_execz .LBB0_383
	v_lshl_add_u64 v[52:53], v[56:57], 2, s[30:31]
	s_waitcnt lgkmcnt(0)
	v_add_f32_e32 v49, v49, v51
	global_atomic_add_f32 v[52:53], v49, off

;     __device__ __forceinline__ float* out() const { return (float*)(GAS float*)ld(25); }
; __device__ __forceinline__ unsigned pk2(float lo, float hi) { f32x2_t v = {lo, hi}; bf16x2_t b = __builtin_convertvector(v, bf16x2_t); return __builtin_bit_cast(unsigned, b); }
; __device__ __forceinline__ int permk(int k) { return (k & ~12) | ((k & 4) << 1) | ((k & 8) >> 1); }
;     __device__ __forceinline__ void operator()(const f32x4 (&acc)[2][2][4][2], const Unit& u, int wr, int wc, int fr, int fq) const {
;     ...
;                 } else if (pn < 6) {
;                     const int g = 4 * (pn - 4) + wc;
;                     float* o = out_row(out, r, O_DVP, O_DVS, 512) + 64 * g + 8 * fq;
;                     const bool odd = (fr & 1) != 0;
;                     bf16_t* vb = vtd + (size_t)(kr - kl) * 512 + permk(kl & ~1);
; #pragma unroll
;                     for (int bj = 0; bj < 2; ++bj) {
;                         *(f32x4*)(o + 32 * bj) = acc[ai][bj][m][0]; *(f32x4*)(o + 32 * bj + 4) = acc[ai][bj][m][1];
;                         const f32x4 mine = odd ? acc[ai][bj][m][1] : acc[ai][bj][m][0], send = odd ? acc[ai][bj][m][0] : acc[ai][bj][m][1];
; #pragma unroll
;                         for (int e = 0; e < 4; ++e) {
;                             const float recv = __shfl_xor(send[e], 1);
;                             const int col = 64 * g + 32 * bj + 8 * fq + (odd ? 4 : 0) + e;
;                             if (!novt) *(unsigned*)(vb + (size_t)col * len) = odd ? pk2(recv, mine[e]) : pk2(mine[e], recv);
;                         }
;                     }
.LBB0_385:
	s_andn2_b64 vcc, exec, s[60:61]
	s_cbranch_vccnz .LBB0_387
	v_add_u32_e32 v49, 0xffff0010, v72
	s_waitcnt lgkmcnt(0)
	v_ashrrev_i32_e32 v51, 31, v56
	v_cndmask_b32_e64 v53, 0, v51, s[14:15]
	v_cndmask_b32_e64 v52, v49, v56, s[14:15]
	v_cndmask_b32_e64 v144, v181, v182, s[14:15]
	v_lshl_add_u64 v[54:55], s[16:17], 0, v[144:145]
	v_lshlrev_b64 v[52:53], 11, v[52:53]
	v_lshl_add_u64 v[52:53], v[54:55], 0, v[52:53]
	v_lshlrev_b32_e32 v51, 1, v50
	v_lshrrev_b32_e32 v57, 1, v50
	v_lshl_add_u64 v[52:53], s[54:55], 2, v[52:53]
	v_lshlrev_b32_e32 v144, 2, v146
	v_and_b32_e32 v49, -14, v50
	v_and_b32_e32 v51, 8, v51
	v_and_b32_e32 v57, 4, v57
	v_lshl_add_u64 v[52:53], v[52:53], 0, v[144:145]
	v_or3_b32 v144, v51, v49, v57
	v_and_b32_e32 v51, 64, v180
	v_xor_b32_e32 v49, 1, v180
	v_add_u32_e32 v51, 64, v51
	v_cmp_lt_i32_e32 vcc, v49, v51
	v_cndmask_b32_e64 v60, v44, v40, s[4:5]
	v_sub_u32_e32 v54, v58, v50
	v_cndmask_b32_e32 v49, v180, v49, vcc
	v_lshlrev_b32_e32 v49, 2, v49
	ds_bpermute_b32 v60, v49, v60
	v_cndmask_b32_e64 v64, v45, v41, s[4:5]
	v_ashrrev_i32_e32 v55, 31, v54
	ds_bpermute_b32 v64, v49, v64
	v_lshlrev_b64 v[54:55], 10, v[54:55]
	v_cndmask_b32_e64 v61, v40, v44, s[4:5]
	v_lshl_add_u64 v[54:55], s[28:29], 0, v[54:55]
	v_cndmask_b32_e64 v63, v46, v42, s[4:5]
	s_waitcnt lgkmcnt(0)
	v_cndmask_b32_e64 v65, v61, v60, s[4:5]
	v_cndmask_b32_e64 v60, v60, v61, s[4:5]
	v_lshl_add_u64 v[54:55], v[144:145], 1, v[54:55]
	v_cvt_pk_bf16_f32 v65, v60, v65
	v_mad_i64_i32 v[60:61], s[60:61], v48, v187, 0
	ds_bpermute_b32 v63, v49, v63
	v_cndmask_b32_e64 v59, v41, v45, s[4:5]
	v_lshl_add_u64 v[60:61], v[60:61], 1, v[54:55]
	global_store_dwordx4 v[52:53], v[44:47], off nt
	global_store_dwordx4 v[52:53], v[40:43], off offset:16 nt
	global_store_dword v[60:61], v65, off
	v_or_b32_e32 v60, 1, v187
	v_cndmask_b32_e64 v61, v59, v64, s[4:5]
	v_cndmask_b32_e64 v59, v64, v59, s[4:5]
	v_cndmask_b32_e64 v62, v47, v43, s[4:5]
	v_cvt_pk_bf16_f32 v59, v59, v61
	v_mad_i64_i32 v[60:61], s[60:61], v48, v60, 0
	v_cndmask_b32_e64 v57, v42, v46, s[4:5]
	v_lshl_add_u64 v[60:61], v[60:61], 1, v[54:55]
	ds_bpermute_b32 v62, v49, v62
	global_store_dword v[60:61], v59, off
	v_or_b32_e32 v59, 2, v187
	s_waitcnt lgkmcnt(0)
	v_cndmask_b32_e64 v60, v57, v63, s[4:5]
	v_cndmask_b32_e64 v57, v63, v57, s[4:5]
	v_cvt_pk_bf16_f32 v57, v57, v60
	v_mad_i64_i32 v[60:61], s[60:61], v48, v59, 0
	v_lshl_add_u64 v[60:61], v[60:61], 1, v[54:55]
	v_cndmask_b32_e64 v51, v43, v47, s[4:5]
	global_store_dword v[60:61], v57, off
	v_or_b32_e32 v57, 3, v187
	v_cndmask_b32_e64 v59, v51, v62, s[4:5]
	v_cndmask_b32_e64 v51, v62, v51, s[4:5]
	v_mad_i64_i32 v[60:61], s[60:61], v48, v57, 0
	v_cvt_pk_bf16_f32 v51, v51, v59
	v_lshl_add_u64 v[60:61], v[60:61], 1, v[54:55]
	global_store_dword v[60:61], v51, off
	global_store_dwordx4 v[52:53], v[36:39], off offset:128 nt
	global_store_dwordx4 v[52:53], v[32:35], off offset:144 nt
	v_cndmask_b32_e64 v53, v36, v32, s[4:5]
	ds_bpermute_b32 v53, v49, v53
	v_cndmask_b32_e64 v62, v37, v33, s[4:5]
	ds_bpermute_b32 v62, v49, v62
	v_cndmask_b32_e64 v52, v32, v36, s[4:5]
	v_cndmask_b32_e64 v61, v38, v34, s[4:5]
	v_or_b32_e32 v63, 32, v187
	s_waitcnt lgkmcnt(0)
	v_cndmask_b32_e64 v64, v52, v53, s[4:5]
	v_cndmask_b32_e64 v52, v53, v52, s[4:5]
	v_cvt_pk_bf16_f32 v64, v52, v64
	v_mad_i64_i32 v[52:53], s[60:61], v48, v63, 0
	ds_bpermute_b32 v61, v49, v61
	v_cndmask_b32_e64 v59, v33, v37, s[4:5]
	v_lshl_add_u64 v[52:53], v[52:53], 1, v[54:55]
	v_cndmask_b32_e64 v60, v39, v35, s[4:5]
	global_store_dword v[52:53], v64, off
	v_or_b32_e32 v52, 33, v187
	v_cndmask_b32_e64 v53, v59, v62, s[4:5]
	v_cndmask_b32_e64 v59, v62, v59, s[4:5]
	v_cvt_pk_bf16_f32 v59, v59, v53
	v_mad_i64_i32 v[52:53], s[60:61], v48, v52, 0
	ds_bpermute_b32 v49, v49, v60
	v_cndmask_b32_e64 v57, v34, v38, s[4:5]
	v_lshl_add_u64 v[52:53], v[52:53], 1, v[54:55]
	global_store_dword v[52:53], v59, off
	v_or_b32_e32 v52, 34, v187
	s_waitcnt lgkmcnt(0)
	v_cndmask_b32_e64 v53, v57, v61, s[4:5]
	v_cndmask_b32_e64 v57, v61, v57, s[4:5]
	v_cvt_pk_bf16_f32 v57, v57, v53
	v_mad_i64_i32 v[52:53], s[60:61], v48, v52, 0
	v_cndmask_b32_e64 v51, v35, v39, s[4:5]
	v_lshl_add_u64 v[52:53], v[52:53], 1, v[54:55]
	global_store_dword v[52:53], v57, off
	v_or_b32_e32 v52, 35, v187
	v_cndmask_b32_e64 v53, v51, v49, s[4:5]
	v_cndmask_b32_e64 v49, v49, v51, s[4:5]
	v_cvt_pk_bf16_f32 v51, v49, v53
	v_mad_i64_i32 v[48:49], s[60:61], v48, v52, 0
	v_lshl_add_u64 v[48:49], v[48:49], 1, v[54:55]
	global_store_dword v[48:49], v51, off

;     __device__ __forceinline__ float* out() const { return (float*)(GAS float*)ld(25); }
; __device__ __forceinline__ u32x4 pack8(f32x4 a, f32x4 b) { u32x4 w; w.x = pk2(a[0], a[1]); w.y = pk2(a[2], a[3]); w.z = pk2(b[0], b[1]); w.w = pk2(b[2], b[3]); return w; }
;     __device__ __forceinline__ void operator()(const f32x4 (&acc)[2][2][4][2], const Unit& u, int wr, int wc, int fr, int fq) const {
;     ...
;                 if (do_rope) {
;                     const float* cs = rope + pos * 64 + 8 * fq;
;                     const f32x4 c0 = *(const f32x4*)cs, c1 = *(const f32x4*)(cs + 4), s0 = *(const f32x4*)(cs + 32), s1 = *(const f32x4*)(cs + 36);
;                     const f32x4 x10 = acc[ai][0][m][0], x11 = acc[ai][0][m][1], x20 = acc[ai][1][m][0], x21 = acc[ai][1][m][1];
;                     f32x4 a0 = x10 * c0 - x20 * s0, a1 = x11 * c1 - x21 * s1, b0 = x20 * c0 + x10 * s0, b1 = x21 * c1 + x11 * s1;
;                     if (pn < 2) {
;                         const int g = 4 * pn + wc;
;                         bf16_t* d = qd + (size_t)r * 512 + 64 * g + 8 * fq;
;                         *(u32x4*)d = pack8(a0 * QS_D, a1 * QS_D); *(u32x4*)(d + 32) = pack8(b0 * QS_D, b1 * QS_D);
;                     } else if (pn < 4) {
;                         const int g = 4 * (pn - 2) + wc;
;                         float* o = out_row(out, r, O_DKP, O_DKS, 512) + 64 * g + 8 * fq;
;                         *(f32x4*)o = a0; *(f32x4*)(o + 4) = a1; *(f32x4*)(o + 32) = b0; *(f32x4*)(o + 36) = b1;
;                         bf16_t* d = kd + (size_t)kr * 512 + 64 * g + 8 * fq;
;                         *(u32x4*)d = pack8(a0, a1); *(u32x4*)(d + 32) = pack8(b0, b1);
;                     } else {
;                         float* o = out_row(out, r, O_KRP, O_KRS, 64) + 8 * fq;
;                         *(f32x4*)o = a0; *(f32x4*)(o + 4) = a1; *(f32x4*)(o + 32) = b0; *(f32x4*)(o + 36) = b1;
;                         const u32x4 wa = pack8(a0, a1), wb = pack8(b0, b1);
; #pragma unroll
;                         for (int hh = 0; hh < 4; ++hh) { bf16_t* d = km + (size_t)kr * 768 + hh * 192 + 128 + 8 * fq; *(u32x4*)d = wa; *(u32x4*)(d + 32) = wb; }
;                     }
.LBB0_388:
	v_lshlrev_b32_e32 v144, 6, v50
	v_lshl_add_u64 v[64:65], v[144:145], 2, v[152:153]
	s_waitcnt lgkmcnt(0)
	global_load_dwordx4 v[48:51], v[64:65], off offset:128
	global_load_dwordx4 v[52:55], v[64:65], off offset:144
	global_load_dwordx4 v[60:63], v[64:65], off
	s_nop 0
	global_load_dwordx4 v[64:67], v[64:65], off offset:16
	s_mov_b64 s[60:61], -1
	s_and_b64 vcc, exec, s[8:9]
	v_ashrrev_i32_e32 v57, 31, v56
	s_waitcnt vmcnt(0)
	v_pk_mul_f32 v[68:69], v[38:39], v[50:51]
	v_pk_mul_f32 v[70:71], v[36:37], v[48:49]
	v_pk_mul_f32 v[74:75], v[34:35], v[54:55]
	v_pk_mul_f32 v[76:77], v[32:33], v[52:53]
	v_pk_mul_f32 v[50:51], v[46:47], v[50:51]
	v_pk_mul_f32 v[48:49], v[44:45], v[48:49]
	v_pk_mul_f32 v[54:55], v[42:43], v[54:55]
	v_pk_mul_f32 v[52:53], v[40:41], v[52:53]
	v_pk_fma_f32 v[46:47], v[46:47], v[62:63], v[68:69] neg_lo:[0,0,1] neg_hi:[0,0,1]
	v_pk_fma_f32 v[44:45], v[44:45], v[60:61], v[70:71] neg_lo:[0,0,1] neg_hi:[0,0,1]
	v_pk_fma_f32 v[42:43], v[42:43], v[66:67], v[74:75] neg_lo:[0,0,1] neg_hi:[0,0,1]
	v_pk_fma_f32 v[40:41], v[40:41], v[64:65], v[76:77] neg_lo:[0,0,1] neg_hi:[0,0,1]
	v_pk_fma_f32 v[38:39], v[38:39], v[62:63], v[50:51]
	v_pk_fma_f32 v[36:37], v[36:37], v[60:61], v[48:49]
	v_pk_fma_f32 v[34:35], v[34:35], v[66:67], v[54:55]
	v_pk_fma_f32 v[32:33], v[32:33], v[64:65], v[52:53]
	s_cbranch_vccnz .LBB0_394
	v_add_u32_e32 v48, 0xffff0010, v72
	v_cndmask_b32_e64 v61, 0, v57, s[14:15]
	v_cndmask_b32_e64 v60, v48, v56, s[14:15]
	s_andn2_b64 vcc, exec, s[52:53]
	v_cvt_pk_bf16_f32 v52, v44, v45
	v_cvt_pk_bf16_f32 v53, v46, v47
	v_cvt_pk_bf16_f32 v54, v40, v41
	v_cvt_pk_bf16_f32 v55, v42, v43
	v_cvt_pk_bf16_f32 v48, v36, v37
	v_cvt_pk_bf16_f32 v49, v38, v39
	v_cvt_pk_bf16_f32 v50, v32, v33
	v_cvt_pk_bf16_f32 v51, v34, v35
	s_cbranch_vccnz .LBB0_391
	v_cndmask_b32_e64 v144, v183, v184, s[14:15]
	v_lshl_add_u64 v[62:63], s[16:17], 0, v[144:145]
	v_lshlrev_b64 v[64:65], 8, v[60:61]
	v_lshl_add_u64 v[62:63], v[62:63], 0, v[64:65]
	v_lshlrev_b32_e32 v144, 2, v146
	v_lshl_add_u64 v[62:63], v[62:63], 0, v[144:145]
	global_store_dwordx4 v[62:63], v[44:47], off nt
	global_store_dwordx4 v[62:63], v[40:43], off offset:16 nt
	global_store_dwordx4 v[62:63], v[36:39], off offset:128 nt
	global_store_dwordx4 v[62:63], v[32:35], off offset:144 nt
	v_mad_i64_i32 v[62:63], s[60:61], v58, s89, v[156:157]
	s_mov_b64 s[60:61], 0
	global_store_dwordx4 v[62:63], v[52:55], off offset:256 nt
	global_store_dwordx4 v[62:63], v[48:51], off offset:320 nt
	global_store_dwordx4 v[62:63], v[52:55], off offset:640 nt
	global_store_dwordx4 v[62:63], v[48:51], off offset:704 nt
	global_store_dwordx4 v[62:63], v[52:55], off offset:1024 nt
	global_store_dwordx4 v[62:63], v[48:51], off offset:1088 nt
	global_store_dwordx4 v[62:63], v[52:55], off offset:1408 nt
	global_store_dwordx4 v[62:63], v[48:51], off offset:1472 nt
.LBB0_391:
	s_andn2_b64 vcc, exec, s[60:61]
	s_cbranch_vccnz .LBB0_393
	v_cndmask_b32_e64 v144, v185, v186, s[14:15]
	v_lshl_add_u64 v[62:63], s[16:17], 0, v[144:145]
	v_lshlrev_b64 v[60:61], 11, v[60:61]
	v_ashrrev_i32_e32 v59, 31, v58
	v_lshl_add_u64 v[60:61], v[62:63], 0, v[60:61]
	v_lshlrev_b64 v[58:59], 10, v[58:59]
	v_lshl_add_u64 v[60:61], s[20:21], 2, v[60:61]
	v_lshlrev_b32_e32 v144, 2, v146
	v_lshl_add_u64 v[58:59], s[26:27], 0, v[58:59]
	v_lshl_add_u64 v[60:61], v[60:61], 0, v[144:145]
	v_lshl_add_u64 v[58:59], s[20:21], 1, v[58:59]
	v_lshlrev_b32_e32 v144, 1, v146
	v_lshl_add_u64 v[58:59], v[58:59], 0, v[144:145]
	global_store_dwordx4 v[60:61], v[44:47], off nt
	global_store_dwordx4 v[60:61], v[40:43], off offset:16 nt
	global_store_dwordx4 v[60:61], v[36:39], off offset:128 nt
	global_store_dwordx4 v[60:61], v[32:35], off offset:144 nt
	global_store_dwordx4 v[58:59], v[52:55], off nt
	global_store_dwordx4 v[58:59], v[48:51], off offset:64 nt

; __device__ __forceinline__ u32x4 pack8(f32x4 a, f32x4 b) { u32x4 w; w.x = pk2(a[0], a[1]); w.y = pk2(a[2], a[3]); w.z = pk2(b[0], b[1]); w.w = pk2(b[2], b[3]); return w; }
;     __device__ __forceinline__ void operator()(const f32x4 (&acc)[2][2][4][2], const Unit& u, int wr, int wc, int fr, int fq) const {
;     ...
;                     if (pn < 2) {
;                         const int g = 4 * pn + wc;
;                         bf16_t* d = qd + (size_t)r * 512 + 64 * g + 8 * fq;
;                         *(u32x4*)d = pack8(a0 * QS_D, a1 * QS_D); *(u32x4*)(d + 32) = pack8(b0 * QS_D, b1 * QS_D);
.LBB0_394:
	s_andn2_b64 vcc, exec, s[60:61]
	s_cbranch_vccnz .LBB0_396
	v_lshlrev_b64 v[48:49], 10, v[56:57]
	v_lshl_add_u64 v[48:49], s[24:25], 0, v[48:49]
	v_lshl_add_u64 v[48:49], s[56:57], 1, v[48:49]
	v_lshlrev_b32_e32 v144, 1, v146
	v_pk_mul_f32 v[46:47], v[46:47], s[40:41] op_sel_hi:[1,0]
	v_pk_mul_f32 v[44:45], v[44:45], s[40:41] op_sel_hi:[1,0]
	v_pk_mul_f32 v[50:51], v[42:43], s[40:41] op_sel_hi:[1,0]
	v_pk_mul_f32 v[42:43], v[40:41], s[40:41] op_sel_hi:[1,0]
	v_lshl_add_u64 v[48:49], v[48:49], 0, v[144:145]
	v_cvt_pk_bf16_f32 v40, v44, v45
	v_cvt_pk_bf16_f32 v41, v46, v47
	v_cvt_pk_bf16_f32 v42, v42, v43
	v_cvt_pk_bf16_f32 v43, v50, v51
	global_store_dwordx4 v[48:49], v[40:43], off nt
	v_pk_mul_f32 v[38:39], v[38:39], s[40:41] op_sel_hi:[1,0]
	v_pk_mul_f32 v[36:37], v[36:37], s[40:41] op_sel_hi:[1,0]
	v_pk_mul_f32 v[40:41], v[34:35], s[40:41] op_sel_hi:[1,0]
	v_pk_mul_f32 v[34:35], v[32:33], s[40:41] op_sel_hi:[1,0]
	v_cvt_pk_bf16_f32 v32, v36, v37
	v_cvt_pk_bf16_f32 v33, v38, v39
	v_cvt_pk_bf16_f32 v34, v34, v35
	v_cvt_pk_bf16_f32 v35, v40, v41
	global_store_dwordx4 v[48:49], v[32:35], off offset:64 nt

;     __device__ __forceinline__ void operator()(const f32x4 (&acc)[2][2][4][2], const Unit& u, int wr, int wc, int fr, int fq) const {
;     ...
;                 } else if (wc < 2) {
;                     float* o = ckvraw + (size_t)r * 128 + 64 * wc + 8 * fq;
; #pragma unroll
;                     for (int bj = 0; bj < 2; ++bj) { *(f32x4*)(o + 32 * bj) = acc[ai][bj][m][0]; *(f32x4*)(o + 32 * bj + 4) = acc[ai][bj][m][1]; }
.LBB0_402:
	s_and_b64 vcc, exec, s[10:11]
	s_cbranch_vccnz .LBB0_412
	s_andn2_b64 vcc, exec, s[58:59]
	s_cbranch_vccnz .LBB0_407
	s_andn2_b64 vcc, exec, s[38:39]
	s_cbranch_vccnz .LBB0_406
	v_ashrrev_i32_e32 v41, 31, v40
	v_lshlrev_b64 v[36:37], 9, v[40:41]
	v_lshl_add_u64 v[36:37], v[148:149], 0, v[36:37]
	global_store_dwordx4 v[36:37], v[28:31], off nt
	global_store_dwordx4 v[36:37], v[24:27], off offset:16 nt
	global_store_dwordx4 v[36:37], v[20:23], off offset:128 nt
	global_store_dwordx4 v[36:37], v[16:19], off offset:144 nt

; __device__ __forceinline__ u32x4 pack8(f32x4 a, f32x4 b) { u32x4 w; w.x = pk2(a[0], a[1]); w.y = pk2(a[2], a[3]); w.z = pk2(b[0], b[1]); w.w = pk2(b[2], b[3]); return w; }
;     __device__ __forceinline__ void operator()(const f32x4 (&acc)[2][2][4][2], const Unit& u, int wr, int wc, int fr, int fq) const {
;     ...
;                 } else if (pn == 6) {
;                     const int c = 64 * wc + 8 * fq; float ss = 0.f;
; #pragma unroll
;                     for (int bj = 0; bj < 2; ++bj) {
;                         const f32x4 y0 = acc[ai][bj][m][0], y1 = acc[ai][bj][m][1];
;                         const f32x4 g0 = *(const f32x4*)(gq + c + 32 * bj), g1 = *(const f32x4*)(gq + c + 32 * bj + 4);
;                         *(u32x4*)(cq + (size_t)r * 256 + c + 32 * bj) = pack8(y0 * g0, y1 * g1);
;                         ss += (y0[0] * y0[0] + y0[1] * y0[1]) + (y0[2] * y0[2] + y0[3] * y0[3]) + (y1[0] * y1[0] + y1[1] * y1[1]) + (y1[2] * y1[2] + y1[3] * y1[3]);
;                     }
;                     ss += __shfl_xor(ss, 16); ss += __shfl_xor(ss, 32);
;                     if (fq == 0) atomicAdd(rsqq + r, ss);
.LBB0_407:
	s_andn2_b64 vcc, exec, s[60:61]
	s_cbranch_vccnz .LBB0_411
	global_load_dwordx4 v[36:39], v[154:155], off
	global_load_dwordx4 v[44:47], v[154:155], off offset:16
	v_ashrrev_i32_e32 v41, 31, v40
	v_lshlrev_b64 v[48:49], 9, v[40:41]
	v_lshl_add_u64 v[48:49], v[150:151], 0, v[48:49]
	v_mul_f32_e32 v33, v29, v29
	v_mul_f32_e32 v35, v31, v31
	s_waitcnt lgkmcnt(0)
	v_mul_f32_e32 v51, v21, v21
	v_mul_f32_e32 v52, v23, v23
	v_mul_f32_e32 v43, v25, v25
	v_mul_f32_e32 v53, v17, v17
	v_and_b32_e32 v56, 64, v180
	v_fmac_f32_e32 v33, v28, v28
	v_fmac_f32_e32 v35, v30, v30
	v_fmac_f32_e32 v51, v20, v20
	v_fmac_f32_e32 v52, v22, v22
	v_mul_f32_e32 v50, v27, v27
	v_mul_f32_e32 v54, v19, v19
	v_xor_b32_e32 v55, 16, v180
	v_fmac_f32_e32 v43, v24, v24
	v_fmac_f32_e32 v53, v16, v16
	v_add_u32_e32 v56, 64, v56
	v_add_f32_e32 v33, v33, v35
	v_add_f32_e32 v35, v51, v52
	v_fmac_f32_e32 v50, v26, v26
	v_fmac_f32_e32 v54, v18, v18
	v_cmp_lt_i32_e32 vcc, v55, v56
	v_add_f32_e32 v33, v33, v43
	v_add_f32_e32 v35, v35, v53
	v_cndmask_b32_e32 v51, v180, v55, vcc
	v_add_f32_e32 v33, v50, v33
	v_add_f32_e32 v35, v54, v35
	v_lshlrev_b32_e32 v43, 2, v51
	v_add_f32_e32 v33, v33, v35
	ds_bpermute_b32 v35, v43, v33
	v_xor_b32_e32 v43, 32, v180
	v_cmp_lt_i32_e32 vcc, v43, v56
	s_waitcnt lgkmcnt(0)
	v_add_f32_e32 v33, v33, v35
	v_cndmask_b32_e32 v43, v180, v43, vcc
	v_lshlrev_b32_e32 v43, 2, v43
	ds_bpermute_b32 v35, v43, v33
	s_waitcnt vmcnt(0)
	v_pk_mul_f32 v[38:39], v[30:31], v[38:39]
	v_pk_mul_f32 v[36:37], v[28:29], v[36:37]
	v_pk_mul_f32 v[46:47], v[26:27], v[46:47]
	v_pk_mul_f32 v[44:45], v[24:25], v[44:45]
	v_cvt_pk_bf16_f32 v36, v36, v37
	v_cvt_pk_bf16_f32 v37, v38, v39
	v_cvt_pk_bf16_f32 v38, v44, v45
	v_cvt_pk_bf16_f32 v39, v46, v47
	global_store_dwordx4 v[48:49], v[36:39], off nt
	global_load_dwordx4 v[36:39], v[154:155], off offset:128
	s_nop 0
	global_load_dwordx4 v[44:47], v[154:155], off offset:144
	s_waitcnt vmcnt(1)
	v_pk_mul_f32 v[38:39], v[22:23], v[38:39]
	v_pk_mul_f32 v[36:37], v[20:21], v[36:37]
	s_waitcnt vmcnt(0)
	v_pk_mul_f32 v[46:47], v[18:19], v[46:47]
	v_pk_mul_f32 v[44:45], v[16:17], v[44:45]
	v_cvt_pk_bf16_f32 v36, v36, v37
	v_cvt_pk_bf16_f32 v37, v38, v39
	v_cvt_pk_bf16_f32 v38, v44, v45
	v_cvt_pk_bf16_f32 v39, v46, v47
	global_store_dwordx4 v[48:49], v[36:39], off offset:64 nt
	s_and_saveexec_b64 s[60:61], s[0:1]
	s_cbranch_execz .LBB0_410
	v_lshl_add_u64 v[36:37], v[40:41], 2, s[30:31]
	s_waitcnt lgkmcnt(0)
	v_add_f32_e32 v33, v33, v35
	global_atomic_add_f32 v[36:37], v33, off

;     __device__ __forceinline__ float* out() const { return (float*)(GAS float*)ld(25); }
; __device__ __forceinline__ unsigned pk2(float lo, float hi) { f32x2_t v = {lo, hi}; bf16x2_t b = __builtin_convertvector(v, bf16x2_t); return __builtin_bit_cast(unsigned, b); }
; __device__ __forceinline__ int permk(int k) { return (k & ~12) | ((k & 4) << 1) | ((k & 8) >> 1); }
;     __device__ __forceinline__ void operator()(const f32x4 (&acc)[2][2][4][2], const Unit& u, int wr, int wc, int fr, int fq) const {
;     ...
;                 } else if (pn < 6) {
;                     const int g = 4 * (pn - 4) + wc;
;                     float* o = out_row(out, r, O_DVP, O_DVS, 512) + 64 * g + 8 * fq;
;                     const bool odd = (fr & 1) != 0;
;                     bf16_t* vb = vtd + (size_t)(kr - kl) * 512 + permk(kl & ~1);
; #pragma unroll
;                     for (int bj = 0; bj < 2; ++bj) {
;                         *(f32x4*)(o + 32 * bj) = acc[ai][bj][m][0]; *(f32x4*)(o + 32 * bj + 4) = acc[ai][bj][m][1];
;                         const f32x4 mine = odd ? acc[ai][bj][m][1] : acc[ai][bj][m][0], send = odd ? acc[ai][bj][m][0] : acc[ai][bj][m][1];
; #pragma unroll
;                         for (int e = 0; e < 4; ++e) {
;                             const float recv = __shfl_xor(send[e], 1);
;                             const int col = 64 * g + 32 * bj + 8 * fq + (odd ? 4 : 0) + e;
;                             if (!novt) *(unsigned*)(vb + (size_t)col * len) = odd ? pk2(recv, mine[e]) : pk2(mine[e], recv);
;                         }
;                     }
.LBB0_412:
	s_andn2_b64 vcc, exec, s[60:61]
	s_cbranch_vccnz .LBB0_414
	v_add_u32_e32 v33, 0xffff0020, v72
	s_waitcnt lgkmcnt(0)
	v_ashrrev_i32_e32 v35, 31, v40
	v_cndmask_b32_e64 v37, 0, v35, s[14:15]
	v_cndmask_b32_e64 v36, v33, v40, s[14:15]
	v_cndmask_b32_e64 v144, v181, v182, s[14:15]
	v_lshl_add_u64 v[38:39], s[16:17], 0, v[144:145]
	v_lshlrev_b64 v[36:37], 11, v[36:37]
	v_lshl_add_u64 v[36:37], v[38:39], 0, v[36:37]
	v_lshlrev_b32_e32 v35, 1, v34
	v_lshrrev_b32_e32 v41, 1, v34
	v_lshl_add_u64 v[36:37], s[54:55], 2, v[36:37]
	v_lshlrev_b32_e32 v144, 2, v146
	v_and_b32_e32 v33, -14, v34
	v_and_b32_e32 v35, 8, v35
	v_and_b32_e32 v41, 4, v41
	v_lshl_add_u64 v[36:37], v[36:37], 0, v[144:145]
	v_or3_b32 v144, v35, v33, v41
	v_and_b32_e32 v35, 64, v180
	v_xor_b32_e32 v33, 1, v180
	v_add_u32_e32 v35, 64, v35
	v_cmp_lt_i32_e32 vcc, v33, v35
	v_cndmask_b32_e64 v44, v28, v24, s[4:5]
	v_sub_u32_e32 v38, v42, v34
	v_cndmask_b32_e32 v33, v180, v33, vcc
	v_lshlrev_b32_e32 v33, 2, v33
	ds_bpermute_b32 v44, v33, v44
	v_cndmask_b32_e64 v48, v29, v25, s[4:5]
	v_ashrrev_i32_e32 v39, 31, v38
	ds_bpermute_b32 v48, v33, v48
	v_lshlrev_b64 v[38:39], 10, v[38:39]
	v_cndmask_b32_e64 v45, v24, v28, s[4:5]
	v_lshl_add_u64 v[38:39], s[28:29], 0, v[38:39]
	v_cndmask_b32_e64 v47, v30, v26, s[4:5]
	s_waitcnt lgkmcnt(0)
	v_cndmask_b32_e64 v49, v45, v44, s[4:5]
	v_cndmask_b32_e64 v44, v44, v45, s[4:5]
	v_lshl_add_u64 v[38:39], v[144:145], 1, v[38:39]
	v_cvt_pk_bf16_f32 v49, v44, v49
	v_mad_i64_i32 v[44:45], s[60:61], v32, v187, 0
	ds_bpermute_b32 v47, v33, v47
	v_cndmask_b32_e64 v43, v25, v29, s[4:5]
	v_lshl_add_u64 v[44:45], v[44:45], 1, v[38:39]
	global_store_dwordx4 v[36:37], v[28:31], off nt
	global_store_dwordx4 v[36:37], v[24:27], off offset:16 nt
	global_store_dword v[44:45], v49, off
	v_or_b32_e32 v44, 1, v187
	v_cndmask_b32_e64 v45, v43, v48, s[4:5]
	v_cndmask_b32_e64 v43, v48, v43, s[4:5]
	v_cndmask_b32_e64 v46, v31, v27, s[4:5]
	v_cvt_pk_bf16_f32 v43, v43, v45
	v_mad_i64_i32 v[44:45], s[60:61], v32, v44, 0
	v_cndmask_b32_e64 v41, v26, v30, s[4:5]
	v_lshl_add_u64 v[44:45], v[44:45], 1, v[38:39]
	ds_bpermute_b32 v46, v33, v46
	global_store_dword v[44:45], v43, off
	v_or_b32_e32 v43, 2, v187
	s_waitcnt lgkmcnt(0)
	v_cndmask_b32_e64 v44, v41, v47, s[4:5]
	v_cndmask_b32_e64 v41, v47, v41, s[4:5]
	v_cvt_pk_bf16_f32 v41, v41, v44
	v_mad_i64_i32 v[44:45], s[60:61], v32, v43, 0
	v_lshl_add_u64 v[44:45], v[44:45], 1, v[38:39]
	v_cndmask_b32_e64 v35, v27, v31, s[4:5]
	global_store_dword v[44:45], v41, off
	v_or_b32_e32 v41, 3, v187
	v_cndmask_b32_e64 v43, v35, v46, s[4:5]
	v_cndmask_b32_e64 v35, v46, v35, s[4:5]
	v_mad_i64_i32 v[44:45], s[60:61], v32, v41, 0
	v_cvt_pk_bf16_f32 v35, v35, v43
	v_lshl_add_u64 v[44:45], v[44:45], 1, v[38:39]
	global_store_dword v[44:45], v35, off
	global_store_dwordx4 v[36:37], v[20:23], off offset:128 nt
	global_store_dwordx4 v[36:37], v[16:19], off offset:144 nt
	v_cndmask_b32_e64 v37, v20, v16, s[4:5]
	ds_bpermute_b32 v37, v33, v37
	v_cndmask_b32_e64 v46, v21, v17, s[4:5]
	ds_bpermute_b32 v46, v33, v46
	v_cndmask_b32_e64 v36, v16, v20, s[4:5]
	v_cndmask_b32_e64 v45, v22, v18, s[4:5]
	v_or_b32_e32 v47, 32, v187
	s_waitcnt lgkmcnt(0)
	v_cndmask_b32_e64 v48, v36, v37, s[4:5]
	v_cndmask_b32_e64 v36, v37, v36, s[4:5]
	v_cvt_pk_bf16_f32 v48, v36, v48
	v_mad_i64_i32 v[36:37], s[60:61], v32, v47, 0
	ds_bpermute_b32 v45, v33, v45
	v_cndmask_b32_e64 v43, v17, v21, s[4:5]
	v_lshl_add_u64 v[36:37], v[36:37], 1, v[38:39]
	v_cndmask_b32_e64 v44, v23, v19, s[4:5]
	global_store_dword v[36:37], v48, off
	v_or_b32_e32 v36, 33, v187
	v_cndmask_b32_e64 v37, v43, v46, s[4:5]
	v_cndmask_b32_e64 v43, v46, v43, s[4:5]
	v_cvt_pk_bf16_f32 v43, v43, v37
	v_mad_i64_i32 v[36:37], s[60:61], v32, v36, 0
	ds_bpermute_b32 v33, v33, v44
	v_cndmask_b32_e64 v41, v18, v22, s[4:5]
	v_lshl_add_u64 v[36:37], v[36:37], 1, v[38:39]
	global_store_dword v[36:37], v43, off
	v_or_b32_e32 v36, 34, v187
	s_waitcnt lgkmcnt(0)
	v_cndmask_b32_e64 v37, v41, v45, s[4:5]
	v_cndmask_b32_e64 v41, v45, v41, s[4:5]
	v_cvt_pk_bf16_f32 v41, v41, v37
	v_mad_i64_i32 v[36:37], s[60:61], v32, v36, 0
	v_cndmask_b32_e64 v35, v19, v23, s[4:5]
	v_lshl_add_u64 v[36:37], v[36:37], 1, v[38:39]
	global_store_dword v[36:37], v41, off
	v_or_b32_e32 v36, 35, v187
	v_cndmask_b32_e64 v37, v35, v33, s[4:5]
	v_cndmask_b32_e64 v33, v33, v35, s[4:5]
	v_cvt_pk_bf16_f32 v35, v33, v37
	v_mad_i64_i32 v[32:33], s[60:61], v32, v36, 0
	v_lshl_add_u64 v[32:33], v[32:33], 1, v[38:39]
	global_store_dword v[32:33], v35, off

;     __device__ __forceinline__ float* out() const { return (float*)(GAS float*)ld(25); }
; __device__ __forceinline__ u32x4 pack8(f32x4 a, f32x4 b) { u32x4 w; w.x = pk2(a[0], a[1]); w.y = pk2(a[2], a[3]); w.z = pk2(b[0], b[1]); w.w = pk2(b[2], b[3]); return w; }
;     __device__ __forceinline__ void operator()(const f32x4 (&acc)[2][2][4][2], const Unit& u, int wr, int wc, int fr, int fq) const {
;     ...
;                 if (do_rope) {
;                     const float* cs = rope + pos * 64 + 8 * fq;
;                     const f32x4 c0 = *(const f32x4*)cs, c1 = *(const f32x4*)(cs + 4), s0 = *(const f32x4*)(cs + 32), s1 = *(const f32x4*)(cs + 36);
;                     const f32x4 x10 = acc[ai][0][m][0], x11 = acc[ai][0][m][1], x20 = acc[ai][1][m][0], x21 = acc[ai][1][m][1];
;                     f32x4 a0 = x10 * c0 - x20 * s0, a1 = x11 * c1 - x21 * s1, b0 = x20 * c0 + x10 * s0, b1 = x21 * c1 + x11 * s1;
;                     if (pn < 2) {
;                         const int g = 4 * pn + wc;
;                         bf16_t* d = qd + (size_t)r * 512 + 64 * g + 8 * fq;
;                         *(u32x4*)d = pack8(a0 * QS_D, a1 * QS_D); *(u32x4*)(d + 32) = pack8(b0 * QS_D, b1 * QS_D);
;                     } else if (pn < 4) {
;                         const int g = 4 * (pn - 2) + wc;
;                         float* o = out_row(out, r, O_DKP, O_DKS, 512) + 64 * g + 8 * fq;
;                         *(f32x4*)o = a0; *(f32x4*)(o + 4) = a1; *(f32x4*)(o + 32) = b0; *(f32x4*)(o + 36) = b1;
;                         bf16_t* d = kd + (size_t)kr * 512 + 64 * g + 8 * fq;
;                         *(u32x4*)d = pack8(a0, a1); *(u32x4*)(d + 32) = pack8(b0, b1);
;                     } else {
;                         float* o = out_row(out, r, O_KRP, O_KRS, 64) + 8 * fq;
;                         *(f32x4*)o = a0; *(f32x4*)(o + 4) = a1; *(f32x4*)(o + 32) = b0; *(f32x4*)(o + 36) = b1;
;                         const u32x4 wa = pack8(a0, a1), wb = pack8(b0, b1);
; #pragma unroll
;                         for (int hh = 0; hh < 4; ++hh) { bf16_t* d = km + (size_t)kr * 768 + hh * 192 + 128 + 8 * fq; *(u32x4*)d = wa; *(u32x4*)(d + 32) = wb; }
;                     }
.LBB0_415:
	v_lshlrev_b32_e32 v144, 6, v34
	v_lshl_add_u64 v[48:49], v[144:145], 2, v[152:153]
	s_waitcnt lgkmcnt(0)
	global_load_dwordx4 v[32:35], v[48:49], off offset:128
	global_load_dwordx4 v[36:39], v[48:49], off offset:144
	global_load_dwordx4 v[44:47], v[48:49], off
	s_nop 0
	global_load_dwordx4 v[48:51], v[48:49], off offset:16
	s_mov_b64 s[60:61], -1
	s_and_b64 vcc, exec, s[8:9]
	v_ashrrev_i32_e32 v41, 31, v40
	s_waitcnt vmcnt(0)
	v_pk_mul_f32 v[52:53], v[22:23], v[34:35]
	v_pk_mul_f32 v[54:55], v[20:21], v[32:33]
	v_pk_mul_f32 v[56:57], v[18:19], v[38:39]
	v_pk_mul_f32 v[58:59], v[16:17], v[36:37]
	v_pk_mul_f32 v[34:35], v[30:31], v[34:35]
	v_pk_mul_f32 v[32:33], v[28:29], v[32:33]
	v_pk_mul_f32 v[38:39], v[26:27], v[38:39]
	v_pk_mul_f32 v[36:37], v[24:25], v[36:37]
	v_pk_fma_f32 v[30:31], v[30:31], v[46:47], v[52:53] neg_lo:[0,0,1] neg_hi:[0,0,1]
	v_pk_fma_f32 v[28:29], v[28:29], v[44:45], v[54:55] neg_lo:[0,0,1] neg_hi:[0,0,1]
	v_pk_fma_f32 v[26:27], v[26:27], v[50:51], v[56:57] neg_lo:[0,0,1] neg_hi:[0,0,1]
	v_pk_fma_f32 v[24:25], v[24:25], v[48:49], v[58:59] neg_lo:[0,0,1] neg_hi:[0,0,1]
	v_pk_fma_f32 v[22:23], v[22:23], v[46:47], v[34:35]
	v_pk_fma_f32 v[20:21], v[20:21], v[44:45], v[32:33]
	v_pk_fma_f32 v[18:19], v[18:19], v[50:51], v[38:39]
	v_pk_fma_f32 v[16:17], v[16:17], v[48:49], v[36:37]
	s_cbranch_vccnz .LBB0_421
	v_add_u32_e32 v32, 0xffff0020, v72
	v_cndmask_b32_e64 v45, 0, v41, s[14:15]
	v_cndmask_b32_e64 v44, v32, v40, s[14:15]
	s_andn2_b64 vcc, exec, s[52:53]
	v_cvt_pk_bf16_f32 v36, v28, v29
	v_cvt_pk_bf16_f32 v37, v30, v31
	v_cvt_pk_bf16_f32 v38, v24, v25
	v_cvt_pk_bf16_f32 v39, v26, v27
	v_cvt_pk_bf16_f32 v32, v20, v21
	v_cvt_pk_bf16_f32 v33, v22, v23
	v_cvt_pk_bf16_f32 v34, v16, v17
	v_cvt_pk_bf16_f32 v35, v18, v19
	s_cbranch_vccnz .LBB0_418
	v_cndmask_b32_e64 v144, v183, v184, s[14:15]
	v_lshl_add_u64 v[46:47], s[16:17], 0, v[144:145]
	v_lshlrev_b64 v[48:49], 8, v[44:45]
	v_lshl_add_u64 v[46:47], v[46:47], 0, v[48:49]
	v_lshlrev_b32_e32 v144, 2, v146
	v_lshl_add_u64 v[46:47], v[46:47], 0, v[144:145]
	global_store_dwordx4 v[46:47], v[28:31], off nt
	global_store_dwordx4 v[46:47], v[24:27], off offset:16 nt
	global_store_dwordx4 v[46:47], v[20:23], off offset:128 nt
	global_store_dwordx4 v[46:47], v[16:19], off offset:144 nt
	v_mad_i64_i32 v[46:47], s[60:61], v42, s89, v[156:157]
	s_mov_b64 s[60:61], 0
	global_store_dwordx4 v[46:47], v[36:39], off offset:256 nt
	global_store_dwordx4 v[46:47], v[32:35], off offset:320 nt
	global_store_dwordx4 v[46:47], v[36:39], off offset:640 nt
	global_store_dwordx4 v[46:47], v[32:35], off offset:704 nt
	global_store_dwordx4 v[46:47], v[36:39], off offset:1024 nt
	global_store_dwordx4 v[46:47], v[32:35], off offset:1088 nt
	global_store_dwordx4 v[46:47], v[36:39], off offset:1408 nt
	global_store_dwordx4 v[46:47], v[32:35], off offset:1472 nt
.LBB0_418:
	s_andn2_b64 vcc, exec, s[60:61]
	s_cbranch_vccnz .LBB0_420
	v_cndmask_b32_e64 v144, v185, v186, s[14:15]
	v_lshl_add_u64 v[46:47], s[16:17], 0, v[144:145]
	v_lshlrev_b64 v[44:45], 11, v[44:45]
	v_ashrrev_i32_e32 v43, 31, v42
	v_lshl_add_u64 v[44:45], v[46:47], 0, v[44:45]
	v_lshlrev_b64 v[42:43], 10, v[42:43]
	v_lshl_add_u64 v[44:45], s[20:21], 2, v[44:45]
	v_lshlrev_b32_e32 v144, 2, v146
	v_lshl_add_u64 v[42:43], s[26:27], 0, v[42:43]
	v_lshl_add_u64 v[44:45], v[44:45], 0, v[144:145]
	v_lshl_add_u64 v[42:43], s[20:21], 1, v[42:43]
	v_lshlrev_b32_e32 v144, 1, v146
	v_lshl_add_u64 v[42:43], v[42:43], 0, v[144:145]
	global_store_dwordx4 v[44:45], v[28:31], off nt
	global_store_dwordx4 v[44:45], v[24:27], off offset:16 nt
	global_store_dwordx4 v[44:45], v[20:23], off offset:128 nt
	global_store_dwordx4 v[44:45], v[16:19], off offset:144 nt
	global_store_dwordx4 v[42:43], v[36:39], off nt
	global_store_dwordx4 v[42:43], v[32:35], off offset:64 nt

; __device__ __forceinline__ u32x4 pack8(f32x4 a, f32x4 b) { u32x4 w; w.x = pk2(a[0], a[1]); w.y = pk2(a[2], a[3]); w.z = pk2(b[0], b[1]); w.w = pk2(b[2], b[3]); return w; }
;     __device__ __forceinline__ void operator()(const f32x4 (&acc)[2][2][4][2], const Unit& u, int wr, int wc, int fr, int fq) const {
;     ...
;                     if (pn < 2) {
;                         const int g = 4 * pn + wc;
;                         bf16_t* d = qd + (size_t)r * 512 + 64 * g + 8 * fq;
;                         *(u32x4*)d = pack8(a0 * QS_D, a1 * QS_D); *(u32x4*)(d + 32) = pack8(b0 * QS_D, b1 * QS_D);
.LBB0_421:
	s_andn2_b64 vcc, exec, s[60:61]
	s_cbranch_vccnz .LBB0_423
	v_lshlrev_b64 v[32:33], 10, v[40:41]
	v_lshl_add_u64 v[32:33], s[24:25], 0, v[32:33]
	v_lshl_add_u64 v[32:33], s[56:57], 1, v[32:33]
	v_lshlrev_b32_e32 v144, 1, v146
	v_pk_mul_f32 v[30:31], v[30:31], s[40:41] op_sel_hi:[1,0]
	v_pk_mul_f32 v[28:29], v[28:29], s[40:41] op_sel_hi:[1,0]
	v_pk_mul_f32 v[34:35], v[26:27], s[40:41] op_sel_hi:[1,0]
	v_pk_mul_f32 v[26:27], v[24:25], s[40:41] op_sel_hi:[1,0]
	v_lshl_add_u64 v[32:33], v[32:33], 0, v[144:145]
	v_cvt_pk_bf16_f32 v24, v28, v29
	v_cvt_pk_bf16_f32 v25, v30, v31
	v_cvt_pk_bf16_f32 v26, v26, v27
	v_cvt_pk_bf16_f32 v27, v34, v35
	global_store_dwordx4 v[32:33], v[24:27], off nt
	v_pk_mul_f32 v[22:23], v[22:23], s[40:41] op_sel_hi:[1,0]
	v_pk_mul_f32 v[20:21], v[20:21], s[40:41] op_sel_hi:[1,0]
	v_pk_mul_f32 v[24:25], v[18:19], s[40:41] op_sel_hi:[1,0]
	v_pk_mul_f32 v[18:19], v[16:17], s[40:41] op_sel_hi:[1,0]
	v_cvt_pk_bf16_f32 v16, v20, v21
	v_cvt_pk_bf16_f32 v17, v22, v23
	v_cvt_pk_bf16_f32 v18, v18, v19
	v_cvt_pk_bf16_f32 v19, v24, v25
	global_store_dwordx4 v[32:33], v[16:19], off offset:64 nt

;     __device__ __forceinline__ void operator()(const f32x4 (&acc)[2][2][4][2], const Unit& u, int wr, int wc, int fr, int fq) const {
;     ...
;                 } else if (wc < 2) {
;                     float* o = ckvraw + (size_t)r * 128 + 64 * wc + 8 * fq;
; #pragma unroll
;                     for (int bj = 0; bj < 2; ++bj) { *(f32x4*)(o + 32 * bj) = acc[ai][bj][m][0]; *(f32x4*)(o + 32 * bj + 4) = acc[ai][bj][m][1]; }
.LBB0_429:
	s_and_b64 vcc, exec, s[10:11]
	s_mov_b64 s[10:11], -1
	s_cbranch_vccnz .LBB0_439
	s_andn2_b64 vcc, exec, s[58:59]
	s_cbranch_vccnz .LBB0_434
	s_andn2_b64 vcc, exec, s[38:39]
	s_cbranch_vccnz .LBB0_433
	v_ashrrev_i32_e32 v25, 31, v24
	v_lshlrev_b64 v[20:21], 9, v[24:25]
	v_lshl_add_u64 v[20:21], v[148:149], 0, v[20:21]
	global_store_dwordx4 v[20:21], v[12:15], off nt
	global_store_dwordx4 v[20:21], v[8:11], off offset:16 nt
	global_store_dwordx4 v[20:21], v[4:7], off offset:128 nt
	global_store_dwordx4 v[20:21], v[0:3], off offset:144 nt

; __device__ __forceinline__ u32x4 pack8(f32x4 a, f32x4 b) { u32x4 w; w.x = pk2(a[0], a[1]); w.y = pk2(a[2], a[3]); w.z = pk2(b[0], b[1]); w.w = pk2(b[2], b[3]); return w; }
;     __device__ __forceinline__ void operator()(const f32x4 (&acc)[2][2][4][2], const Unit& u, int wr, int wc, int fr, int fq) const {
;     ...
;                 } else if (pn == 6) {
;                     const int c = 64 * wc + 8 * fq; float ss = 0.f;
; #pragma unroll
;                     for (int bj = 0; bj < 2; ++bj) {
;                         const f32x4 y0 = acc[ai][bj][m][0], y1 = acc[ai][bj][m][1];
;                         const f32x4 g0 = *(const f32x4*)(gq + c + 32 * bj), g1 = *(const f32x4*)(gq + c + 32 * bj + 4);
;                         *(u32x4*)(cq + (size_t)r * 256 + c + 32 * bj) = pack8(y0 * g0, y1 * g1);
;                         ss += (y0[0] * y0[0] + y0[1] * y0[1]) + (y0[2] * y0[2] + y0[3] * y0[3]) + (y1[0] * y1[0] + y1[1] * y1[1]) + (y1[2] * y1[2] + y1[3] * y1[3]);
;                     }
;                     ss += __shfl_xor(ss, 16); ss += __shfl_xor(ss, 32);
;                     if (fq == 0) atomicAdd(rsqq + r, ss);
.LBB0_434:
	s_andn2_b64 vcc, exec, s[10:11]
	s_cbranch_vccnz .LBB0_438
	global_load_dwordx4 v[20:23], v[154:155], off
	global_load_dwordx4 v[28:31], v[154:155], off offset:16
	v_ashrrev_i32_e32 v25, 31, v24
	v_lshlrev_b64 v[32:33], 9, v[24:25]
	v_lshl_add_u64 v[32:33], v[150:151], 0, v[32:33]
	v_mul_f32_e32 v17, v13, v13
	v_mul_f32_e32 v19, v15, v15
	s_waitcnt lgkmcnt(0)
	v_mul_f32_e32 v35, v5, v5
	v_mul_f32_e32 v36, v7, v7
	v_mul_f32_e32 v27, v9, v9
	v_mul_f32_e32 v37, v1, v1
	v_and_b32_e32 v40, 64, v180
	v_fmac_f32_e32 v17, v12, v12
	v_fmac_f32_e32 v19, v14, v14
	v_fmac_f32_e32 v35, v4, v4
	v_fmac_f32_e32 v36, v6, v6
	v_mul_f32_e32 v34, v11, v11
	v_mul_f32_e32 v38, v3, v3
	v_xor_b32_e32 v39, 16, v180
	v_fmac_f32_e32 v27, v8, v8
	v_fmac_f32_e32 v37, v0, v0
	v_add_u32_e32 v40, 64, v40
	v_add_f32_e32 v17, v17, v19
	v_add_f32_e32 v19, v35, v36
	v_fmac_f32_e32 v34, v10, v10
	v_fmac_f32_e32 v38, v2, v2
	v_cmp_lt_i32_e32 vcc, v39, v40
	v_add_f32_e32 v17, v17, v27
	v_add_f32_e32 v19, v19, v37
	v_cndmask_b32_e32 v35, v180, v39, vcc
	v_add_f32_e32 v17, v34, v17
	v_add_f32_e32 v19, v38, v19
	v_lshlrev_b32_e32 v27, 2, v35
	v_add_f32_e32 v17, v17, v19
	ds_bpermute_b32 v19, v27, v17
	v_xor_b32_e32 v27, 32, v180
	v_cmp_lt_i32_e32 vcc, v27, v40
	s_waitcnt lgkmcnt(0)
	v_add_f32_e32 v17, v17, v19
	v_cndmask_b32_e32 v27, v180, v27, vcc
	v_lshlrev_b32_e32 v27, 2, v27
	ds_bpermute_b32 v19, v27, v17
	s_waitcnt vmcnt(0)
	v_pk_mul_f32 v[22:23], v[14:15], v[22:23]
	v_pk_mul_f32 v[20:21], v[12:13], v[20:21]
	v_pk_mul_f32 v[30:31], v[10:11], v[30:31]
	v_pk_mul_f32 v[28:29], v[8:9], v[28:29]
	v_cvt_pk_bf16_f32 v20, v20, v21
	v_cvt_pk_bf16_f32 v21, v22, v23
	v_cvt_pk_bf16_f32 v22, v28, v29
	v_cvt_pk_bf16_f32 v23, v30, v31
	global_store_dwordx4 v[32:33], v[20:23], off nt
	global_load_dwordx4 v[20:23], v[154:155], off offset:128
	s_nop 0
	global_load_dwordx4 v[28:31], v[154:155], off offset:144
	s_waitcnt vmcnt(1)
	v_pk_mul_f32 v[22:23], v[6:7], v[22:23]
	v_pk_mul_f32 v[20:21], v[4:5], v[20:21]
	s_waitcnt vmcnt(0)
	v_pk_mul_f32 v[30:31], v[2:3], v[30:31]
	v_pk_mul_f32 v[28:29], v[0:1], v[28:29]
	v_cvt_pk_bf16_f32 v20, v20, v21
	v_cvt_pk_bf16_f32 v21, v22, v23
	v_cvt_pk_bf16_f32 v22, v28, v29
	v_cvt_pk_bf16_f32 v23, v30, v31
	global_store_dwordx4 v[32:33], v[20:23], off offset:64 nt
	s_and_saveexec_b64 s[10:11], s[0:1]
	s_cbranch_execz .LBB0_437
	v_lshl_add_u64 v[20:21], v[24:25], 2, s[30:31]
	s_waitcnt lgkmcnt(0)
	v_add_f32_e32 v17, v17, v19
	global_atomic_add_f32 v[20:21], v17, off

;     __device__ __forceinline__ float* out() const { return (float*)(GAS float*)ld(25); }
; __device__ __forceinline__ unsigned pk2(float lo, float hi) { f32x2_t v = {lo, hi}; bf16x2_t b = __builtin_convertvector(v, bf16x2_t); return __builtin_bit_cast(unsigned, b); }
; __device__ __forceinline__ int permk(int k) { return (k & ~12) | ((k & 4) << 1) | ((k & 8) >> 1); }
;     __device__ __forceinline__ void operator()(const f32x4 (&acc)[2][2][4][2], const Unit& u, int wr, int wc, int fr, int fq) const {
;     ...
;                 } else if (pn < 6) {
;                     const int g = 4 * (pn - 4) + wc;
;                     float* o = out_row(out, r, O_DVP, O_DVS, 512) + 64 * g + 8 * fq;
;                     const bool odd = (fr & 1) != 0;
;                     bf16_t* vb = vtd + (size_t)(kr - kl) * 512 + permk(kl & ~1);
; #pragma unroll
;                     for (int bj = 0; bj < 2; ++bj) {
;                         *(f32x4*)(o + 32 * bj) = acc[ai][bj][m][0]; *(f32x4*)(o + 32 * bj + 4) = acc[ai][bj][m][1];
;                         const f32x4 mine = odd ? acc[ai][bj][m][1] : acc[ai][bj][m][0], send = odd ? acc[ai][bj][m][0] : acc[ai][bj][m][1];
; #pragma unroll
;                         for (int e = 0; e < 4; ++e) {
;                             const float recv = __shfl_xor(send[e], 1);
;                             const int col = 64 * g + 32 * bj + 8 * fq + (odd ? 4 : 0) + e;
;                             if (!novt) *(unsigned*)(vb + (size_t)col * len) = odd ? pk2(recv, mine[e]) : pk2(mine[e], recv);
;                         }
;                     }
.LBB0_439:
	s_andn2_b64 vcc, exec, s[10:11]
	s_cbranch_vccnz .LBB0_441
	v_add_u32_e32 v17, 0xffff0030, v72
	s_waitcnt lgkmcnt(0)
	v_ashrrev_i32_e32 v19, 31, v24
	v_cndmask_b32_e64 v21, 0, v19, s[14:15]
	v_cndmask_b32_e64 v20, v17, v24, s[14:15]
	v_cndmask_b32_e64 v144, v181, v182, s[14:15]
	v_lshl_add_u64 v[22:23], s[16:17], 0, v[144:145]
	v_lshlrev_b64 v[20:21], 11, v[20:21]
	v_lshl_add_u64 v[20:21], v[22:23], 0, v[20:21]
	v_lshlrev_b32_e32 v19, 1, v18
	v_lshrrev_b32_e32 v25, 1, v18
	v_lshl_add_u64 v[20:21], s[54:55], 2, v[20:21]
	v_lshlrev_b32_e32 v144, 2, v146
	v_and_b32_e32 v17, -14, v18
	v_and_b32_e32 v19, 8, v19
	v_and_b32_e32 v25, 4, v25
	v_lshl_add_u64 v[20:21], v[20:21], 0, v[144:145]
	v_or3_b32 v144, v19, v17, v25
	v_and_b32_e32 v19, 64, v180
	v_xor_b32_e32 v17, 1, v180
	v_add_u32_e32 v19, 64, v19
	v_cmp_lt_i32_e32 vcc, v17, v19
	v_cndmask_b32_e64 v28, v12, v8, s[4:5]
	v_sub_u32_e32 v22, v26, v18
	v_cndmask_b32_e32 v17, v180, v17, vcc
	v_lshlrev_b32_e32 v17, 2, v17
	ds_bpermute_b32 v28, v17, v28
	v_cndmask_b32_e64 v32, v13, v9, s[4:5]
	v_ashrrev_i32_e32 v23, 31, v22
	ds_bpermute_b32 v32, v17, v32
	v_lshlrev_b64 v[22:23], 10, v[22:23]
	v_cndmask_b32_e64 v29, v8, v12, s[4:5]
	v_lshl_add_u64 v[22:23], s[28:29], 0, v[22:23]
	v_cndmask_b32_e64 v31, v14, v10, s[4:5]
	s_waitcnt lgkmcnt(0)
	v_cndmask_b32_e64 v33, v29, v28, s[4:5]
	v_cndmask_b32_e64 v28, v28, v29, s[4:5]
	v_lshl_add_u64 v[22:23], v[144:145], 1, v[22:23]
	v_cvt_pk_bf16_f32 v33, v28, v33
	v_mad_i64_i32 v[28:29], s[10:11], v16, v187, 0
	ds_bpermute_b32 v31, v17, v31
	v_cndmask_b32_e64 v27, v9, v13, s[4:5]
	v_lshl_add_u64 v[28:29], v[28:29], 1, v[22:23]
	global_store_dwordx4 v[20:21], v[12:15], off nt
	global_store_dwordx4 v[20:21], v[8:11], off offset:16 nt
	global_store_dword v[28:29], v33, off
	v_or_b32_e32 v28, 1, v187
	v_cndmask_b32_e64 v29, v27, v32, s[4:5]
	v_cndmask_b32_e64 v27, v32, v27, s[4:5]
	v_cndmask_b32_e64 v30, v15, v11, s[4:5]
	v_cvt_pk_bf16_f32 v27, v27, v29
	v_mad_i64_i32 v[28:29], s[10:11], v16, v28, 0
	v_cndmask_b32_e64 v25, v10, v14, s[4:5]
	v_lshl_add_u64 v[28:29], v[28:29], 1, v[22:23]
	ds_bpermute_b32 v30, v17, v30
	global_store_dword v[28:29], v27, off
	v_or_b32_e32 v27, 2, v187
	s_waitcnt lgkmcnt(0)
	v_cndmask_b32_e64 v28, v25, v31, s[4:5]
	v_cndmask_b32_e64 v25, v31, v25, s[4:5]
	v_cvt_pk_bf16_f32 v25, v25, v28
	v_mad_i64_i32 v[28:29], s[10:11], v16, v27, 0
	v_lshl_add_u64 v[28:29], v[28:29], 1, v[22:23]
	v_cndmask_b32_e64 v19, v11, v15, s[4:5]
	global_store_dword v[28:29], v25, off
	v_or_b32_e32 v25, 3, v187
	v_cndmask_b32_e64 v27, v19, v30, s[4:5]
	v_cndmask_b32_e64 v19, v30, v19, s[4:5]
	v_mad_i64_i32 v[28:29], s[10:11], v16, v25, 0
	v_cvt_pk_bf16_f32 v19, v19, v27
	v_lshl_add_u64 v[28:29], v[28:29], 1, v[22:23]
	global_store_dword v[28:29], v19, off
	global_store_dwordx4 v[20:21], v[4:7], off offset:128 nt
	global_store_dwordx4 v[20:21], v[0:3], off offset:144 nt
	v_cndmask_b32_e64 v21, v4, v0, s[4:5]
	ds_bpermute_b32 v21, v17, v21
	v_cndmask_b32_e64 v30, v5, v1, s[4:5]
	ds_bpermute_b32 v30, v17, v30
	v_cndmask_b32_e64 v20, v0, v4, s[4:5]
	v_cndmask_b32_e64 v29, v6, v2, s[4:5]
	v_or_b32_e32 v31, 32, v187
	s_waitcnt lgkmcnt(0)
	v_cndmask_b32_e64 v32, v20, v21, s[4:5]
	v_cndmask_b32_e64 v20, v21, v20, s[4:5]
	v_cvt_pk_bf16_f32 v32, v20, v32
	v_mad_i64_i32 v[20:21], s[10:11], v16, v31, 0
	ds_bpermute_b32 v29, v17, v29
	v_cndmask_b32_e64 v27, v1, v5, s[4:5]
	v_lshl_add_u64 v[20:21], v[20:21], 1, v[22:23]
	v_cndmask_b32_e64 v28, v7, v3, s[4:5]
	global_store_dword v[20:21], v32, off
	v_or_b32_e32 v20, 33, v187
	v_cndmask_b32_e64 v21, v27, v30, s[4:5]
	v_cndmask_b32_e64 v27, v30, v27, s[4:5]
	v_cvt_pk_bf16_f32 v27, v27, v21
	v_mad_i64_i32 v[20:21], s[10:11], v16, v20, 0
	ds_bpermute_b32 v17, v17, v28
	v_cndmask_b32_e64 v25, v2, v6, s[4:5]
	v_lshl_add_u64 v[20:21], v[20:21], 1, v[22:23]
	global_store_dword v[20:21], v27, off
	v_or_b32_e32 v20, 34, v187
	s_waitcnt lgkmcnt(0)
	v_cndmask_b32_e64 v21, v25, v29, s[4:5]
	v_cndmask_b32_e64 v25, v29, v25, s[4:5]
	v_cvt_pk_bf16_f32 v25, v25, v21
	v_mad_i64_i32 v[20:21], s[10:11], v16, v20, 0
	v_cndmask_b32_e64 v19, v3, v7, s[4:5]
	v_lshl_add_u64 v[20:21], v[20:21], 1, v[22:23]
	global_store_dword v[20:21], v25, off
	v_or_b32_e32 v20, 35, v187
	v_cndmask_b32_e64 v21, v19, v17, s[4:5]
	v_cndmask_b32_e64 v17, v17, v19, s[4:5]
	v_cvt_pk_bf16_f32 v19, v17, v21
	v_mad_i64_i32 v[16:17], s[10:11], v16, v20, 0
	v_lshl_add_u64 v[16:17], v[16:17], 1, v[22:23]
	global_store_dword v[16:17], v19, off

;     __device__ __forceinline__ float* out() const { return (float*)(GAS float*)ld(25); }
; __device__ __forceinline__ u32x4 pack8(f32x4 a, f32x4 b) { u32x4 w; w.x = pk2(a[0], a[1]); w.y = pk2(a[2], a[3]); w.z = pk2(b[0], b[1]); w.w = pk2(b[2], b[3]); return w; }
;     __device__ __forceinline__ void operator()(const f32x4 (&acc)[2][2][4][2], const Unit& u, int wr, int wc, int fr, int fq) const {
;     ...
;                 if (do_rope) {
;                     const float* cs = rope + pos * 64 + 8 * fq;
;                     const f32x4 c0 = *(const f32x4*)cs, c1 = *(const f32x4*)(cs + 4), s0 = *(const f32x4*)(cs + 32), s1 = *(const f32x4*)(cs + 36);
;                     const f32x4 x10 = acc[ai][0][m][0], x11 = acc[ai][0][m][1], x20 = acc[ai][1][m][0], x21 = acc[ai][1][m][1];
;                     f32x4 a0 = x10 * c0 - x20 * s0, a1 = x11 * c1 - x21 * s1, b0 = x20 * c0 + x10 * s0, b1 = x21 * c1 + x11 * s1;
;                     if (pn < 2) {
;                         const int g = 4 * pn + wc;
;                         bf16_t* d = qd + (size_t)r * 512 + 64 * g + 8 * fq;
;                         *(u32x4*)d = pack8(a0 * QS_D, a1 * QS_D); *(u32x4*)(d + 32) = pack8(b0 * QS_D, b1 * QS_D);
;                     } else if (pn < 4) {
;                         const int g = 4 * (pn - 2) + wc;
;                         float* o = out_row(out, r, O_DKP, O_DKS, 512) + 64 * g + 8 * fq;
;                         *(f32x4*)o = a0; *(f32x4*)(o + 4) = a1; *(f32x4*)(o + 32) = b0; *(f32x4*)(o + 36) = b1;
;                         bf16_t* d = kd + (size_t)kr * 512 + 64 * g + 8 * fq;
;                         *(u32x4*)d = pack8(a0, a1); *(u32x4*)(d + 32) = pack8(b0, b1);
;                     } else {
;                         float* o = out_row(out, r, O_KRP, O_KRS, 64) + 8 * fq;
;                         *(f32x4*)o = a0; *(f32x4*)(o + 4) = a1; *(f32x4*)(o + 32) = b0; *(f32x4*)(o + 36) = b1;
;                         const u32x4 wa = pack8(a0, a1), wb = pack8(b0, b1);
; #pragma unroll
;                         for (int hh = 0; hh < 4; ++hh) { bf16_t* d = km + (size_t)kr * 768 + hh * 192 + 128 + 8 * fq; *(u32x4*)d = wa; *(u32x4*)(d + 32) = wb; }
;                     }
.LBB0_442:
	v_lshlrev_b32_e32 v144, 6, v18
	v_lshl_add_u64 v[32:33], v[144:145], 2, v[152:153]
	s_waitcnt lgkmcnt(0)
	global_load_dwordx4 v[16:19], v[32:33], off offset:128
	global_load_dwordx4 v[20:23], v[32:33], off offset:144
	global_load_dwordx4 v[28:31], v[32:33], off
	s_nop 0
	global_load_dwordx4 v[32:35], v[32:33], off offset:16
	s_mov_b64 s[10:11], -1
	s_and_b64 vcc, exec, s[8:9]
	v_ashrrev_i32_e32 v25, 31, v24
	s_waitcnt vmcnt(0)
	v_pk_mul_f32 v[36:37], v[6:7], v[18:19]
	v_pk_mul_f32 v[38:39], v[4:5], v[16:17]
	v_pk_mul_f32 v[40:41], v[2:3], v[22:23]
	v_pk_mul_f32 v[42:43], v[0:1], v[20:21]
	v_pk_mul_f32 v[18:19], v[14:15], v[18:19]
	v_pk_mul_f32 v[16:17], v[12:13], v[16:17]
	v_pk_mul_f32 v[22:23], v[10:11], v[22:23]
	v_pk_mul_f32 v[20:21], v[8:9], v[20:21]
	v_pk_fma_f32 v[14:15], v[14:15], v[30:31], v[36:37] neg_lo:[0,0,1] neg_hi:[0,0,1]
	v_pk_fma_f32 v[12:13], v[12:13], v[28:29], v[38:39] neg_lo:[0,0,1] neg_hi:[0,0,1]
	v_pk_fma_f32 v[10:11], v[10:11], v[34:35], v[40:41] neg_lo:[0,0,1] neg_hi:[0,0,1]
	v_pk_fma_f32 v[8:9], v[8:9], v[32:33], v[42:43] neg_lo:[0,0,1] neg_hi:[0,0,1]
	v_pk_fma_f32 v[6:7], v[6:7], v[30:31], v[18:19]
	v_pk_fma_f32 v[4:5], v[4:5], v[28:29], v[16:17]
	v_pk_fma_f32 v[2:3], v[2:3], v[34:35], v[22:23]
	v_pk_fma_f32 v[0:1], v[0:1], v[32:33], v[20:21]
	s_cbranch_vccnz .LBB0_448
	v_add_u32_e32 v16, 0xffff0030, v72
	v_cndmask_b32_e64 v29, 0, v25, s[14:15]
	v_cndmask_b32_e64 v28, v16, v24, s[14:15]
	s_mov_b64 s[8:9], -1
	s_andn2_b64 vcc, exec, s[52:53]
	v_lshlrev_b32_e32 v30, 2, v146
	v_cvt_pk_bf16_f32 v20, v12, v13
	v_cvt_pk_bf16_f32 v21, v14, v15
	v_cvt_pk_bf16_f32 v22, v8, v9
	v_cvt_pk_bf16_f32 v23, v10, v11
	v_cvt_pk_bf16_f32 v16, v4, v5
	v_cvt_pk_bf16_f32 v17, v6, v7
	v_cvt_pk_bf16_f32 v18, v0, v1
	v_cvt_pk_bf16_f32 v19, v2, v3
	s_cbranch_vccnz .LBB0_445
	v_cndmask_b32_e64 v144, v183, v184, s[14:15]
	v_lshl_add_u64 v[32:33], s[16:17], 0, v[144:145]
	v_lshlrev_b64 v[34:35], 8, v[28:29]
	v_lshl_add_u64 v[32:33], v[32:33], 0, v[34:35]
	v_mov_b32_e32 v31, v145
	v_lshl_add_u64 v[32:33], v[32:33], 0, v[30:31]
	global_store_dwordx4 v[32:33], v[12:15], off nt
	global_store_dwordx4 v[32:33], v[8:11], off offset:16 nt
	global_store_dwordx4 v[32:33], v[4:7], off offset:128 nt
	global_store_dwordx4 v[32:33], v[0:3], off offset:144 nt
	v_mad_i64_i32 v[32:33], s[8:9], v26, s89, v[156:157]
	s_mov_b64 s[8:9], 0
	global_store_dwordx4 v[32:33], v[20:23], off offset:256 nt
	global_store_dwordx4 v[32:33], v[16:19], off offset:320 nt
	global_store_dwordx4 v[32:33], v[20:23], off offset:640 nt
	global_store_dwordx4 v[32:33], v[16:19], off offset:704 nt
	global_store_dwordx4 v[32:33], v[20:23], off offset:1024 nt
	global_store_dwordx4 v[32:33], v[16:19], off offset:1088 nt
	global_store_dwordx4 v[32:33], v[20:23], off offset:1408 nt
	global_store_dwordx4 v[32:33], v[16:19], off offset:1472 nt
.LBB0_445:
	s_andn2_b64 vcc, exec, s[8:9]
	s_cbranch_vccnz .LBB0_447
	v_cndmask_b32_e64 v144, v185, v186, s[14:15]
	v_ashrrev_i32_e32 v27, 31, v26
	v_lshl_add_u64 v[32:33], s[16:17], 0, v[144:145]
	v_lshlrev_b64 v[28:29], 11, v[28:29]
	v_lshlrev_b64 v[26:27], 10, v[26:27]
	v_lshl_add_u64 v[28:29], v[32:33], 0, v[28:29]
	v_lshl_add_u64 v[26:27], s[26:27], 0, v[26:27]
	v_lshl_add_u64 v[28:29], s[20:21], 2, v[28:29]
	v_mov_b32_e32 v31, v145
	v_lshl_add_u64 v[26:27], s[20:21], 1, v[26:27]
	v_lshlrev_b32_e32 v144, 1, v146
	v_lshl_add_u64 v[28:29], v[28:29], 0, v[30:31]
	v_lshl_add_u64 v[26:27], v[26:27], 0, v[144:145]
	global_store_dwordx4 v[28:29], v[12:15], off nt
	global_store_dwordx4 v[28:29], v[8:11], off offset:16 nt
	global_store_dwordx4 v[28:29], v[4:7], off offset:128 nt
	global_store_dwordx4 v[28:29], v[0:3], off offset:144 nt
	global_store_dwordx4 v[26:27], v[20:23], off nt
	global_store_dwordx4 v[26:27], v[16:19], off offset:64 nt

; __device__ __forceinline__ u32x4 pack8(f32x4 a, f32x4 b) { u32x4 w; w.x = pk2(a[0], a[1]); w.y = pk2(a[2], a[3]); w.z = pk2(b[0], b[1]); w.w = pk2(b[2], b[3]); return w; }
;     __device__ __forceinline__ void operator()(const f32x4 (&acc)[2][2][4][2], const Unit& u, int wr, int wc, int fr, int fq) const {
;     ...
;                     if (pn < 2) {
;                         const int g = 4 * pn + wc;
;                         bf16_t* d = qd + (size_t)r * 512 + 64 * g + 8 * fq;
;                         *(u32x4*)d = pack8(a0 * QS_D, a1 * QS_D); *(u32x4*)(d + 32) = pack8(b0 * QS_D, b1 * QS_D);
.LBB0_448:
	s_andn2_b64 vcc, exec, s[10:11]
	s_cbranch_vccnz .LBB0_450
	v_lshlrev_b64 v[16:17], 10, v[24:25]
	v_lshl_add_u64 v[16:17], s[24:25], 0, v[16:17]
	v_lshl_add_u64 v[16:17], s[56:57], 1, v[16:17]
	v_lshlrev_b32_e32 v144, 1, v146
	v_pk_mul_f32 v[14:15], v[14:15], s[40:41] op_sel_hi:[1,0]
	v_pk_mul_f32 v[12:13], v[12:13], s[40:41] op_sel_hi:[1,0]
	v_pk_mul_f32 v[18:19], v[10:11], s[40:41] op_sel_hi:[1,0]
	v_pk_mul_f32 v[10:11], v[8:9], s[40:41] op_sel_hi:[1,0]
	v_lshl_add_u64 v[16:17], v[16:17], 0, v[144:145]
	v_cvt_pk_bf16_f32 v8, v12, v13
	v_cvt_pk_bf16_f32 v9, v14, v15
	v_cvt_pk_bf16_f32 v10, v10, v11
	v_cvt_pk_bf16_f32 v11, v18, v19
	global_store_dwordx4 v[16:17], v[8:11], off nt
	v_pk_mul_f32 v[6:7], v[6:7], s[40:41] op_sel_hi:[1,0]
	v_pk_mul_f32 v[4:5], v[4:5], s[40:41] op_sel_hi:[1,0]
	v_pk_mul_f32 v[8:9], v[2:3], s[40:41] op_sel_hi:[1,0]
	v_pk_mul_f32 v[2:3], v[0:1], s[40:41] op_sel_hi:[1,0]
	v_cvt_pk_bf16_f32 v0, v4, v5
	v_cvt_pk_bf16_f32 v1, v6, v7
	v_cvt_pk_bf16_f32 v2, v2, v3
	v_cvt_pk_bf16_f32 v3, v8, v9
	global_store_dwordx4 v[16:17], v[0:3], off offset:64 nt
